# v034fill
# baseline (speedup 1.0000x reference)
;   #define STAGE(P,BASE,LD,br,kt) do{ const HALF* _u=(BASE)+(long)(br)*(((&(LD))==&lda)?lda_u:(LD))+(long)(kt)*G_BK; \
;     for(int _i=0;_i<2;++_i){ \
;       __builtin_amdgcn_global_load_lds((const unsigned*)(_u+(long)_i*(((&(LD))==&lda)?stepa:stepb)+((&(LD))==&lda?oa0:ob0)), \
;         (unsigned*)((char*)(P)+t5*16+_i*8192),16,0,0);}}while(0)
;   #define WAIT_V(n) asm volatile("s_waitcnt vmcnt(" #n ")":::"memory")
;   #define BAR __builtin_amdgcn_s_barrier()
;     ...
;   if(wr==1)BAR;
;   WAIT_V(4); BAR;
;   STAGE(SB(1,0),Bt,ldb,0,1); STAGE(SA(1,0),A,lda,0,1); STAGE(SB(1,1),Bt,ldb,G_HALF,1);
;   WAIT_V(6); BAR;
.LBB0_126:
	s_or_b64 exec, exec, s[6:7]
	v_lshlrev_b32_e32 v11, 6, v131
	v_lshlrev_b32_e32 v13, 2, v131
	v_and_b32_e32 v10, 48, v131
	v_and_b32_e32 v12, 0x3c0, v11
	v_and_b32_e32 v13, 32, v13
	v_add_u32_e32 v142, s29, v5
	v_bitop3_b32 v12, v12, v13, v10 bitop3:0x36
	v_and_b32_e32 v10, 0x3000, v11
	v_readfirstlane_b32 s9, v142
	v_add_u32_e32 v143, 0x2000, v142
	v_add_u32_e32 v13, s95, v10
	v_lshl_add_u64 v[10:11], v[0:1], 0, s[84:85]
	s_mov_b32 m0, s9
	s_mov_b64 s[10:11], 0x20080
	v_readfirstlane_b32 s9, v143
	v_add_u32_e32 v144, 0x8000, v136
	global_load_lds_dwordx4 v[10:11], off
	v_lshl_add_u64 v[0:1], v[0:1], 0, s[10:11]
	s_mov_b32 m0, s9
	v_readfirstlane_b32 s9, v144
	v_add_u32_e32 v145, 0xa000, v136
	global_load_lds_dwordx4 v[0:1], off
	v_lshl_add_u64 v[0:1], v[2:3], 0, s[84:85]
	s_mov_b32 m0, s9
	v_readfirstlane_b32 s9, v145
	global_load_lds_dwordx4 v[0:1], off
	v_lshl_add_u64 v[0:1], v[2:3], 0, s[10:11]
	s_mov_b32 m0, s9
	v_add_u32_e32 v146, s62, v5
	global_load_lds_dwordx4 v[0:1], off
	v_lshl_add_u64 v[0:1], v[152:153], 1, s[4:5]
	v_readfirstlane_b32 s4, v146
	v_add_u32_e32 v147, 0x2000, v146
	v_lshl_add_u64 v[2:3], v[0:1], 0, s[88:89]
	s_mov_b32 m0, s4
	v_readfirstlane_b32 s4, v147
	global_load_lds_dwordx4 v[2:3], off
	v_lshl_add_u64 v[0:1], v[0:1], 0, s[90:91]
	s_mov_b32 m0, s4
	s_mov_b32 s76, s58
	global_load_lds_dwordx4 v[0:1], off
	s_lshl_b32 s6, s21, 8
	s_ashr_i32 s77, s76, 31
	v_lshlrev_b32_e32 v0, 13, v4
	s_lshl_b64 s[70:71], s[58:59], 10
	s_bfe_u32 s44, s21, 0x2000b
	s_and_b32 s8, s6, 0x180000
	s_lshl_b64 s[6:7], s[76:77], 11
	v_and_b32_e32 v0, 0xffffc000, v0
	v_lshl_add_u32 v0, v6, 10, v0
	s_add_u32 s8, s0, s8
	v_or_b32_e32 v0, v0, v7
	s_addc_u32 s9, s1, 0
	s_waitcnt vmcnt(10)
	s_barrier
	s_waitcnt vmcnt(6)
	v_add_u32_sdwa v0, v0, sext(v8) dst_sel:DWORD dst_unused:UNUSED_PAD src0_sel:DWORD src1_sel:WORD_0
	v_mov_b32_e32 v1, v153
	s_add_u32 s10, s0, s6
	v_lshl_add_u32 v9, v9, 13, 0
	v_lshlrev_b64 v[128:129], 1, v[0:1]
	s_addc_u32 s11, s1, s7
	v_mov_b32_e32 v0, 0
	s_mov_b32 s12, -2
	v_add_u32_e32 v133, v13, v12
	v_add_u32_e32 v132, v9, v12
	s_mov_b64 s[4:5], s[10:11]
	s_mov_b64 s[6:7], s[8:9]
	v_mov_b32_e32 v1, v0
	v_mov_b32_e32 v2, v0
	v_mov_b32_e32 v3, v0
	v_mov_b32_e32 v4, v0
	v_mov_b32_e32 v5, v0
	v_mov_b32_e32 v6, v0
	v_mov_b32_e32 v7, v0
	v_mov_b32_e32 v8, v0
	v_mov_b32_e32 v9, v0
	v_mov_b32_e32 v10, v0
	v_mov_b32_e32 v11, v0
	v_mov_b32_e32 v12, v0
	v_mov_b32_e32 v13, v0
	v_mov_b32_e32 v14, v0
	v_mov_b32_e32 v15, v0
	v_mov_b32_e32 v16, v0
	v_mov_b32_e32 v17, v0
	v_mov_b32_e32 v18, v0
	v_mov_b32_e32 v19, v0
	v_mov_b32_e32 v20, v0
	v_mov_b32_e32 v21, v0
	v_mov_b32_e32 v22, v0
	v_mov_b32_e32 v23, v0
	v_mov_b32_e32 v24, v0
	v_mov_b32_e32 v25, v0
	v_mov_b32_e32 v26, v0
	v_mov_b32_e32 v27, v0
	v_mov_b32_e32 v28, v0
	v_mov_b32_e32 v29, v0
	v_mov_b32_e32 v30, v0
	v_mov_b32_e32 v31, v0
	v_mov_b32_e32 v32, v0
	v_mov_b32_e32 v33, v0
	v_mov_b32_e32 v34, v0
	v_mov_b32_e32 v35, v0
	v_mov_b32_e32 v36, v0
	v_mov_b32_e32 v37, v0
	v_mov_b32_e32 v38, v0
	v_mov_b32_e32 v39, v0
	v_mov_b32_e32 v40, v0
	v_mov_b32_e32 v41, v0
	v_mov_b32_e32 v42, v0
	v_mov_b32_e32 v43, v0
	v_mov_b32_e32 v44, v0
	v_mov_b32_e32 v45, v0
	v_mov_b32_e32 v46, v0
	v_mov_b32_e32 v47, v0
	v_mov_b32_e32 v48, v0
	v_mov_b32_e32 v49, v0
	v_mov_b32_e32 v50, v0
	v_mov_b32_e32 v51, v0
	v_mov_b32_e32 v52, v0
	v_mov_b32_e32 v53, v0
	v_mov_b32_e32 v54, v0
	v_mov_b32_e32 v55, v0
	v_mov_b32_e32 v56, v0
	v_mov_b32_e32 v57, v0
	v_mov_b32_e32 v58, v0
	v_mov_b32_e32 v59, v0
	v_mov_b32_e32 v60, v0
	v_mov_b32_e32 v61, v0
	v_mov_b32_e32 v62, v0
	v_mov_b32_e32 v63, v0
	v_mov_b32_e32 v64, v0
	v_mov_b32_e32 v65, v0
	v_mov_b32_e32 v66, v0
	v_mov_b32_e32 v67, v0
	v_mov_b32_e32 v68, v0
	v_mov_b32_e32 v69, v0
	v_mov_b32_e32 v70, v0
	v_mov_b32_e32 v71, v0
	v_mov_b32_e32 v76, v0
	v_mov_b32_e32 v77, v0
	v_mov_b32_e32 v78, v0
	v_mov_b32_e32 v79, v0
	v_mov_b32_e32 v80, v0
	v_mov_b32_e32 v81, v0
	v_mov_b32_e32 v82, v0
	v_mov_b32_e32 v83, v0
	v_mov_b32_e32 v84, v0
	v_mov_b32_e32 v85, v0
	v_mov_b32_e32 v86, v0
	v_mov_b32_e32 v87, v0
	v_mov_b32_e32 v88, v0
	v_mov_b32_e32 v89, v0
	v_mov_b32_e32 v90, v0
	v_mov_b32_e32 v91, v0
	v_mov_b32_e32 v92, v0
	v_mov_b32_e32 v93, v0
	v_mov_b32_e32 v94, v0
	v_mov_b32_e32 v95, v0
	v_mov_b32_e32 v96, v0
	v_mov_b32_e32 v97, v0
	v_mov_b32_e32 v98, v0
	v_mov_b32_e32 v99, v0
	v_mov_b32_e32 v100, v0
	v_mov_b32_e32 v101, v0
	v_mov_b32_e32 v102, v0
	v_mov_b32_e32 v103, v0
	v_mov_b32_e32 v104, v0
	v_mov_b32_e32 v105, v0
	v_mov_b32_e32 v106, v0
	v_mov_b32_e32 v107, v0
	v_mov_b32_e32 v108, v0
	v_mov_b32_e32 v109, v0
	v_mov_b32_e32 v110, v0
	v_mov_b32_e32 v111, v0
	v_mov_b32_e32 v112, v0
	v_mov_b32_e32 v113, v0
	v_mov_b32_e32 v114, v0
	v_mov_b32_e32 v115, v0
	v_mov_b32_e32 v116, v0
	v_mov_b32_e32 v117, v0
	v_mov_b32_e32 v118, v0
	v_mov_b32_e32 v119, v0
	v_mov_b32_e32 v120, v0
	v_mov_b32_e32 v121, v0
	v_mov_b32_e32 v122, v0
	v_mov_b32_e32 v123, v0
	v_mov_b32_e32 v124, v0
	v_mov_b32_e32 v125, v0
	v_mov_b32_e32 v126, v0
	v_mov_b32_e32 v127, v0
	v_mov_b32_e32 v72, v0
	v_mov_b32_e32 v73, v0
	v_mov_b32_e32 v74, v0
	v_mov_b32_e32 v75, v0
	s_barrier

;   #define STAGE(P,BASE,LD,br,kt) do{ const HALF* _u=(BASE)+(long)(br)*(((&(LD))==&lda)?lda_u:(LD))+(long)(kt)*G_BK; \
;     for(int _i=0;_i<2;++_i){ \
;       __builtin_amdgcn_global_load_lds((const unsigned*)(_u+(long)_i*(((&(LD))==&lda)?stepa:stepb)+((&(LD))==&lda?oa0:ob0)), \
;         (unsigned*)((char*)(P)+t5*16+_i*8192),16,0,0);}}while(0)
;   #define WAIT_V(n) asm volatile("s_waitcnt vmcnt(" #n ")":::"memory")
;   #define BAR __builtin_amdgcn_s_barrier()
;     ...
;   if(wr==1)BAR;
;   WAIT_V(4); BAR;
;   STAGE(SB(1,0),Bt,ldb,0,1); STAGE(SA(1,0),A,lda,0,1); STAGE(SB(1,1),Bt,ldb,G_HALF,1);
;   WAIT_V(6); BAR;
.LBB0_138:
	s_or_b64 exec, exec, s[14:15]
	v_lshlrev_b32_e32 v11, 6, v133
	v_lshlrev_b32_e32 v13, 2, v133
	v_and_b32_e32 v10, 48, v133
	v_and_b32_e32 v12, 0x3c0, v11
	v_and_b32_e32 v13, 32, v13
	v_add_u32_e32 v144, s29, v5
	v_bitop3_b32 v12, v12, v13, v10 bitop3:0x36
	v_and_b32_e32 v10, 0x3000, v11
	s_lshl_b64 s[14:15], s[76:77], 12
	v_readfirstlane_b32 s76, v144
	v_add_u32_e32 v145, 0x2000, v144
	v_add_u32_e32 v13, s95, v10
	v_lshl_add_u64 v[10:11], v[0:1], 0, s[84:85]
	s_mov_b32 m0, s76
	v_readfirstlane_b32 s76, v145
	v_add_u32_e32 v146, 0x8000, v138
	global_load_lds_dwordx4 v[10:11], off
	v_lshl_add_u64 v[0:1], v[0:1], 0, s[88:89]
	s_mov_b32 m0, s76
	v_readfirstlane_b32 s76, v146
	v_add_u32_e32 v147, 0xa000, v138
	global_load_lds_dwordx4 v[0:1], off
	v_lshl_add_u64 v[0:1], v[2:3], 0, s[84:85]
	s_mov_b32 m0, s76
	v_readfirstlane_b32 s76, v147
	global_load_lds_dwordx4 v[0:1], off
	v_lshl_add_u64 v[0:1], v[2:3], 0, s[88:89]
	s_mov_b32 m0, s76
	v_add_u32_e32 v148, s62, v5
	global_load_lds_dwordx4 v[0:1], off
	v_lshl_add_u64 v[0:1], v[152:153], 1, s[12:13]
	s_mov_b64 s[12:13], 0x80080
	v_lshl_add_u64 v[2:3], v[0:1], 0, s[12:13]
	v_readfirstlane_b32 s12, v148
	s_mov_b32 m0, s12
	s_mov_b64 s[12:13], 0xc0080
	v_add_u32_e32 v149, 0x2000, v148
	v_lshl_add_u64 v[0:1], v[0:1], 0, s[12:13]
	v_readfirstlane_b32 s12, v149
	global_load_lds_dwordx4 v[2:3], off
	s_mov_b32 m0, s12
	s_lshl_b32 s44, s44, 20
	global_load_lds_dwordx4 v[0:1], off
	v_lshlrev_b32_e32 v0, 14, v4
	v_and_b32_e32 v0, 0xffff8000, v0
	v_lshl_add_u32 v0, v6, 11, v0
	v_or_b32_e32 v0, v0, v7
	s_add_u32 s76, s0, s44
	s_waitcnt vmcnt(10)
	s_barrier
	s_waitcnt vmcnt(6)
	v_add_u32_sdwa v0, v0, sext(v8) dst_sel:DWORD dst_unused:UNUSED_PAD src0_sel:DWORD src1_sel:WORD_0
	v_mov_b32_e32 v1, v153
	s_addc_u32 s77, s1, 0
	v_lshl_add_u32 v9, v9, 13, 0
	v_lshlrev_b64 v[128:129], 1, v[0:1]
	s_add_u32 vcc_lo, s0, s14
	v_mov_b32_e32 v0, 0
	s_addc_u32 vcc_hi, s1, s15
	s_mov_b32 s12, -2
	v_add_u32_e32 v135, v13, v12
	v_add_u32_e32 v134, v9, v12
	v_mov_b32_e32 v1, v0
	v_mov_b32_e32 v2, v0
	v_mov_b32_e32 v3, v0
	v_mov_b32_e32 v4, v0
	v_mov_b32_e32 v5, v0
	v_mov_b32_e32 v6, v0
	v_mov_b32_e32 v7, v0
	v_mov_b32_e32 v8, v0
	v_mov_b32_e32 v9, v0
	v_mov_b32_e32 v10, v0
	v_mov_b32_e32 v11, v0
	v_mov_b32_e32 v12, v0
	v_mov_b32_e32 v13, v0
	v_mov_b32_e32 v14, v0
	v_mov_b32_e32 v15, v0
	v_mov_b32_e32 v16, v0
	v_mov_b32_e32 v17, v0
	v_mov_b32_e32 v18, v0
	v_mov_b32_e32 v19, v0
	v_mov_b32_e32 v20, v0
	v_mov_b32_e32 v21, v0
	v_mov_b32_e32 v22, v0
	v_mov_b32_e32 v23, v0
	v_mov_b32_e32 v24, v0
	v_mov_b32_e32 v25, v0
	v_mov_b32_e32 v26, v0
	v_mov_b32_e32 v27, v0
	v_mov_b32_e32 v28, v0
	v_mov_b32_e32 v29, v0
	v_mov_b32_e32 v30, v0
	v_mov_b32_e32 v31, v0
	v_mov_b32_e32 v32, v0
	v_mov_b32_e32 v33, v0
	v_mov_b32_e32 v34, v0
	v_mov_b32_e32 v35, v0
	v_mov_b32_e32 v36, v0
	v_mov_b32_e32 v37, v0
	v_mov_b32_e32 v38, v0
	v_mov_b32_e32 v39, v0
	v_mov_b32_e32 v40, v0
	v_mov_b32_e32 v41, v0
	v_mov_b32_e32 v42, v0
	v_mov_b32_e32 v43, v0
	v_mov_b32_e32 v44, v0
	v_mov_b32_e32 v45, v0
	v_mov_b32_e32 v46, v0
	v_mov_b32_e32 v47, v0
	v_mov_b32_e32 v48, v0
	v_mov_b32_e32 v49, v0
	v_mov_b32_e32 v50, v0
	v_mov_b32_e32 v51, v0
	v_mov_b32_e32 v52, v0
	v_mov_b32_e32 v53, v0
	v_mov_b32_e32 v54, v0
	v_mov_b32_e32 v55, v0
	v_mov_b32_e32 v56, v0
	v_mov_b32_e32 v57, v0
	v_mov_b32_e32 v58, v0
	v_mov_b32_e32 v59, v0
	v_mov_b32_e32 v60, v0
	v_mov_b32_e32 v61, v0
	v_mov_b32_e32 v62, v0
	v_mov_b32_e32 v63, v0
	v_mov_b32_e32 v64, v0
	v_mov_b32_e32 v65, v0
	v_mov_b32_e32 v66, v0
	v_mov_b32_e32 v67, v0
	v_mov_b32_e32 v68, v0
	v_mov_b32_e32 v69, v0
	v_mov_b32_e32 v70, v0
	v_mov_b32_e32 v71, v0
	v_mov_b32_e32 v76, v0
	v_mov_b32_e32 v77, v0
	v_mov_b32_e32 v78, v0
	v_mov_b32_e32 v79, v0
	v_mov_b32_e32 v80, v0
	v_mov_b32_e32 v81, v0
	v_mov_b32_e32 v82, v0
	v_mov_b32_e32 v83, v0
	v_mov_b32_e32 v84, v0
	v_mov_b32_e32 v85, v0
	v_mov_b32_e32 v86, v0
	v_mov_b32_e32 v87, v0
	v_mov_b32_e32 v88, v0
	v_mov_b32_e32 v89, v0
	v_mov_b32_e32 v90, v0
	v_mov_b32_e32 v91, v0
	v_mov_b32_e32 v92, v0
	v_mov_b32_e32 v93, v0
	v_mov_b32_e32 v94, v0
	v_mov_b32_e32 v95, v0
	v_mov_b32_e32 v96, v0
	v_mov_b32_e32 v97, v0
	v_mov_b32_e32 v98, v0
	v_mov_b32_e32 v99, v0
	v_mov_b32_e32 v100, v0
	v_mov_b32_e32 v101, v0
	v_mov_b32_e32 v102, v0
	v_mov_b32_e32 v103, v0
	v_mov_b32_e32 v104, v0
	v_mov_b32_e32 v105, v0
	v_mov_b32_e32 v106, v0
	v_mov_b32_e32 v107, v0
	v_mov_b32_e32 v108, v0
	v_mov_b32_e32 v109, v0
	v_mov_b32_e32 v110, v0
	v_mov_b32_e32 v111, v0
	v_mov_b32_e32 v112, v0
	v_mov_b32_e32 v113, v0
	v_mov_b32_e32 v114, v0
	v_mov_b32_e32 v115, v0
	v_mov_b32_e32 v116, v0
	v_mov_b32_e32 v117, v0
	v_mov_b32_e32 v118, v0
	v_mov_b32_e32 v119, v0
	v_mov_b32_e32 v120, v0
	v_mov_b32_e32 v121, v0
	v_mov_b32_e32 v122, v0
	v_mov_b32_e32 v123, v0
	v_mov_b32_e32 v124, v0
	v_mov_b32_e32 v125, v0
	v_mov_b32_e32 v126, v0
	v_mov_b32_e32 v127, v0
	v_mov_b32_e32 v72, v0
	v_mov_b32_e32 v73, v0
	v_mov_b32_e32 v74, v0
	v_mov_b32_e32 v75, v0
	s_barrier

;   #define STAGE(P,BASE,LD,br,kt) do{ const HALF* _u=(BASE)+(long)(br)*(((&(LD))==&lda)?lda_u:(LD))+(long)(kt)*G_BK; \
;     for(int _i=0;_i<2;++_i){ \
;       __builtin_amdgcn_global_load_lds((const unsigned*)(_u+(long)_i*(((&(LD))==&lda)?stepa:stepb)+((&(LD))==&lda?oa0:ob0)), \
;         (unsigned*)((char*)(P)+t5*16+_i*8192),16,0,0);}}while(0)
;   #define WAIT_V(n) asm volatile("s_waitcnt vmcnt(" #n ")":::"memory")
;   #define BAR __builtin_amdgcn_s_barrier()
;     ...
;   if(wr==1)BAR;
;   WAIT_V(4); BAR;
;   STAGE(SB(1,0),Bt,ldb,0,1); STAGE(SA(1,0),A,lda,0,1); STAGE(SB(1,1),Bt,ldb,G_HALF,1);
;   WAIT_V(6); BAR;
.LBB0_150:
	s_or_b64 exec, exec, s[12:13]
	v_lshlrev_b32_e32 v11, 6, v133
	v_lshlrev_b32_e32 v13, 2, v133
	v_and_b32_e32 v10, 48, v133
	v_and_b32_e32 v12, 0x3c0, v11
	v_and_b32_e32 v13, 32, v13
	v_add_u32_e32 v144, s29, v5
	v_bitop3_b32 v12, v12, v13, v10 bitop3:0x36
	v_and_b32_e32 v10, 0x3000, v11
	v_readfirstlane_b32 s12, v144
	v_add_u32_e32 v145, 0x2000, v144
	v_add_u32_e32 v13, s95, v10
	v_lshl_add_u64 v[10:11], v[0:1], 0, s[84:85]
	s_mov_b32 m0, s12
	s_mov_b64 s[14:15], 0x20080
	v_readfirstlane_b32 s12, v145
	v_add_u32_e32 v146, 0x8000, v138
	global_load_lds_dwordx4 v[10:11], off
	v_lshl_add_u64 v[0:1], v[0:1], 0, s[14:15]
	s_mov_b32 m0, s12
	v_readfirstlane_b32 s12, v146
	v_add_u32_e32 v147, 0xa000, v138
	global_load_lds_dwordx4 v[0:1], off
	v_lshl_add_u64 v[0:1], v[2:3], 0, s[84:85]
	s_mov_b32 m0, s12
	v_readfirstlane_b32 s12, v147
	global_load_lds_dwordx4 v[0:1], off
	v_lshl_add_u64 v[0:1], v[2:3], 0, s[14:15]
	s_mov_b32 m0, s12
	v_add_u32_e32 v148, s62, v5
	global_load_lds_dwordx4 v[0:1], off
	v_lshl_add_u64 v[0:1], v[152:153], 1, s[0:1]
	v_readfirstlane_b32 s0, v148
	v_add_u32_e32 v149, 0x2000, v148
	v_lshl_add_u64 v[2:3], v[0:1], 0, s[88:89]
	s_mov_b32 m0, s0
	v_readfirstlane_b32 s0, v149
	global_load_lds_dwordx4 v[2:3], off
	v_lshl_add_u64 v[0:1], v[0:1], 0, s[90:91]
	s_mov_b32 m0, s0
	v_lshl_add_u32 v9, v9, 13, 0
	global_load_lds_dwordx4 v[0:1], off
	v_lshlrev_b32_e32 v0, 13, v4
	v_and_b32_e32 v0, 0xffffc000, v0
	v_lshl_add_u32 v0, v6, 10, v0
	v_or_b32_e32 v0, v0, v7
	s_waitcnt vmcnt(10)
	s_barrier
	s_waitcnt vmcnt(6)
	v_add_u32_sdwa v0, v0, sext(v8) dst_sel:DWORD dst_unused:UNUSED_PAD src0_sel:DWORD src1_sel:WORD_0
	v_mov_b32_e32 v1, v153
	v_lshlrev_b64 v[128:129], 1, v[0:1]
	v_mov_b32_e32 v0, 0
	s_mov_b32 s0, -2
	v_add_u32_e32 v135, v13, v12
	v_add_u32_e32 v134, v9, v12
	v_mov_b32_e32 v1, v0
	v_mov_b32_e32 v2, v0
	v_mov_b32_e32 v3, v0
	v_mov_b32_e32 v4, v0
	v_mov_b32_e32 v5, v0
	v_mov_b32_e32 v6, v0
	v_mov_b32_e32 v7, v0
	v_mov_b32_e32 v8, v0
	v_mov_b32_e32 v9, v0
	v_mov_b32_e32 v10, v0
	v_mov_b32_e32 v11, v0
	v_mov_b32_e32 v12, v0
	v_mov_b32_e32 v13, v0
	v_mov_b32_e32 v14, v0
	v_mov_b32_e32 v15, v0
	v_mov_b32_e32 v16, v0
	v_mov_b32_e32 v17, v0
	v_mov_b32_e32 v18, v0
	v_mov_b32_e32 v19, v0
	v_mov_b32_e32 v20, v0
	v_mov_b32_e32 v21, v0
	v_mov_b32_e32 v22, v0
	v_mov_b32_e32 v23, v0
	v_mov_b32_e32 v24, v0
	v_mov_b32_e32 v25, v0
	v_mov_b32_e32 v26, v0
	v_mov_b32_e32 v27, v0
	v_mov_b32_e32 v28, v0
	v_mov_b32_e32 v29, v0
	v_mov_b32_e32 v30, v0
	v_mov_b32_e32 v31, v0
	v_mov_b32_e32 v32, v0
	v_mov_b32_e32 v33, v0
	v_mov_b32_e32 v34, v0
	v_mov_b32_e32 v35, v0
	v_mov_b32_e32 v36, v0
	v_mov_b32_e32 v37, v0
	v_mov_b32_e32 v38, v0
	v_mov_b32_e32 v39, v0
	v_mov_b32_e32 v40, v0
	v_mov_b32_e32 v41, v0
	v_mov_b32_e32 v42, v0
	v_mov_b32_e32 v43, v0
	v_mov_b32_e32 v44, v0
	v_mov_b32_e32 v45, v0
	v_mov_b32_e32 v46, v0
	v_mov_b32_e32 v47, v0
	v_mov_b32_e32 v48, v0
	v_mov_b32_e32 v49, v0
	v_mov_b32_e32 v50, v0
	v_mov_b32_e32 v51, v0
	v_mov_b32_e32 v52, v0
	v_mov_b32_e32 v53, v0
	v_mov_b32_e32 v54, v0
	v_mov_b32_e32 v55, v0
	v_mov_b32_e32 v56, v0
	v_mov_b32_e32 v57, v0
	v_mov_b32_e32 v58, v0
	v_mov_b32_e32 v59, v0
	v_mov_b32_e32 v60, v0
	v_mov_b32_e32 v61, v0
	v_mov_b32_e32 v62, v0
	v_mov_b32_e32 v63, v0
	v_mov_b32_e32 v64, v0
	v_mov_b32_e32 v65, v0
	v_mov_b32_e32 v66, v0
	v_mov_b32_e32 v67, v0
	v_mov_b32_e32 v68, v0
	v_mov_b32_e32 v69, v0
	v_mov_b32_e32 v70, v0
	v_mov_b32_e32 v71, v0
	v_mov_b32_e32 v76, v0
	v_mov_b32_e32 v77, v0
	v_mov_b32_e32 v78, v0
	v_mov_b32_e32 v79, v0
	v_mov_b32_e32 v80, v0
	v_mov_b32_e32 v81, v0
	v_mov_b32_e32 v82, v0
	v_mov_b32_e32 v83, v0
	v_mov_b32_e32 v84, v0
	v_mov_b32_e32 v85, v0
	v_mov_b32_e32 v86, v0
	v_mov_b32_e32 v87, v0
	v_mov_b32_e32 v88, v0
	v_mov_b32_e32 v89, v0
	v_mov_b32_e32 v90, v0
	v_mov_b32_e32 v91, v0
	v_mov_b32_e32 v92, v0
	v_mov_b32_e32 v93, v0
	v_mov_b32_e32 v94, v0
	v_mov_b32_e32 v95, v0
	v_mov_b32_e32 v96, v0
	v_mov_b32_e32 v97, v0
	v_mov_b32_e32 v98, v0
	v_mov_b32_e32 v99, v0
	v_mov_b32_e32 v100, v0
	v_mov_b32_e32 v101, v0
	v_mov_b32_e32 v102, v0
	v_mov_b32_e32 v103, v0
	v_mov_b32_e32 v104, v0
	v_mov_b32_e32 v105, v0
	v_mov_b32_e32 v106, v0
	v_mov_b32_e32 v107, v0
	v_mov_b32_e32 v108, v0
	v_mov_b32_e32 v109, v0
	v_mov_b32_e32 v110, v0
	v_mov_b32_e32 v111, v0
	v_mov_b32_e32 v112, v0
	v_mov_b32_e32 v113, v0
	v_mov_b32_e32 v114, v0
	v_mov_b32_e32 v115, v0
	v_mov_b32_e32 v116, v0
	v_mov_b32_e32 v117, v0
	v_mov_b32_e32 v118, v0
	v_mov_b32_e32 v119, v0
	v_mov_b32_e32 v120, v0
	v_mov_b32_e32 v121, v0
	v_mov_b32_e32 v122, v0
	v_mov_b32_e32 v123, v0
	v_mov_b32_e32 v124, v0
	v_mov_b32_e32 v125, v0
	v_mov_b32_e32 v126, v0
	v_mov_b32_e32 v127, v0
	v_mov_b32_e32 v72, v0
	v_mov_b32_e32 v73, v0
	v_mov_b32_e32 v74, v0
	v_mov_b32_e32 v75, v0
	s_barrier

;   #define STAGE(P,BASE,LD,br,kt) do{ const HALF* _u=(BASE)+(long)(br)*(((&(LD))==&lda)?lda_u:(LD))+(long)(kt)*G_BK; \
;     for(int _i=0;_i<2;++_i){ \
;       __builtin_amdgcn_global_load_lds((const unsigned*)(_u+(long)_i*(((&(LD))==&lda)?stepa:stepb)+((&(LD))==&lda?oa0:ob0)), \
;         (unsigned*)((char*)(P)+t5*16+_i*8192),16,0,0);}}while(0)
;   #define WAIT_V(n) asm volatile("s_waitcnt vmcnt(" #n ")":::"memory")
;   #define BAR __builtin_amdgcn_s_barrier()
;     ...
;   if(wr==1)BAR;
;   WAIT_V(4); BAR;
;   STAGE(SB(1,0),Bt,ldb,0,1); STAGE(SA(1,0),A,lda,0,1); STAGE(SB(1,1),Bt,ldb,G_HALF,1);
;   WAIT_V(6); BAR;
.LBB0_176:
	s_or_b64 exec, exec, s[12:13]
	v_lshlrev_b32_e32 v9, 6, v135
	v_lshlrev_b32_e32 v11, 2, v135
	v_and_b32_e32 v8, 48, v135
	v_and_b32_e32 v10, 0x3c0, v9
	v_and_b32_e32 v11, 32, v11
	v_add_u32_e32 v146, s29, v3
	v_bitop3_b32 v10, v10, v11, v8 bitop3:0x36
	v_and_b32_e32 v8, 0x3000, v9
	v_readfirstlane_b32 s1, v146
	v_add_u32_e32 v147, 0x2000, v146
	v_add_u32_e32 v11, s95, v8
	v_lshl_add_u64 v[8:9], v[0:1], 0, s[84:85]
	s_mov_b32 m0, s1
	s_mov_b64 s[12:13], 0x20080
	v_readfirstlane_b32 s1, v147
	v_add_u32_e32 v148, 0x8000, v140
	global_load_lds_dwordx4 v[8:9], off
	v_lshl_add_u64 v[8:9], v[0:1], 0, s[12:13]
	s_mov_b32 m0, s1
	v_readfirstlane_b32 s1, v148
	v_add_u32_e32 v149, 0xa000, v140
	global_load_lds_dwordx4 v[8:9], off
	v_lshl_add_u64 v[8:9], v[128:129], 0, s[84:85]
	s_mov_b32 m0, s1
	s_mov_b64 s[12:13], 0x880
	v_readfirstlane_b32 s1, v149
	v_add_u32_e32 v150, s62, v3
	global_load_lds_dwordx4 v[8:9], off
	v_lshl_add_u64 v[8:9], v[128:129], 0, s[12:13]
	s_mov_b32 m0, s1
	v_readfirstlane_b32 s1, v150
	v_add_u32_e32 v151, 0x2000, v150
	global_load_lds_dwordx4 v[8:9], off
	v_lshl_add_u64 v[8:9], v[0:1], 0, s[88:89]
	s_mov_b32 m0, s1
	v_readfirstlane_b32 s1, v151
	global_load_lds_dwordx4 v[8:9], off
	v_lshl_add_u64 v[0:1], v[0:1], 0, s[90:91]
	s_mov_b32 m0, s1
	s_add_i32 s1, s20, s14
	global_load_lds_dwordx4 v[0:1], off
	v_lshlrev_b32_e32 v0, 13, v2
	v_and_b32_e32 v0, 0xffffc000, v0
	v_lshl_add_u32 v0, v4, 10, v0
	v_or_b32_e32 v0, v0, v5
	s_waitcnt vmcnt(10)
	s_barrier
	s_waitcnt vmcnt(6)
	v_add_u32_sdwa v0, v0, sext(v6) dst_sel:DWORD dst_unused:UNUSED_PAD src0_sel:DWORD src1_sel:WORD_0
	v_mov_b32_e32 v1, v153
	s_add_i32 s44, s1, s15
	v_lshl_add_u32 v7, v7, 13, 0
	v_lshl_add_u64 v[130:131], v[0:1], 1, s[6:7]
	s_lshl_b64 s[6:7], s[44:45], 11
	v_mov_b32_e32 v0, 0
	v_lshl_add_u64 v[132:133], v[152:153], 1, s[6:7]
	s_mov_b32 s1, -2
	v_add_u32_e32 v137, v11, v10
	v_add_u32_e32 v136, v7, v10
	s_mov_b64 s[6:7], s[2:3]
	v_mov_b32_e32 v1, v0
	v_mov_b32_e32 v2, v0
	v_mov_b32_e32 v3, v0
	v_mov_b32_e32 v4, v0
	v_mov_b32_e32 v5, v0
	v_mov_b32_e32 v6, v0
	v_mov_b32_e32 v7, v0
	v_mov_b32_e32 v8, v0
	v_mov_b32_e32 v9, v0
	v_mov_b32_e32 v10, v0
	v_mov_b32_e32 v11, v0
	v_mov_b32_e32 v12, v0
	v_mov_b32_e32 v13, v0
	v_mov_b32_e32 v14, v0
	v_mov_b32_e32 v15, v0
	v_mov_b32_e32 v16, v0
	v_mov_b32_e32 v17, v0
	v_mov_b32_e32 v18, v0
	v_mov_b32_e32 v19, v0
	v_mov_b32_e32 v20, v0
	v_mov_b32_e32 v21, v0
	v_mov_b32_e32 v22, v0
	v_mov_b32_e32 v23, v0
	v_mov_b32_e32 v24, v0
	v_mov_b32_e32 v25, v0
	v_mov_b32_e32 v26, v0
	v_mov_b32_e32 v27, v0
	v_mov_b32_e32 v28, v0
	v_mov_b32_e32 v29, v0
	v_mov_b32_e32 v30, v0
	v_mov_b32_e32 v31, v0
	v_mov_b32_e32 v32, v0
	v_mov_b32_e32 v33, v0
	v_mov_b32_e32 v34, v0
	v_mov_b32_e32 v35, v0
	v_mov_b32_e32 v36, v0
	v_mov_b32_e32 v37, v0
	v_mov_b32_e32 v38, v0
	v_mov_b32_e32 v39, v0
	v_mov_b32_e32 v40, v0
	v_mov_b32_e32 v41, v0
	v_mov_b32_e32 v42, v0
	v_mov_b32_e32 v43, v0
	v_mov_b32_e32 v44, v0
	v_mov_b32_e32 v45, v0
	v_mov_b32_e32 v46, v0
	v_mov_b32_e32 v47, v0
	v_mov_b32_e32 v48, v0
	v_mov_b32_e32 v49, v0
	v_mov_b32_e32 v50, v0
	v_mov_b32_e32 v51, v0
	v_mov_b32_e32 v52, v0
	v_mov_b32_e32 v53, v0
	v_mov_b32_e32 v54, v0
	v_mov_b32_e32 v55, v0
	v_mov_b32_e32 v56, v0
	v_mov_b32_e32 v57, v0
	v_mov_b32_e32 v58, v0
	v_mov_b32_e32 v59, v0
	v_mov_b32_e32 v60, v0
	v_mov_b32_e32 v61, v0
	v_mov_b32_e32 v62, v0
	v_mov_b32_e32 v63, v0
	v_mov_b32_e32 v64, v0
	v_mov_b32_e32 v65, v0
	v_mov_b32_e32 v66, v0
	v_mov_b32_e32 v67, v0
	v_mov_b32_e32 v68, v0
	v_mov_b32_e32 v69, v0
	v_mov_b32_e32 v70, v0
	v_mov_b32_e32 v71, v0
	v_mov_b32_e32 v72, v0
	v_mov_b32_e32 v73, v0
	v_mov_b32_e32 v74, v0
	v_mov_b32_e32 v75, v0
	v_mov_b32_e32 v76, v0
	v_mov_b32_e32 v77, v0
	v_mov_b32_e32 v78, v0
	v_mov_b32_e32 v79, v0
	v_mov_b32_e32 v80, v0
	v_mov_b32_e32 v81, v0
	v_mov_b32_e32 v82, v0
	v_mov_b32_e32 v83, v0
	v_mov_b32_e32 v84, v0
	v_mov_b32_e32 v85, v0
	v_mov_b32_e32 v86, v0
	v_mov_b32_e32 v87, v0
	v_mov_b32_e32 v88, v0
	v_mov_b32_e32 v89, v0
	v_mov_b32_e32 v90, v0
	v_mov_b32_e32 v91, v0
	v_mov_b32_e32 v92, v0
	v_mov_b32_e32 v93, v0
	v_mov_b32_e32 v94, v0
	v_mov_b32_e32 v95, v0
	v_mov_b32_e32 v96, v0
	v_mov_b32_e32 v97, v0
	v_mov_b32_e32 v98, v0
	v_mov_b32_e32 v99, v0
	v_mov_b32_e32 v100, v0
	v_mov_b32_e32 v101, v0
	v_mov_b32_e32 v102, v0
	v_mov_b32_e32 v103, v0
	v_mov_b32_e32 v104, v0
	v_mov_b32_e32 v105, v0
	v_mov_b32_e32 v106, v0
	v_mov_b32_e32 v107, v0
	v_mov_b32_e32 v108, v0
	v_mov_b32_e32 v109, v0
	v_mov_b32_e32 v110, v0
	v_mov_b32_e32 v111, v0
	v_mov_b32_e32 v112, v0
	v_mov_b32_e32 v113, v0
	v_mov_b32_e32 v114, v0
	v_mov_b32_e32 v115, v0
	v_mov_b32_e32 v116, v0
	v_mov_b32_e32 v117, v0
	v_mov_b32_e32 v118, v0
	v_mov_b32_e32 v119, v0
	v_mov_b32_e32 v120, v0
	v_mov_b32_e32 v121, v0
	v_mov_b32_e32 v122, v0
	v_mov_b32_e32 v123, v0
	v_mov_b32_e32 v124, v0
	v_mov_b32_e32 v125, v0
	v_mov_b32_e32 v126, v0
	v_mov_b32_e32 v127, v0
	s_mov_b64 s[14:15], 0x40180
	s_mov_b64 s[58:59], 0x60180
	s_barrier

;   #define STAGE(P,BASE,LD,br,kt) do{ const HALF* _u=(BASE)+(long)(br)*(((&(LD))==&lda)?lda_u:(LD))+(long)(kt)*G_BK; \
;     for(int _i=0;_i<2;++_i){ \
;       __builtin_amdgcn_global_load_lds((const unsigned*)(_u+(long)_i*(((&(LD))==&lda)?stepa:stepb)+((&(LD))==&lda?oa0:ob0)), \
;         (unsigned*)((char*)(P)+t5*16+_i*8192),16,0,0);}}while(0)
;   #define WAIT_V(n) asm volatile("s_waitcnt vmcnt(" #n ")":::"memory")
;   #define BAR __builtin_amdgcn_s_barrier()
;     ...
;   {int _b=t5*16;int _r,_c;g_stage_rc(_b,_r,_c);
;     oa0=n2 ? (unsigned)((n2*(_r&63)+(_r>>6))*1024+_c) : (unsigned)(_r*lda+_c); ob0=(unsigned)(_r*ldb+_c);}
;   STAGE(SB(0,0),Bt,ldb,0,0); STAGE(SA(0,0),A,lda,0,0);
;   STAGE(SB(0,1),Bt,ldb,G_HALF,0); STAGE(SA(0,1),A,lda,G_HALF,0);
;   if(wr==1)BAR;
;   WAIT_V(4); BAR;
;   STAGE(SB(1,0),Bt,ldb,0,1); STAGE(SA(1,0),A,lda,0,1); STAGE(SB(1,1),Bt,ldb,G_HALF,1);
;   WAIT_V(6); BAR;
.LBB0_192:
	s_or_b64 exec, exec, s[14:15]
	v_lshlrev_b32_e32 v11, 6, v131
	v_lshlrev_b32_e32 v13, 2, v131
	v_and_b32_e32 v10, 48, v131
	v_and_b32_e32 v12, 0x3c0, v11
	v_and_b32_e32 v13, 32, v13
	v_add_u32_e32 v142, s29, v5
	v_bitop3_b32 v12, v12, v13, v10 bitop3:0x36
	v_and_b32_e32 v10, 0x3000, v11
	v_readfirstlane_b32 s14, v142
	v_add_u32_e32 v143, 0x2000, v142
	v_add_u32_e32 v13, s95, v10
	v_lshl_add_u64 v[10:11], v[0:1], 0, s[84:85]
	s_mov_b32 m0, s14
	s_mov_b64 s[58:59], 0x20080
	v_readfirstlane_b32 s14, v143
	v_add_u32_e32 v144, 0x8000, v136
	global_load_lds_dwordx4 v[10:11], off
	v_lshl_add_u64 v[0:1], v[0:1], 0, s[58:59]
	s_mov_b32 m0, s14
	v_readfirstlane_b32 s14, v144
	v_add_u32_e32 v145, 0xa000, v136
	global_load_lds_dwordx4 v[0:1], off
	v_lshl_add_u64 v[0:1], v[2:3], 0, s[84:85]
	s_mov_b32 m0, s14
	v_readfirstlane_b32 s14, v145
	global_load_lds_dwordx4 v[0:1], off
	v_lshl_add_u64 v[0:1], v[2:3], 0, s[58:59]
	s_mov_b32 m0, s14
	v_add_u32_e32 v146, s62, v5
	global_load_lds_dwordx4 v[0:1], off
	v_lshl_add_u64 v[0:1], v[152:153], 1, s[12:13]
	v_readfirstlane_b32 s12, v146
	v_add_u32_e32 v147, 0x2000, v146
	v_lshl_add_u64 v[2:3], v[0:1], 0, s[88:89]
	s_mov_b32 m0, s12
	v_readfirstlane_b32 s12, v147
	global_load_lds_dwordx4 v[2:3], off
	v_lshl_add_u64 v[0:1], v[0:1], 0, s[90:91]
	s_mov_b32 m0, s12
	v_lshl_add_u32 v9, v9, 13, 0
	global_load_lds_dwordx4 v[0:1], off
	v_lshlrev_b32_e32 v0, 13, v4
	v_and_b32_e32 v0, 0xffffc000, v0
	v_lshl_add_u32 v0, v6, 10, v0
	v_or_b32_e32 v0, v0, v7
	s_waitcnt vmcnt(10)
	s_barrier
	s_waitcnt vmcnt(6)
	v_add_u32_sdwa v0, v0, sext(v8) dst_sel:DWORD dst_unused:UNUSED_PAD src0_sel:DWORD src1_sel:WORD_0
	v_mov_b32_e32 v1, v153
	v_lshl_add_u64 v[128:129], v[0:1], 1, s[0:1]
	v_mov_b32_e32 v0, 0
	s_mov_b32 s12, -2
	v_add_u32_e32 v133, v13, v12
	v_add_u32_e32 v132, v9, v12
	v_mov_b32_e32 v1, v0
	v_mov_b32_e32 v2, v0
	v_mov_b32_e32 v3, v0
	v_mov_b32_e32 v4, v0
	v_mov_b32_e32 v5, v0
	v_mov_b32_e32 v6, v0
	v_mov_b32_e32 v7, v0
	v_mov_b32_e32 v8, v0
	v_mov_b32_e32 v9, v0
	v_mov_b32_e32 v10, v0
	v_mov_b32_e32 v11, v0
	v_mov_b32_e32 v12, v0
	v_mov_b32_e32 v13, v0
	v_mov_b32_e32 v14, v0
	v_mov_b32_e32 v15, v0
	v_mov_b32_e32 v16, v0
	v_mov_b32_e32 v17, v0
	v_mov_b32_e32 v18, v0
	v_mov_b32_e32 v19, v0
	v_mov_b32_e32 v20, v0
	v_mov_b32_e32 v21, v0
	v_mov_b32_e32 v22, v0
	v_mov_b32_e32 v23, v0
	v_mov_b32_e32 v24, v0
	v_mov_b32_e32 v25, v0
	v_mov_b32_e32 v26, v0
	v_mov_b32_e32 v27, v0
	v_mov_b32_e32 v28, v0
	v_mov_b32_e32 v29, v0
	v_mov_b32_e32 v30, v0
	v_mov_b32_e32 v31, v0
	v_mov_b32_e32 v32, v0
	v_mov_b32_e32 v33, v0
	v_mov_b32_e32 v34, v0
	v_mov_b32_e32 v35, v0
	v_mov_b32_e32 v36, v0
	v_mov_b32_e32 v37, v0
	v_mov_b32_e32 v38, v0
	v_mov_b32_e32 v39, v0
	v_mov_b32_e32 v40, v0
	v_mov_b32_e32 v41, v0
	v_mov_b32_e32 v42, v0
	v_mov_b32_e32 v43, v0
	v_mov_b32_e32 v44, v0
	v_mov_b32_e32 v45, v0
	v_mov_b32_e32 v46, v0
	v_mov_b32_e32 v47, v0
	v_mov_b32_e32 v48, v0
	v_mov_b32_e32 v49, v0
	v_mov_b32_e32 v50, v0
	v_mov_b32_e32 v51, v0
	v_mov_b32_e32 v52, v0
	v_mov_b32_e32 v53, v0
	v_mov_b32_e32 v54, v0
	v_mov_b32_e32 v55, v0
	v_mov_b32_e32 v56, v0
	v_mov_b32_e32 v57, v0
	v_mov_b32_e32 v58, v0
	v_mov_b32_e32 v59, v0
	v_mov_b32_e32 v60, v0
	v_mov_b32_e32 v61, v0
	v_mov_b32_e32 v62, v0
	v_mov_b32_e32 v63, v0
	v_mov_b32_e32 v64, v0
	v_mov_b32_e32 v65, v0
	v_mov_b32_e32 v66, v0
	v_mov_b32_e32 v67, v0
	v_mov_b32_e32 v68, v0
	v_mov_b32_e32 v69, v0
	v_mov_b32_e32 v70, v0
	v_mov_b32_e32 v71, v0
	v_mov_b32_e32 v72, v0
	v_mov_b32_e32 v73, v0
	v_mov_b32_e32 v74, v0
	v_mov_b32_e32 v75, v0
	v_mov_b32_e32 v76, v0
	v_mov_b32_e32 v77, v0
	v_mov_b32_e32 v78, v0
	v_mov_b32_e32 v79, v0
	v_mov_b32_e32 v80, v0
	v_mov_b32_e32 v81, v0
	v_mov_b32_e32 v82, v0
	v_mov_b32_e32 v83, v0
	v_mov_b32_e32 v84, v0
	v_mov_b32_e32 v85, v0
	v_mov_b32_e32 v86, v0
	v_mov_b32_e32 v87, v0
	v_mov_b32_e32 v88, v0
	v_mov_b32_e32 v89, v0
	v_mov_b32_e32 v90, v0
	v_mov_b32_e32 v91, v0
	v_mov_b32_e32 v92, v0
	v_mov_b32_e32 v93, v0
	v_mov_b32_e32 v94, v0
	v_mov_b32_e32 v95, v0
	v_mov_b32_e32 v96, v0
	v_mov_b32_e32 v97, v0
	v_mov_b32_e32 v98, v0
	v_mov_b32_e32 v99, v0
	v_mov_b32_e32 v100, v0
	v_mov_b32_e32 v101, v0
	v_mov_b32_e32 v102, v0
	v_mov_b32_e32 v103, v0
	v_mov_b32_e32 v104, v0
	v_mov_b32_e32 v105, v0
	v_mov_b32_e32 v106, v0
	v_mov_b32_e32 v107, v0
	v_mov_b32_e32 v108, v0
	v_mov_b32_e32 v109, v0
	v_mov_b32_e32 v110, v0
	v_mov_b32_e32 v111, v0
	v_mov_b32_e32 v112, v0
	v_mov_b32_e32 v113, v0
	v_mov_b32_e32 v114, v0
	v_mov_b32_e32 v115, v0
	v_mov_b32_e32 v116, v0
	v_mov_b32_e32 v117, v0
	v_mov_b32_e32 v118, v0
	v_mov_b32_e32 v119, v0
	v_mov_b32_e32 v120, v0
	v_mov_b32_e32 v121, v0
	v_mov_b32_e32 v122, v0
	v_mov_b32_e32 v123, v0
	v_mov_b32_e32 v124, v0
	v_mov_b32_e32 v125, v0
	v_mov_b32_e32 v126, v0
	v_mov_b32_e32 v127, v0
	s_mov_b64 s[14:15], 0x40180
	s_mov_b64 s[58:59], 0x60180
	s_mov_b64 s[68:69], 0x3ef0080
	s_mov_b64 s[70:71], 0x3f10080
	s_barrier

;   #define STAGE(P,BASE,LD,br,kt) do{ const HALF* _u=(BASE)+(long)(br)*(((&(LD))==&lda)?lda_u:(LD))+(long)(kt)*G_BK; \
;     for(int _i=0;_i<2;++_i){ \
;       __builtin_amdgcn_global_load_lds((const unsigned*)(_u+(long)_i*(((&(LD))==&lda)?stepa:stepb)+((&(LD))==&lda?oa0:ob0)), \
;         (unsigned*)((char*)(P)+t5*16+_i*8192),16,0,0);}}while(0)
;   #define WAIT_V(n) asm volatile("s_waitcnt vmcnt(" #n ")":::"memory")
;   #define BAR __builtin_amdgcn_s_barrier()
;     ...
;   {int _b=t5*16;int _r,_c;g_stage_rc(_b,_r,_c);
;     oa0=n2 ? (unsigned)((n2*(_r&63)+(_r>>6))*1024+_c) : (unsigned)(_r*lda+_c); ob0=(unsigned)(_r*ldb+_c);}
;   STAGE(SB(0,0),Bt,ldb,0,0); STAGE(SA(0,0),A,lda,0,0);
;   STAGE(SB(0,1),Bt,ldb,G_HALF,0); STAGE(SA(0,1),A,lda,G_HALF,0);
;   if(wr==1)BAR;
;   WAIT_V(4); BAR;
;   STAGE(SB(1,0),Bt,ldb,0,1); STAGE(SA(1,0),A,lda,0,1); STAGE(SB(1,1),Bt,ldb,G_HALF,1);
;   WAIT_V(6); BAR;
.LBB0_244:
	s_or_b64 exec, exec, s[14:15]
	v_lshlrev_b32_e32 v11, 6, v131
	v_lshlrev_b32_e32 v13, 2, v131
	v_and_b32_e32 v10, 48, v131
	v_and_b32_e32 v12, 0x3c0, v11
	v_and_b32_e32 v13, 32, v13
	v_add_u32_e32 v142, s29, v5
	v_bitop3_b32 v12, v12, v13, v10 bitop3:0x36
	v_and_b32_e32 v10, 0x3000, v11
	v_readfirstlane_b32 s14, v142
	v_add_u32_e32 v143, 0x2000, v142
	v_add_u32_e32 v13, s95, v10
	v_lshl_add_u64 v[10:11], v[0:1], 0, s[84:85]
	s_mov_b32 m0, s14
	s_mov_b64 s[58:59], 0x20080
	v_readfirstlane_b32 s14, v143
	v_add_u32_e32 v144, 0x8000, v136
	global_load_lds_dwordx4 v[10:11], off
	v_lshl_add_u64 v[0:1], v[0:1], 0, s[58:59]
	s_mov_b32 m0, s14
	v_readfirstlane_b32 s14, v144
	v_add_u32_e32 v145, 0xa000, v136
	global_load_lds_dwordx4 v[0:1], off
	v_lshl_add_u64 v[0:1], v[2:3], 0, s[84:85]
	s_mov_b32 m0, s14
	v_readfirstlane_b32 s14, v145
	global_load_lds_dwordx4 v[0:1], off
	v_lshl_add_u64 v[0:1], v[2:3], 0, s[58:59]
	s_mov_b32 m0, s14
	v_add_u32_e32 v146, s62, v5
	global_load_lds_dwordx4 v[0:1], off
	v_lshl_add_u64 v[0:1], v[152:153], 1, s[12:13]
	v_readfirstlane_b32 s12, v146
	v_add_u32_e32 v147, 0x2000, v146
	v_lshl_add_u64 v[2:3], v[0:1], 0, s[88:89]
	s_mov_b32 m0, s12
	v_readfirstlane_b32 s12, v147
	global_load_lds_dwordx4 v[2:3], off
	v_lshl_add_u64 v[0:1], v[0:1], 0, s[90:91]
	s_mov_b32 m0, s12
	v_lshl_add_u32 v9, v9, 13, 0
	global_load_lds_dwordx4 v[0:1], off
	v_lshlrev_b32_e32 v0, 13, v4
	v_and_b32_e32 v0, 0xffffc000, v0
	v_lshl_add_u32 v0, v6, 10, v0
	v_or_b32_e32 v0, v0, v7
	s_waitcnt vmcnt(10)
	s_barrier
	s_waitcnt vmcnt(6)
	v_add_u32_sdwa v0, v0, sext(v8) dst_sel:DWORD dst_unused:UNUSED_PAD src0_sel:DWORD src1_sel:WORD_0
	v_mov_b32_e32 v1, v153
	v_lshl_add_u64 v[128:129], v[0:1], 1, s[6:7]
	v_mov_b32_e32 v0, 0
	s_mov_b32 s6, -2
	v_add_u32_e32 v133, v13, v12
	v_add_u32_e32 v132, v9, v12
	v_mov_b32_e32 v1, v0
	v_mov_b32_e32 v2, v0
	v_mov_b32_e32 v3, v0
	v_mov_b32_e32 v4, v0
	v_mov_b32_e32 v5, v0
	v_mov_b32_e32 v6, v0
	v_mov_b32_e32 v7, v0
	v_mov_b32_e32 v8, v0
	v_mov_b32_e32 v9, v0
	v_mov_b32_e32 v10, v0
	v_mov_b32_e32 v11, v0
	v_mov_b32_e32 v12, v0
	v_mov_b32_e32 v13, v0
	v_mov_b32_e32 v14, v0
	v_mov_b32_e32 v15, v0
	v_mov_b32_e32 v16, v0
	v_mov_b32_e32 v17, v0
	v_mov_b32_e32 v18, v0
	v_mov_b32_e32 v19, v0
	v_mov_b32_e32 v20, v0
	v_mov_b32_e32 v21, v0
	v_mov_b32_e32 v22, v0
	v_mov_b32_e32 v23, v0
	v_mov_b32_e32 v24, v0
	v_mov_b32_e32 v25, v0
	v_mov_b32_e32 v26, v0
	v_mov_b32_e32 v27, v0
	v_mov_b32_e32 v28, v0
	v_mov_b32_e32 v29, v0
	v_mov_b32_e32 v30, v0
	v_mov_b32_e32 v31, v0
	v_mov_b32_e32 v32, v0
	v_mov_b32_e32 v33, v0
	v_mov_b32_e32 v34, v0
	v_mov_b32_e32 v35, v0
	v_mov_b32_e32 v36, v0
	v_mov_b32_e32 v37, v0
	v_mov_b32_e32 v38, v0
	v_mov_b32_e32 v39, v0
	v_mov_b32_e32 v40, v0
	v_mov_b32_e32 v41, v0
	v_mov_b32_e32 v42, v0
	v_mov_b32_e32 v43, v0
	v_mov_b32_e32 v44, v0
	v_mov_b32_e32 v45, v0
	v_mov_b32_e32 v46, v0
	v_mov_b32_e32 v47, v0
	v_mov_b32_e32 v48, v0
	v_mov_b32_e32 v49, v0
	v_mov_b32_e32 v50, v0
	v_mov_b32_e32 v51, v0
	v_mov_b32_e32 v52, v0
	v_mov_b32_e32 v53, v0
	v_mov_b32_e32 v54, v0
	v_mov_b32_e32 v55, v0
	v_mov_b32_e32 v56, v0
	v_mov_b32_e32 v57, v0
	v_mov_b32_e32 v58, v0
	v_mov_b32_e32 v59, v0
	v_mov_b32_e32 v60, v0
	v_mov_b32_e32 v61, v0
	v_mov_b32_e32 v62, v0
	v_mov_b32_e32 v63, v0
	v_mov_b32_e32 v64, v0
	v_mov_b32_e32 v65, v0
	v_mov_b32_e32 v66, v0
	v_mov_b32_e32 v67, v0
	v_mov_b32_e32 v68, v0
	v_mov_b32_e32 v69, v0
	v_mov_b32_e32 v70, v0
	v_mov_b32_e32 v71, v0
	v_mov_b32_e32 v72, v0
	v_mov_b32_e32 v73, v0
	v_mov_b32_e32 v74, v0
	v_mov_b32_e32 v75, v0
	v_mov_b32_e32 v76, v0
	v_mov_b32_e32 v77, v0
	v_mov_b32_e32 v78, v0
	v_mov_b32_e32 v79, v0
	v_mov_b32_e32 v80, v0
	v_mov_b32_e32 v81, v0
	v_mov_b32_e32 v82, v0
	v_mov_b32_e32 v83, v0
	v_mov_b32_e32 v84, v0
	v_mov_b32_e32 v85, v0
	v_mov_b32_e32 v86, v0
	v_mov_b32_e32 v87, v0
	v_mov_b32_e32 v88, v0
	v_mov_b32_e32 v89, v0
	v_mov_b32_e32 v90, v0
	v_mov_b32_e32 v91, v0
	v_mov_b32_e32 v92, v0
	v_mov_b32_e32 v93, v0
	v_mov_b32_e32 v94, v0
	v_mov_b32_e32 v95, v0
	v_mov_b32_e32 v96, v0
	v_mov_b32_e32 v97, v0
	v_mov_b32_e32 v98, v0
	v_mov_b32_e32 v99, v0
	v_mov_b32_e32 v100, v0
	v_mov_b32_e32 v101, v0
	v_mov_b32_e32 v102, v0
	v_mov_b32_e32 v103, v0
	v_mov_b32_e32 v104, v0
	v_mov_b32_e32 v105, v0
	v_mov_b32_e32 v106, v0
	v_mov_b32_e32 v107, v0
	v_mov_b32_e32 v108, v0
	v_mov_b32_e32 v109, v0
	v_mov_b32_e32 v110, v0
	v_mov_b32_e32 v111, v0
	v_mov_b32_e32 v112, v0
	v_mov_b32_e32 v113, v0
	v_mov_b32_e32 v114, v0
	v_mov_b32_e32 v115, v0
	v_mov_b32_e32 v116, v0
	v_mov_b32_e32 v117, v0
	v_mov_b32_e32 v118, v0
	v_mov_b32_e32 v119, v0
	v_mov_b32_e32 v120, v0
	v_mov_b32_e32 v121, v0
	v_mov_b32_e32 v122, v0
	v_mov_b32_e32 v123, v0
	v_mov_b32_e32 v124, v0
	v_mov_b32_e32 v125, v0
	v_mov_b32_e32 v126, v0
	v_mov_b32_e32 v127, v0
	s_mov_b64 s[12:13], 0x40180
	s_mov_b64 s[14:15], 0x60180
	s_mov_b64 s[58:59], 0x3ef0080
	s_mov_b64 s[68:69], 0x3f10080
	s_barrier

;   #define STAGE(P,BASE,LD,br,kt) do{ const HALF* _u=(BASE)+(long)(br)*(((&(LD))==&lda)?lda_u:(LD))+(long)(kt)*G_BK; \
;     for(int _i=0;_i<2;++_i){ \
;       __builtin_amdgcn_global_load_lds((const unsigned*)(_u+(long)_i*(((&(LD))==&lda)?stepa:stepb)+((&(LD))==&lda?oa0:ob0)), \
;         (unsigned*)((char*)(P)+t5*16+_i*8192),16,0,0);}}while(0)
;   #define WAIT_V(n) asm volatile("s_waitcnt vmcnt(" #n ")":::"memory")
;   #define BAR __builtin_amdgcn_s_barrier()
;     ...
;   {int _b=t5*16;int _r,_c;g_stage_rc(_b,_r,_c);
;     oa0=n2 ? (unsigned)((n2*(_r&63)+(_r>>6))*1024+_c) : (unsigned)(_r*lda+_c); ob0=(unsigned)(_r*ldb+_c);}
;   STAGE(SB(0,0),Bt,ldb,0,0); STAGE(SA(0,0),A,lda,0,0);
;   STAGE(SB(0,1),Bt,ldb,G_HALF,0); STAGE(SA(0,1),A,lda,G_HALF,0);
;   if(wr==1)BAR;
;   WAIT_V(4); BAR;
;   STAGE(SB(1,0),Bt,ldb,0,1); STAGE(SA(1,0),A,lda,0,1); STAGE(SB(1,1),Bt,ldb,G_HALF,1);
;   WAIT_V(6); BAR;
.LBB0_261:
	s_or_b64 exec, exec, s[12:13]
	v_lshlrev_b32_e32 v11, 6, v131
	v_lshlrev_b32_e32 v13, 2, v131
	v_and_b32_e32 v10, 48, v131
	v_and_b32_e32 v12, 0x3c0, v11
	v_and_b32_e32 v13, 32, v13
	v_add_u32_e32 v142, s29, v5
	v_bitop3_b32 v12, v12, v13, v10 bitop3:0x36
	v_and_b32_e32 v10, 0x3000, v11
	v_readfirstlane_b32 s12, v142
	v_add_u32_e32 v143, 0x2000, v142
	v_add_u32_e32 v13, s95, v10
	v_lshl_add_u64 v[10:11], v[0:1], 0, s[84:85]
	s_mov_b32 m0, s12
	s_mov_b64 s[58:59], 0x20080
	v_readfirstlane_b32 s12, v143
	v_add_u32_e32 v144, 0x8000, v136
	global_load_lds_dwordx4 v[10:11], off
	v_lshl_add_u64 v[0:1], v[0:1], 0, s[58:59]
	s_mov_b32 m0, s12
	v_readfirstlane_b32 s12, v144
	v_add_u32_e32 v145, 0xa000, v136
	global_load_lds_dwordx4 v[0:1], off
	v_lshl_add_u64 v[0:1], v[2:3], 0, s[84:85]
	s_mov_b32 m0, s12
	v_readfirstlane_b32 s12, v145
	global_load_lds_dwordx4 v[0:1], off
	v_lshl_add_u64 v[0:1], v[2:3], 0, s[58:59]
	s_mov_b32 m0, s12
	v_add_u32_e32 v146, s62, v5
	global_load_lds_dwordx4 v[0:1], off
	v_lshl_add_u64 v[0:1], v[152:153], 1, s[6:7]
	v_readfirstlane_b32 s6, v146
	v_add_u32_e32 v147, 0x2000, v146
	v_lshl_add_u64 v[2:3], v[0:1], 0, s[88:89]
	s_mov_b32 m0, s6
	v_readfirstlane_b32 s6, v147
	global_load_lds_dwordx4 v[2:3], off
	v_lshl_add_u64 v[0:1], v[0:1], 0, s[90:91]
	s_mov_b32 m0, s6
	v_lshl_add_u32 v9, v9, 13, 0
	global_load_lds_dwordx4 v[0:1], off
	v_lshlrev_b32_e32 v0, 13, v4
	v_and_b32_e32 v0, 0xffffc000, v0
	v_lshl_add_u32 v0, v6, 10, v0
	v_or_b32_e32 v0, v0, v7
	s_waitcnt vmcnt(10)
	s_barrier
	s_waitcnt vmcnt(6)
	v_add_u32_sdwa v0, v0, sext(v8) dst_sel:DWORD dst_unused:UNUSED_PAD src0_sel:DWORD src1_sel:WORD_0
	v_mov_b32_e32 v1, v153
	v_lshlrev_b64 v[128:129], 1, v[0:1]
	s_add_u32 s2, s2, s10
	v_mov_b32_e32 v0, 0
	s_addc_u32 s3, s3, s11
	s_mov_b32 s12, -2
	v_add_u32_e32 v133, v13, v12
	v_add_u32_e32 v132, v9, v12
	s_mov_b64 s[6:7], s[0:1]
	v_mov_b32_e32 v1, v0
	v_mov_b32_e32 v2, v0
	v_mov_b32_e32 v3, v0
	v_mov_b32_e32 v4, v0
	v_mov_b32_e32 v5, v0
	v_mov_b32_e32 v6, v0
	v_mov_b32_e32 v7, v0
	v_mov_b32_e32 v8, v0
	v_mov_b32_e32 v9, v0
	v_mov_b32_e32 v10, v0
	v_mov_b32_e32 v11, v0
	v_mov_b32_e32 v12, v0
	v_mov_b32_e32 v13, v0
	v_mov_b32_e32 v14, v0
	v_mov_b32_e32 v15, v0
	v_mov_b32_e32 v16, v0
	v_mov_b32_e32 v17, v0
	v_mov_b32_e32 v18, v0
	v_mov_b32_e32 v19, v0
	v_mov_b32_e32 v20, v0
	v_mov_b32_e32 v21, v0
	v_mov_b32_e32 v22, v0
	v_mov_b32_e32 v23, v0
	v_mov_b32_e32 v24, v0
	v_mov_b32_e32 v25, v0
	v_mov_b32_e32 v26, v0
	v_mov_b32_e32 v27, v0
	v_mov_b32_e32 v28, v0
	v_mov_b32_e32 v29, v0
	v_mov_b32_e32 v30, v0
	v_mov_b32_e32 v31, v0
	v_mov_b32_e32 v32, v0
	v_mov_b32_e32 v33, v0
	v_mov_b32_e32 v34, v0
	v_mov_b32_e32 v35, v0
	v_mov_b32_e32 v36, v0
	v_mov_b32_e32 v37, v0
	v_mov_b32_e32 v38, v0
	v_mov_b32_e32 v39, v0
	v_mov_b32_e32 v40, v0
	v_mov_b32_e32 v41, v0
	v_mov_b32_e32 v42, v0
	v_mov_b32_e32 v43, v0
	v_mov_b32_e32 v44, v0
	v_mov_b32_e32 v45, v0
	v_mov_b32_e32 v46, v0
	v_mov_b32_e32 v47, v0
	v_mov_b32_e32 v48, v0
	v_mov_b32_e32 v49, v0
	v_mov_b32_e32 v50, v0
	v_mov_b32_e32 v51, v0
	v_mov_b32_e32 v52, v0
	v_mov_b32_e32 v53, v0
	v_mov_b32_e32 v54, v0
	v_mov_b32_e32 v55, v0
	v_mov_b32_e32 v56, v0
	v_mov_b32_e32 v57, v0
	v_mov_b32_e32 v58, v0
	v_mov_b32_e32 v59, v0
	v_mov_b32_e32 v60, v0
	v_mov_b32_e32 v61, v0
	v_mov_b32_e32 v62, v0
	v_mov_b32_e32 v63, v0
	v_mov_b32_e32 v64, v0
	v_mov_b32_e32 v65, v0
	v_mov_b32_e32 v66, v0
	v_mov_b32_e32 v67, v0
	v_mov_b32_e32 v68, v0
	v_mov_b32_e32 v69, v0
	v_mov_b32_e32 v70, v0
	v_mov_b32_e32 v71, v0
	v_mov_b32_e32 v72, v0
	v_mov_b32_e32 v73, v0
	v_mov_b32_e32 v74, v0
	v_mov_b32_e32 v75, v0
	v_mov_b32_e32 v76, v0
	v_mov_b32_e32 v77, v0
	v_mov_b32_e32 v78, v0
	v_mov_b32_e32 v79, v0
	v_mov_b32_e32 v80, v0
	v_mov_b32_e32 v81, v0
	v_mov_b32_e32 v82, v0
	v_mov_b32_e32 v83, v0
	v_mov_b32_e32 v84, v0
	v_mov_b32_e32 v85, v0
	v_mov_b32_e32 v86, v0
	v_mov_b32_e32 v87, v0
	v_mov_b32_e32 v88, v0
	v_mov_b32_e32 v89, v0
	v_mov_b32_e32 v90, v0
	v_mov_b32_e32 v91, v0
	v_mov_b32_e32 v92, v0
	v_mov_b32_e32 v93, v0
	v_mov_b32_e32 v94, v0
	v_mov_b32_e32 v95, v0
	v_mov_b32_e32 v96, v0
	v_mov_b32_e32 v97, v0
	v_mov_b32_e32 v98, v0
	v_mov_b32_e32 v99, v0
	v_mov_b32_e32 v100, v0
	v_mov_b32_e32 v101, v0
	v_mov_b32_e32 v102, v0
	v_mov_b32_e32 v103, v0
	v_mov_b32_e32 v104, v0
	v_mov_b32_e32 v105, v0
	v_mov_b32_e32 v106, v0
	v_mov_b32_e32 v107, v0
	v_mov_b32_e32 v108, v0
	v_mov_b32_e32 v109, v0
	v_mov_b32_e32 v110, v0
	v_mov_b32_e32 v111, v0
	v_mov_b32_e32 v112, v0
	v_mov_b32_e32 v113, v0
	v_mov_b32_e32 v114, v0
	v_mov_b32_e32 v115, v0
	v_mov_b32_e32 v116, v0
	v_mov_b32_e32 v117, v0
	v_mov_b32_e32 v118, v0
	v_mov_b32_e32 v119, v0
	v_mov_b32_e32 v120, v0
	v_mov_b32_e32 v121, v0
	v_mov_b32_e32 v122, v0
	v_mov_b32_e32 v123, v0
	v_mov_b32_e32 v124, v0
	v_mov_b32_e32 v125, v0
	v_mov_b32_e32 v126, v0
	v_mov_b32_e32 v127, v0
	s_barrier

;   #define STAGE(P,BASE,LD,br,kt) do{ const HALF* _u=(BASE)+(long)(br)*(((&(LD))==&lda)?lda_u:(LD))+(long)(kt)*G_BK; \
;     for(int _i=0;_i<2;++_i){ \
;       __builtin_amdgcn_global_load_lds((const unsigned*)(_u+(long)_i*(((&(LD))==&lda)?stepa:stepb)+((&(LD))==&lda?oa0:ob0)), \
;         (unsigned*)((char*)(P)+t5*16+_i*8192),16,0,0);}}while(0)
;   #define WAIT_V(n) asm volatile("s_waitcnt vmcnt(" #n ")":::"memory")
;   #define BAR __builtin_amdgcn_s_barrier()
;     ...
;   {int _b=t5*16;int _r,_c;g_stage_rc(_b,_r,_c);
;     oa0=n2 ? (unsigned)((n2*(_r&63)+(_r>>6))*1024+_c) : (unsigned)(_r*lda+_c); ob0=(unsigned)(_r*ldb+_c);}
;   STAGE(SB(0,0),Bt,ldb,0,0); STAGE(SA(0,0),A,lda,0,0);
;   STAGE(SB(0,1),Bt,ldb,G_HALF,0); STAGE(SA(0,1),A,lda,G_HALF,0);
;   if(wr==1)BAR;
;   WAIT_V(4); BAR;
;   STAGE(SB(1,0),Bt,ldb,0,1); STAGE(SA(1,0),A,lda,0,1); STAGE(SB(1,1),Bt,ldb,G_HALF,1);
;   WAIT_V(6); BAR;
.LBB0_294:
	s_or_b64 exec, exec, s[12:13]
	v_lshlrev_b32_e32 v11, 6, v131
	v_lshlrev_b32_e32 v13, 2, v131
	v_and_b32_e32 v10, 48, v131
	v_and_b32_e32 v12, 0x3c0, v11
	v_and_b32_e32 v13, 32, v13
	v_add_u32_e32 v142, s29, v5
	v_bitop3_b32 v12, v12, v13, v10 bitop3:0x36
	v_and_b32_e32 v10, 0x3000, v11
	v_readfirstlane_b32 s8, v142
	v_add_u32_e32 v143, 0x2000, v142
	v_add_u32_e32 v13, s95, v10
	v_lshl_add_u64 v[10:11], v[0:1], 0, s[84:85]
	s_mov_b32 m0, s8
	s_mov_b64 s[12:13], 0x20080
	v_readfirstlane_b32 s8, v143
	v_add_u32_e32 v144, 0x8000, v136
	global_load_lds_dwordx4 v[10:11], off
	v_lshl_add_u64 v[0:1], v[0:1], 0, s[12:13]
	s_mov_b32 m0, s8
	v_readfirstlane_b32 s8, v144
	v_add_u32_e32 v145, 0xa000, v136
	global_load_lds_dwordx4 v[0:1], off
	v_lshl_add_u64 v[0:1], v[2:3], 0, s[84:85]
	s_mov_b32 m0, s8
	v_readfirstlane_b32 s8, v145
	global_load_lds_dwordx4 v[0:1], off
	v_lshl_add_u64 v[0:1], v[2:3], 0, s[12:13]
	s_mov_b32 m0, s8
	v_add_u32_e32 v146, s62, v5
	global_load_lds_dwordx4 v[0:1], off
	v_lshl_add_u64 v[0:1], v[152:153], 1, s[6:7]
	v_readfirstlane_b32 s6, v146
	v_add_u32_e32 v147, 0x2000, v146
	v_lshl_add_u64 v[2:3], v[0:1], 0, s[88:89]
	s_mov_b32 m0, s6
	v_readfirstlane_b32 s6, v147
	global_load_lds_dwordx4 v[2:3], off
	v_lshl_add_u64 v[0:1], v[0:1], 0, s[90:91]
	s_mov_b32 m0, s6
	v_lshl_add_u32 v9, v9, 13, 0
	global_load_lds_dwordx4 v[0:1], off
	v_lshlrev_b32_e32 v0, 13, v4
	v_and_b32_e32 v0, 0xffffc000, v0
	v_lshl_add_u32 v0, v6, 10, v0
	v_or_b32_e32 v0, v0, v7
	s_waitcnt vmcnt(10)
	s_barrier
	s_waitcnt vmcnt(6)
	v_add_u32_sdwa v0, v0, sext(v8) dst_sel:DWORD dst_unused:UNUSED_PAD src0_sel:DWORD src1_sel:WORD_0
	v_mov_b32_e32 v1, v153
	v_lshlrev_b64 v[128:129], 1, v[0:1]
	s_add_u32 s2, s2, s10
	v_mov_b32_e32 v0, 0
	s_addc_u32 s3, s3, s11
	s_mov_b32 s8, -2
	v_add_u32_e32 v133, v13, v12
	v_add_u32_e32 v132, v9, v12
	s_mov_b64 s[6:7], s[0:1]
	v_mov_b32_e32 v1, v0
	v_mov_b32_e32 v2, v0
	v_mov_b32_e32 v3, v0
	v_mov_b32_e32 v4, v0
	v_mov_b32_e32 v5, v0
	v_mov_b32_e32 v6, v0
	v_mov_b32_e32 v7, v0
	v_mov_b32_e32 v8, v0
	v_mov_b32_e32 v9, v0
	v_mov_b32_e32 v10, v0
	v_mov_b32_e32 v11, v0
	v_mov_b32_e32 v12, v0
	v_mov_b32_e32 v13, v0
	v_mov_b32_e32 v14, v0
	v_mov_b32_e32 v15, v0
	v_mov_b32_e32 v16, v0
	v_mov_b32_e32 v17, v0
	v_mov_b32_e32 v18, v0
	v_mov_b32_e32 v19, v0
	v_mov_b32_e32 v20, v0
	v_mov_b32_e32 v21, v0
	v_mov_b32_e32 v22, v0
	v_mov_b32_e32 v23, v0
	v_mov_b32_e32 v24, v0
	v_mov_b32_e32 v25, v0
	v_mov_b32_e32 v26, v0
	v_mov_b32_e32 v27, v0
	v_mov_b32_e32 v28, v0
	v_mov_b32_e32 v29, v0
	v_mov_b32_e32 v30, v0
	v_mov_b32_e32 v31, v0
	v_mov_b32_e32 v32, v0
	v_mov_b32_e32 v33, v0
	v_mov_b32_e32 v34, v0
	v_mov_b32_e32 v35, v0
	v_mov_b32_e32 v36, v0
	v_mov_b32_e32 v37, v0
	v_mov_b32_e32 v38, v0
	v_mov_b32_e32 v39, v0
	v_mov_b32_e32 v40, v0
	v_mov_b32_e32 v41, v0
	v_mov_b32_e32 v42, v0
	v_mov_b32_e32 v43, v0
	v_mov_b32_e32 v44, v0
	v_mov_b32_e32 v45, v0
	v_mov_b32_e32 v46, v0
	v_mov_b32_e32 v47, v0
	v_mov_b32_e32 v48, v0
	v_mov_b32_e32 v49, v0
	v_mov_b32_e32 v50, v0
	v_mov_b32_e32 v51, v0
	v_mov_b32_e32 v52, v0
	v_mov_b32_e32 v53, v0
	v_mov_b32_e32 v54, v0
	v_mov_b32_e32 v55, v0
	v_mov_b32_e32 v56, v0
	v_mov_b32_e32 v57, v0
	v_mov_b32_e32 v58, v0
	v_mov_b32_e32 v59, v0
	v_mov_b32_e32 v60, v0
	v_mov_b32_e32 v61, v0
	v_mov_b32_e32 v62, v0
	v_mov_b32_e32 v63, v0
	v_mov_b32_e32 v64, v0
	v_mov_b32_e32 v65, v0
	v_mov_b32_e32 v66, v0
	v_mov_b32_e32 v67, v0
	v_mov_b32_e32 v68, v0
	v_mov_b32_e32 v69, v0
	v_mov_b32_e32 v70, v0
	v_mov_b32_e32 v71, v0
	v_mov_b32_e32 v72, v0
	v_mov_b32_e32 v73, v0
	v_mov_b32_e32 v74, v0
	v_mov_b32_e32 v75, v0
	v_mov_b32_e32 v76, v0
	v_mov_b32_e32 v77, v0
	v_mov_b32_e32 v78, v0
	v_mov_b32_e32 v79, v0
	v_mov_b32_e32 v80, v0
	v_mov_b32_e32 v81, v0
	v_mov_b32_e32 v82, v0
	v_mov_b32_e32 v83, v0
	v_mov_b32_e32 v84, v0
	v_mov_b32_e32 v85, v0
	v_mov_b32_e32 v86, v0
	v_mov_b32_e32 v87, v0
	v_mov_b32_e32 v88, v0
	v_mov_b32_e32 v89, v0
	v_mov_b32_e32 v90, v0
	v_mov_b32_e32 v91, v0
	v_mov_b32_e32 v92, v0
	v_mov_b32_e32 v93, v0
	v_mov_b32_e32 v94, v0
	v_mov_b32_e32 v95, v0
	v_mov_b32_e32 v96, v0
	v_mov_b32_e32 v97, v0
	v_mov_b32_e32 v98, v0
	v_mov_b32_e32 v99, v0
	v_mov_b32_e32 v100, v0
	v_mov_b32_e32 v101, v0
	v_mov_b32_e32 v102, v0
	v_mov_b32_e32 v103, v0
	v_mov_b32_e32 v104, v0
	v_mov_b32_e32 v105, v0
	v_mov_b32_e32 v106, v0
	v_mov_b32_e32 v107, v0
	v_mov_b32_e32 v108, v0
	v_mov_b32_e32 v109, v0
	v_mov_b32_e32 v110, v0
	v_mov_b32_e32 v111, v0
	v_mov_b32_e32 v112, v0
	v_mov_b32_e32 v113, v0
	v_mov_b32_e32 v114, v0
	v_mov_b32_e32 v115, v0
	v_mov_b32_e32 v116, v0
	v_mov_b32_e32 v117, v0
	v_mov_b32_e32 v118, v0
	v_mov_b32_e32 v119, v0
	v_mov_b32_e32 v120, v0
	v_mov_b32_e32 v121, v0
	v_mov_b32_e32 v122, v0
	v_mov_b32_e32 v123, v0
	v_mov_b32_e32 v124, v0
	v_mov_b32_e32 v125, v0
	v_mov_b32_e32 v126, v0
	v_mov_b32_e32 v127, v0
	s_barrier

;   #define STAGE(P,BASE,LD,br,kt) do{ const HALF* _u=(BASE)+(long)(br)*(((&(LD))==&lda)?lda_u:(LD))+(long)(kt)*G_BK; \
;     for(int _i=0;_i<2;++_i){ \
;       __builtin_amdgcn_global_load_lds((const unsigned*)(_u+(long)_i*(((&(LD))==&lda)?stepa:stepb)+((&(LD))==&lda?oa0:ob0)), \
;         (unsigned*)((char*)(P)+t5*16+_i*8192),16,0,0);}}while(0)
;   #define WAIT_V(n) asm volatile("s_waitcnt vmcnt(" #n ")":::"memory")
;   #define BAR __builtin_amdgcn_s_barrier()
;     ...
;   {int _b=t5*16;int _r,_c;g_stage_rc(_b,_r,_c);
;     oa0=n2 ? (unsigned)((n2*(_r&63)+(_r>>6))*1024+_c) : (unsigned)(_r*lda+_c); ob0=(unsigned)(_r*ldb+_c);}
;   STAGE(SB(0,0),Bt,ldb,0,0); STAGE(SA(0,0),A,lda,0,0);
;   STAGE(SB(0,1),Bt,ldb,G_HALF,0); STAGE(SA(0,1),A,lda,G_HALF,0);
;   if(wr==1)BAR;
;   WAIT_V(4); BAR;
;   STAGE(SB(1,0),Bt,ldb,0,1); STAGE(SA(1,0),A,lda,0,1); STAGE(SB(1,1),Bt,ldb,G_HALF,1);
;   WAIT_V(6); BAR;
.LBB0_322:
	s_or_b64 exec, exec, s[14:15]
	s_lshl_b32 s14, s17, 8
	s_and_b32 s14, s14, 0x180000
	v_readlane_b32 s22, v254, 8
	v_readlane_b32 s23, v254, 9
	s_add_u32 s58, s22, s14
	s_addc_u32 s59, s23, 0
	s_lshl_b32 s15, s19, 2
	s_and_b32 s15, s15, 0x700
	s_and_b32 s14, s19, 0xfffff800
	s_or_b32 s14, s14, s15
	s_ashr_i32 s15, s14, 31
	v_lshlrev_b32_e32 v11, 6, v131
	v_lshlrev_b32_e32 v13, 2, v131
	s_lshl_b64 s[14:15], s[14:15], 11
	v_and_b32_e32 v10, 48, v131
	v_and_b32_e32 v12, 0x3c0, v11
	v_and_b32_e32 v13, 32, v13
	v_add_u32_e32 v142, s29, v5
	s_add_u32 s70, s22, s14
	v_bitop3_b32 v12, v12, v13, v10 bitop3:0x36
	v_and_b32_e32 v10, 0x3000, v11
	v_readfirstlane_b32 s14, v142
	v_add_u32_e32 v143, 0x2000, v142
	s_addc_u32 s71, s23, s15
	v_add_u32_e32 v13, s95, v10
	v_lshl_add_u64 v[10:11], v[0:1], 0, s[84:85]
	s_mov_b32 m0, s14
	s_mov_b64 s[22:23], 0x20080
	v_readfirstlane_b32 s14, v143
	v_add_u32_e32 v144, 0x8000, v136
	global_load_lds_dwordx4 v[10:11], off
	v_lshl_add_u64 v[0:1], v[0:1], 0, s[22:23]
	s_mov_b32 m0, s14
	v_readfirstlane_b32 s14, v144
	v_add_u32_e32 v145, 0xa000, v136
	global_load_lds_dwordx4 v[0:1], off
	v_lshl_add_u64 v[0:1], v[2:3], 0, s[84:85]
	s_mov_b32 m0, s14
	v_readfirstlane_b32 s14, v145
	global_load_lds_dwordx4 v[0:1], off
	v_lshl_add_u64 v[0:1], v[2:3], 0, s[22:23]
	s_mov_b32 m0, s14
	v_add_u32_e32 v146, s62, v5
	global_load_lds_dwordx4 v[0:1], off
	v_lshl_add_u64 v[0:1], v[152:153], 1, s[12:13]
	v_readfirstlane_b32 s12, v146
	v_add_u32_e32 v147, 0x2000, v146
	v_lshl_add_u64 v[2:3], v[0:1], 0, s[88:89]
	s_mov_b32 m0, s12
	v_readfirstlane_b32 s12, v147
	global_load_lds_dwordx4 v[2:3], off
	v_lshl_add_u64 v[0:1], v[0:1], 0, s[90:91]
	s_mov_b32 m0, s12
	v_lshl_add_u32 v9, v9, 13, 0
	global_load_lds_dwordx4 v[0:1], off
	v_lshlrev_b32_e32 v0, 13, v4
	v_and_b32_e32 v0, 0xffffc000, v0
	v_lshl_add_u32 v0, v6, 10, v0
	v_or_b32_e32 v0, v0, v7
	s_waitcnt vmcnt(10)
	s_barrier
	s_waitcnt vmcnt(6)
	v_add_u32_sdwa v0, v0, sext(v8) dst_sel:DWORD dst_unused:UNUSED_PAD src0_sel:DWORD src1_sel:WORD_0
	v_mov_b32_e32 v1, v153
	v_lshlrev_b64 v[128:129], 1, v[0:1]
	v_mov_b32_e32 v0, 0
	s_mov_b32 s12, -2
	v_add_u32_e32 v133, v13, v12
	v_add_u32_e32 v132, v9, v12
	v_mov_b32_e32 v1, v0
	v_mov_b32_e32 v2, v0
	v_mov_b32_e32 v3, v0
	v_mov_b32_e32 v4, v0
	v_mov_b32_e32 v5, v0
	v_mov_b32_e32 v6, v0
	v_mov_b32_e32 v7, v0
	v_mov_b32_e32 v8, v0
	v_mov_b32_e32 v9, v0
	v_mov_b32_e32 v10, v0
	v_mov_b32_e32 v11, v0
	v_mov_b32_e32 v12, v0
	v_mov_b32_e32 v13, v0
	v_mov_b32_e32 v14, v0
	v_mov_b32_e32 v15, v0
	v_mov_b32_e32 v16, v0
	v_mov_b32_e32 v17, v0
	v_mov_b32_e32 v18, v0
	v_mov_b32_e32 v19, v0
	v_mov_b32_e32 v20, v0
	v_mov_b32_e32 v21, v0
	v_mov_b32_e32 v22, v0
	v_mov_b32_e32 v23, v0
	v_mov_b32_e32 v24, v0
	v_mov_b32_e32 v25, v0
	v_mov_b32_e32 v26, v0
	v_mov_b32_e32 v27, v0
	v_mov_b32_e32 v28, v0
	v_mov_b32_e32 v29, v0
	v_mov_b32_e32 v30, v0
	v_mov_b32_e32 v31, v0
	v_mov_b32_e32 v32, v0
	v_mov_b32_e32 v33, v0
	v_mov_b32_e32 v34, v0
	v_mov_b32_e32 v35, v0
	v_mov_b32_e32 v36, v0
	v_mov_b32_e32 v37, v0
	v_mov_b32_e32 v38, v0
	v_mov_b32_e32 v39, v0
	v_mov_b32_e32 v40, v0
	v_mov_b32_e32 v41, v0
	v_mov_b32_e32 v42, v0
	v_mov_b32_e32 v43, v0
	v_mov_b32_e32 v44, v0
	v_mov_b32_e32 v45, v0
	v_mov_b32_e32 v46, v0
	v_mov_b32_e32 v47, v0
	v_mov_b32_e32 v48, v0
	v_mov_b32_e32 v49, v0
	v_mov_b32_e32 v50, v0
	v_mov_b32_e32 v51, v0
	v_mov_b32_e32 v52, v0
	v_mov_b32_e32 v53, v0
	v_mov_b32_e32 v54, v0
	v_mov_b32_e32 v55, v0
	v_mov_b32_e32 v56, v0
	v_mov_b32_e32 v57, v0
	v_mov_b32_e32 v58, v0
	v_mov_b32_e32 v59, v0
	v_mov_b32_e32 v60, v0
	v_mov_b32_e32 v61, v0
	v_mov_b32_e32 v62, v0
	v_mov_b32_e32 v63, v0
	v_mov_b32_e32 v64, v0
	v_mov_b32_e32 v65, v0
	v_mov_b32_e32 v66, v0
	v_mov_b32_e32 v67, v0
	v_mov_b32_e32 v68, v0
	v_mov_b32_e32 v69, v0
	v_mov_b32_e32 v70, v0
	v_mov_b32_e32 v71, v0
	v_mov_b32_e32 v72, v0
	v_mov_b32_e32 v73, v0
	v_mov_b32_e32 v74, v0
	v_mov_b32_e32 v75, v0
	v_mov_b32_e32 v76, v0
	v_mov_b32_e32 v77, v0
	v_mov_b32_e32 v78, v0
	v_mov_b32_e32 v79, v0
	v_mov_b32_e32 v80, v0
	v_mov_b32_e32 v81, v0
	v_mov_b32_e32 v82, v0
	v_mov_b32_e32 v83, v0
	v_mov_b32_e32 v84, v0
	v_mov_b32_e32 v85, v0
	v_mov_b32_e32 v86, v0
	v_mov_b32_e32 v87, v0
	v_mov_b32_e32 v88, v0
	v_mov_b32_e32 v89, v0
	v_mov_b32_e32 v90, v0
	v_mov_b32_e32 v91, v0
	v_mov_b32_e32 v92, v0
	v_mov_b32_e32 v93, v0
	v_mov_b32_e32 v94, v0
	v_mov_b32_e32 v95, v0
	v_mov_b32_e32 v96, v0
	v_mov_b32_e32 v97, v0
	v_mov_b32_e32 v98, v0
	v_mov_b32_e32 v99, v0
	v_mov_b32_e32 v100, v0
	v_mov_b32_e32 v101, v0
	v_mov_b32_e32 v102, v0
	v_mov_b32_e32 v103, v0
	v_mov_b32_e32 v104, v0
	v_mov_b32_e32 v105, v0
	v_mov_b32_e32 v106, v0
	v_mov_b32_e32 v107, v0
	v_mov_b32_e32 v108, v0
	v_mov_b32_e32 v109, v0
	v_mov_b32_e32 v110, v0
	v_mov_b32_e32 v111, v0
	v_mov_b32_e32 v112, v0
	v_mov_b32_e32 v113, v0
	v_mov_b32_e32 v114, v0
	v_mov_b32_e32 v115, v0
	v_mov_b32_e32 v116, v0
	v_mov_b32_e32 v117, v0
	v_mov_b32_e32 v118, v0
	v_mov_b32_e32 v119, v0
	v_mov_b32_e32 v120, v0
	v_mov_b32_e32 v121, v0
	v_mov_b32_e32 v122, v0
	v_mov_b32_e32 v123, v0
	v_mov_b32_e32 v124, v0
	v_mov_b32_e32 v125, v0
	v_mov_b32_e32 v126, v0
	v_mov_b32_e32 v127, v0
	s_barrier

;   #define STAGE(P,BASE,LD,br,kt) do{ const HALF* _u=(BASE)+(long)(br)*(((&(LD))==&lda)?lda_u:(LD))+(long)(kt)*G_BK; \
;     for(int _i=0;_i<2;++_i){ \
;       __builtin_amdgcn_global_load_lds((const unsigned*)(_u+(long)_i*(((&(LD))==&lda)?stepa:stepb)+((&(LD))==&lda?oa0:ob0)), \
;         (unsigned*)((char*)(P)+t5*16+_i*8192),16,0,0);}}while(0)
;   #define LDA(dst,b,h) for(int m=0;m<4;++m)for(int k=0;k<2;++k) \
;     dst[m][k]=*reinterpret_cast<const h8*>(la+(((b)*2+(h))*16384+m*2048+k*1024))
;   #define LDB(dst,b,h) for(int n=0;n<2;++n)for(int k=0;k<2;++k) \
;     dst[n][k]=*reinterpret_cast<const h8*>(lb+(((b)*2+(h))*16384+n*2048+k*1024))
;   #define MMA(ai,bj,At,Bt_) do{__builtin_amdgcn_s_setprio(1); \
;     for(int m=0;m<4;++m)for(int n=0;n<2;++n)for(int k=0;k<2;++k) \
;       acc[ai][bj][m][n]=__builtin_amdgcn_mfma_f32_16x16x32_f16(At[m][k],Bt_[n][k],acc[ai][bj][m][n],0,0,0); \
;     __builtin_amdgcn_s_setprio(0);}while(0)
;   #define WAIT_V(n) asm volatile("s_waitcnt vmcnt(" #n ")":::"memory")
;   #define WAIT_L(n) asm volatile("s_waitcnt lgkmcnt(" #n ")":::"memory")
;   #define BAR __builtin_amdgcn_s_barrier()
;   #define SCHED __builtin_amdgcn_sched_barrier(0)
;     ...
;   {int _b=t5*16;int _r,_c;g_stage_rc(_b,_r,_c);
;     oa0=n2 ? (unsigned)((n2*(_r&63)+(_r>>6))*1024+_c) : (unsigned)(_r*lda+_c); ob0=(unsigned)(_r*ldb+_c);}
;   STAGE(SB(0,0),Bt,ldb,0,0); STAGE(SA(0,0),A,lda,0,0);
;   STAGE(SB(0,1),Bt,ldb,G_HALF,0); STAGE(SA(0,1),A,lda,G_HALF,0);
;   if(wr==1)BAR;
;   WAIT_V(4); BAR;
;   STAGE(SB(1,0),Bt,ldb,0,1); STAGE(SA(1,0),A,lda,0,1); STAGE(SB(1,1),Bt,ldb,G_HALF,1);
;   WAIT_V(6); BAR;
;   for(int t=0;t<nt-2;t+=2){
;     LDB(B0,0,0); SCHED; LDA(At,0,0); STAGE(SA(1,1),A,lda,G_HALF,t+1);
;     WAIT_L(8); BAR; WAIT_L(0); MMA(0,0,At,B0); BAR; SCHED;
;     LDB(B1,0,1); STAGE(SB(0,0),Bt,ldb,0,t+2);
;     BAR; WAIT_L(0); MMA(0,1,At,B1); BAR;
;     LDA(At,0,1); STAGE(SA(0,0),A,lda,0,t+2);
.LBB0_380:
	s_or_b64 exec, exec, s[0:1]
	v_lshlrev_b32_e32 v19, 6, v128
	v_lshlrev_b32_e32 v21, 2, v128
	v_and_b32_e32 v18, 48, v128
	v_and_b32_e32 v20, 0x3c0, v19
	v_and_b32_e32 v21, 32, v21
	v_bitop3_b32 v20, v20, v21, v18 bitop3:0x36
	v_lshlrev_b32_e32 v21, 13, v17
	v_add_u32_e32 v17, s29, v16
	v_and_b32_e32 v22, 0x3000, v19
	v_readfirstlane_b32 s15, v17
	v_add_u32_e32 v17, 0x2000, v17
	v_lshl_add_u64 v[18:19], v[4:5], 0, s[84:85]
	s_mov_b32 m0, s15
	s_mov_b64 s[16:17], 0x20080
	v_readfirstlane_b32 s14, v17
	v_add_u32_e32 v17, 0x8000, v12
	global_load_lds_dwordx4 v[18:19], off
	v_lshl_add_u64 v[18:19], v[4:5], 0, s[16:17]
	s_mov_b32 m0, s14
	v_readfirstlane_b32 s12, v17
	v_add_u32_e32 v17, 0xa000, v12
	global_load_lds_dwordx4 v[18:19], off
	v_lshl_add_u64 v[18:19], v[0:1], 0, s[84:85]
	s_mov_b32 m0, s12
	v_readfirstlane_b32 s7, v17
	v_add_u32_e32 v23, s62, v16
	global_load_lds_dwordx4 v[18:19], off
	v_lshl_add_u64 v[18:19], v[0:1], 0, s[16:17]
	s_mov_b32 m0, s7
	v_readfirstlane_b32 s1, v23
	global_load_lds_dwordx4 v[18:19], off
	v_lshl_add_u64 v[18:19], v[4:5], 0, s[88:89]
	s_mov_b32 m0, s1
	v_lshl_add_u64 v[16:17], v[4:5], 0, s[90:91]
	global_load_lds_dwordx4 v[18:19], off
	v_add_u32_e32 v18, 0x2000, v23
	v_add3_u32 v129, s95, v22, v20
	v_readfirstlane_b32 s0, v18
	s_mov_b32 m0, s0
	v_add3_u32 v131, 0, v21, v20
	global_load_lds_dwordx4 v[16:17], off
	s_waitcnt vmcnt(10)
	s_barrier
	s_waitcnt vmcnt(6)
	s_barrier
	ds_read_b128 v[16:19], v129
	ds_read_b128 v[20:23], v129 offset:1024
	ds_read_b128 v[24:27], v129 offset:2048
	ds_read_b128 v[28:31], v129 offset:3072
	v_add_u32_e32 v66, 0xc000, v12
	v_lshl_add_u64 v[64:65], v[6:7], 0, s[84:85]
	v_readfirstlane_b32 s13, v66
	v_add_u32_e32 v66, 0xe000, v12
	s_mov_b32 m0, s13
	v_readfirstlane_b32 s11, v66
	ds_read_b128 v[32:35], v131
	ds_read_b128 v[36:39], v131 offset:1024
	ds_read_b128 v[40:43], v131 offset:2048
	ds_read_b128 v[44:47], v131 offset:3072
	ds_read_b128 v[48:51], v131 offset:4096
	ds_read_b128 v[52:55], v131 offset:5120
	ds_read_b128 v[56:59], v131 offset:6144
	ds_read_b128 v[60:63], v131 offset:7168
	global_load_lds_dwordx4 v[64:65], off
	v_lshl_add_u64 v[64:65], v[6:7], 0, s[16:17]
	s_mov_b32 m0, s11
	s_nop 0
	global_load_lds_dwordx4 v[64:65], off
	s_waitcnt lgkmcnt(8)
	s_barrier
	s_waitcnt lgkmcnt(0)
	s_setprio 1
	s_waitcnt lgkmcnt(0)
	v_mfma_f32_16x16x32_f16 v[64:67], v[32:35], v[16:19], 0
	v_mfma_f32_16x16x32_f16 v[68:71], v[32:35], v[24:27], 0
	v_mfma_f32_16x16x32_f16 v[72:75], v[40:43], v[16:19], 0
	v_mfma_f32_16x16x32_f16 v[76:79], v[40:43], v[24:27], 0
	v_mfma_f32_16x16x32_f16 v[80:83], v[48:51], v[16:19], 0
	v_mfma_f32_16x16x32_f16 v[84:87], v[48:51], v[24:27], 0
	v_mfma_f32_16x16x32_f16 v[88:91], v[56:59], v[16:19], 0
	v_mfma_f32_16x16x32_f16 v[92:95], v[56:59], v[24:27], 0
	v_mfma_f32_16x16x32_f16 v[64:67], v[36:39], v[20:23], v[64:67]
	v_mfma_f32_16x16x32_f16 v[68:71], v[36:39], v[28:31], v[68:71]
	v_mfma_f32_16x16x32_f16 v[72:75], v[44:47], v[20:23], v[72:75]
	v_mfma_f32_16x16x32_f16 v[76:79], v[44:47], v[28:31], v[76:79]
	v_mfma_f32_16x16x32_f16 v[80:83], v[52:55], v[20:23], v[80:83]
	v_mfma_f32_16x16x32_f16 v[84:87], v[52:55], v[28:31], v[84:87]
	v_mfma_f32_16x16x32_f16 v[88:91], v[60:63], v[20:23], v[88:91]
	v_mfma_f32_16x16x32_f16 v[92:95], v[60:63], v[28:31], v[92:95]
	s_setprio 0
	s_barrier
	v_readfirstlane_b32 s16, v14
	v_lshl_add_u64 v[112:113], v[4:5], 0, s[92:93]
	s_mov_b32 m0, s16
	v_readfirstlane_b32 s16, v15
	ds_read_b128 v[96:99], v129 offset:16384
	ds_read_b128 v[100:103], v129 offset:17408
	ds_read_b128 v[104:107], v129 offset:18432
	ds_read_b128 v[108:111], v129 offset:19456
	global_load_lds_dwordx4 v[112:113], off
	v_lshl_add_u64 v[112:113], v[4:5], 0, s[66:67]
	s_mov_b32 m0, s16
	s_nop 0
	global_load_lds_dwordx4 v[112:113], off
	s_barrier
	s_waitcnt lgkmcnt(0)
	s_setprio 1
	s_waitcnt lgkmcnt(0)
	v_mfma_f32_16x16x32_f16 v[112:115], v[32:35], v[96:99], 0
	v_mfma_f32_16x16x32_f16 v[32:35], v[32:35], v[104:107], 0
	v_mfma_f32_16x16x32_f16 v[112:115], v[36:39], v[100:103], v[112:115]
	v_mfma_f32_16x16x32_f16 v[32:35], v[36:39], v[108:111], v[32:35]
	v_mfma_f32_16x16x32_f16 v[36:39], v[40:43], v[96:99], 0
	v_mfma_f32_16x16x32_f16 v[40:43], v[40:43], v[104:107], 0
	v_mfma_f32_16x16x32_f16 v[36:39], v[44:47], v[100:103], v[36:39]
	v_mfma_f32_16x16x32_f16 v[40:43], v[44:47], v[108:111], v[40:43]
	v_mfma_f32_16x16x32_f16 v[44:47], v[48:51], v[96:99], 0
	v_mfma_f32_16x16x32_f16 v[48:51], v[48:51], v[104:107], 0
	v_mfma_f32_16x16x32_f16 v[44:47], v[52:55], v[100:103], v[44:47]
	v_mfma_f32_16x16x32_f16 v[48:51], v[52:55], v[108:111], v[48:51]
	v_mfma_f32_16x16x32_f16 v[52:55], v[56:59], v[96:99], 0
	v_mfma_f32_16x16x32_f16 v[56:59], v[56:59], v[104:107], 0
	v_mfma_f32_16x16x32_f16 v[52:55], v[60:63], v[100:103], v[52:55]
	v_mfma_f32_16x16x32_f16 v[56:59], v[60:63], v[108:111], v[56:59]
	s_setprio 0
	v_readfirstlane_b32 s16, v12
	v_lshl_add_u64 v[14:15], v[0:1], 0, s[92:93]
	s_mov_b32 m0, s16
	v_readfirstlane_b32 s16, v13
	s_barrier
	ds_read_b128 v[60:63], v131 offset:16384
	ds_read_b128 v[116:119], v131 offset:17408
	ds_read_b128 v[120:123], v131 offset:18432
	ds_read_b128 v[124:127], v131 offset:19456
	ds_read_b128 v[132:135], v131 offset:20480
	ds_read_b128 v[136:139], v131 offset:21504
	ds_read_b128 v[140:143], v131 offset:22528
	ds_read_b128 v[144:147], v131 offset:23552
	global_load_lds_dwordx4 v[14:15], off
	v_lshl_add_u64 v[14:15], v[0:1], 0, s[66:67]
	s_mov_b32 m0, s16
	s_nop 0
	global_load_lds_dwordx4 v[14:15], off
	s_barrier
;   #define STAGE(P,BASE,LD,br,kt) do{ const HALF* _u=(BASE)+(long)(br)*(((&(LD))==&lda)?lda_u:(LD))+(long)(kt)*G_BK; \
;     for(int _i=0;_i<2;++_i){ \
;       __builtin_amdgcn_global_load_lds((const unsigned*)(_u+(long)_i*(((&(LD))==&lda)?stepa:stepb)+((&(LD))==&lda?oa0:ob0)), \
;         (unsigned*)((char*)(P)+t5*16+_i*8192),16,0,0);}}while(0)
;   #define LDA(dst,b,h) for(int m=0;m<4;++m)for(int k=0;k<2;++k) \
;     dst[m][k]=*reinterpret_cast<const h8*>(la+(((b)*2+(h))*16384+m*2048+k*1024))
;   #define LDB(dst,b,h) for(int n=0;n<2;++n)for(int k=0;k<2;++k) \
;     dst[n][k]=*reinterpret_cast<const h8*>(lb+(((b)*2+(h))*16384+n*2048+k*1024))
;   #define MMA(ai,bj,At,Bt_) do{__builtin_amdgcn_s_setprio(1); \
;     for(int m=0;m<4;++m)for(int n=0;n<2;++n)for(int k=0;k<2;++k) \
;       acc[ai][bj][m][n]=__builtin_amdgcn_mfma_f32_16x16x32_f16(At[m][k],Bt_[n][k],acc[ai][bj][m][n],0,0,0); \
;     __builtin_amdgcn_s_setprio(0);}while(0)
;   #define WAIT_V(n) asm volatile("s_waitcnt vmcnt(" #n ")":::"memory")
;   #define WAIT_L(n) asm volatile("s_waitcnt lgkmcnt(" #n ")":::"memory")
;   #define BAR __builtin_amdgcn_s_barrier()
;   #define SCHED __builtin_amdgcn_sched_barrier(0)
;     ...
;     LDA(At,0,1); STAGE(SA(0,0),A,lda,0,t+2);
;     BAR; WAIT_L(0); MMA(1,0,At,B0); BAR; SCHED;
;     STAGE(SB(0,1),Bt,ldb,G_HALF,t+2);
;     WAIT_V(6); BAR; MMA(1,1,At,B1); BAR;
;     LDB(B0,1,0); SCHED; LDA(At,1,0); STAGE(SA(0,1),A,lda,G_HALF,t+2);
;     WAIT_L(8); BAR; WAIT_L(0); MMA(0,0,At,B0); BAR; SCHED;
;     LDB(B1,1,1); STAGE(SB(1,0),Bt,ldb,0,t+3);
;     BAR; WAIT_L(0); MMA(0,1,At,B1); BAR;
;     LDA(At,1,1); STAGE(SA(1,0),A,lda,0,t+3);
	s_waitcnt lgkmcnt(0)
	s_setprio 1
	s_waitcnt lgkmcnt(0)
	v_mfma_f32_16x16x32_f16 v[12:15], v[60:63], v[16:19], 0
	v_mfma_f32_16x16x32_f16 v[158:161], v[120:123], v[16:19], 0
	v_mfma_f32_16x16x32_f16 v[170:173], v[132:135], v[16:19], 0
	v_mfma_f32_16x16x32_f16 v[16:19], v[140:143], v[16:19], 0
	v_mfma_f32_16x16x32_f16 v[12:15], v[116:119], v[20:23], v[12:15]
	v_mfma_f32_16x16x32_f16 v[158:161], v[124:127], v[20:23], v[158:161]
	v_mfma_f32_16x16x32_f16 v[170:173], v[136:139], v[20:23], v[170:173]
	v_mfma_f32_16x16x32_f16 v[16:19], v[144:147], v[20:23], v[16:19]
	v_mfma_f32_16x16x32_f16 v[20:23], v[140:143], v[24:27], 0
	v_mfma_f32_16x16x32_f16 v[148:151], v[60:63], v[24:27], 0
	v_mfma_f32_16x16x32_f16 v[162:165], v[120:123], v[24:27], 0
	v_mfma_f32_16x16x32_f16 v[186:189], v[132:135], v[24:27], 0
	v_mfma_f32_16x16x32_f16 v[20:23], v[144:147], v[28:31], v[20:23]
	v_mfma_f32_16x16x32_f16 v[148:151], v[116:119], v[28:31], v[148:151]
	v_mfma_f32_16x16x32_f16 v[162:165], v[124:127], v[28:31], v[162:165]
	v_mfma_f32_16x16x32_f16 v[186:189], v[136:139], v[28:31], v[186:189]
	s_setprio 0
	s_barrier
	v_readfirstlane_b32 s16, v10
	v_lshl_add_u64 v[24:25], v[2:3], 0, s[92:93]
	s_mov_b32 m0, s16
	v_readfirstlane_b32 s16, v11
	global_load_lds_dwordx4 v[24:25], off
	v_lshl_add_u64 v[24:25], v[2:3], 0, s[66:67]
	s_mov_b32 m0, s16
	s_nop 0
	global_load_lds_dwordx4 v[24:25], off
	s_waitcnt vmcnt(6)
	s_barrier
	s_setprio 1
	v_mfma_f32_16x16x32_f16 v[24:27], v[60:63], v[96:99], 0
	v_mfma_f32_16x16x32_f16 v[28:31], v[60:63], v[104:107], 0
	v_mfma_f32_16x16x32_f16 v[24:27], v[116:119], v[100:103], v[24:27]
	v_mfma_f32_16x16x32_f16 v[28:31], v[116:119], v[108:111], v[28:31]
	v_mfma_f32_16x16x32_f16 v[60:63], v[120:123], v[96:99], 0
	v_mfma_f32_16x16x32_f16 v[116:119], v[120:123], v[104:107], 0
	v_mfma_f32_16x16x32_f16 v[120:123], v[132:135], v[96:99], 0
	v_mfma_f32_16x16x32_f16 v[96:99], v[140:143], v[96:99], 0
	v_mfma_f32_16x16x32_f16 v[60:63], v[124:127], v[100:103], v[60:63]
	v_mfma_f32_16x16x32_f16 v[116:119], v[124:127], v[108:111], v[116:119]
	v_mfma_f32_16x16x32_f16 v[120:123], v[136:139], v[100:103], v[120:123]
	v_mfma_f32_16x16x32_f16 v[124:127], v[132:135], v[104:107], 0
	v_mfma_f32_16x16x32_f16 v[96:99], v[144:147], v[100:103], v[96:99]
	v_mfma_f32_16x16x32_f16 v[100:103], v[140:143], v[104:107], 0
	v_mfma_f32_16x16x32_f16 v[124:127], v[136:139], v[108:111], v[124:127]
	v_mfma_f32_16x16x32_f16 v[100:103], v[144:147], v[108:111], v[100:103]
	s_setprio 0
	s_barrier
	ds_read_b128 v[104:107], v129 offset:32768
	ds_read_b128 v[108:111], v129 offset:33792
	ds_read_b128 v[132:135], v129 offset:34816
	ds_read_b128 v[136:139], v129 offset:35840
	v_readfirstlane_b32 s16, v8
	v_lshl_add_u64 v[10:11], v[6:7], 0, s[92:93]
	s_mov_b32 m0, s16
	v_readfirstlane_b32 s16, v9
	ds_read_b128 v[140:143], v131 offset:32768
	ds_read_b128 v[144:147], v131 offset:33792
	ds_read_b128 v[190:193], v131 offset:34816
	ds_read_b128 v[194:197], v131 offset:35840
	ds_read_b128 v[198:201], v131 offset:36864
	ds_read_b128 v[202:205], v131 offset:37888
	ds_read_b128 v[206:209], v131 offset:38912
	ds_read_b128 v[210:213], v131 offset:39936
	global_load_lds_dwordx4 v[10:11], off
	v_lshl_add_u64 v[6:7], v[6:7], 0, s[66:67]
	s_mov_b32 m0, s16
	s_nop 0
	global_load_lds_dwordx4 v[6:7], off
	s_waitcnt lgkmcnt(8)
	s_barrier
	s_waitcnt lgkmcnt(0)
	s_setprio 1
	s_waitcnt lgkmcnt(0)
	v_mfma_f32_16x16x32_f16 v[6:9], v[140:143], v[104:107], v[64:67]
	v_mfma_f32_16x16x32_f16 v[64:67], v[140:143], v[132:135], v[68:71]
	v_mfma_f32_16x16x32_f16 v[68:71], v[190:193], v[104:107], v[72:75]
	v_mfma_f32_16x16x32_f16 v[72:75], v[190:193], v[132:135], v[76:79]
	v_mfma_f32_16x16x32_f16 v[76:79], v[198:201], v[104:107], v[80:83]
	v_mfma_f32_16x16x32_f16 v[80:83], v[198:201], v[132:135], v[84:87]
	v_mfma_f32_16x16x32_f16 v[84:87], v[206:209], v[104:107], v[88:91]
	v_mfma_f32_16x16x32_f16 v[88:91], v[206:209], v[132:135], v[92:95]
	v_mfma_f32_16x16x32_f16 v[6:9], v[144:147], v[108:111], v[6:9]
	v_mfma_f32_16x16x32_f16 v[64:67], v[144:147], v[136:139], v[64:67]
	v_mfma_f32_16x16x32_f16 v[68:71], v[194:197], v[108:111], v[68:71]
	v_mfma_f32_16x16x32_f16 v[72:75], v[194:197], v[136:139], v[72:75]
	v_mfma_f32_16x16x32_f16 v[76:79], v[202:205], v[108:111], v[76:79]
	v_mfma_f32_16x16x32_f16 v[80:83], v[202:205], v[136:139], v[80:83]
	v_mfma_f32_16x16x32_f16 v[84:87], v[210:213], v[108:111], v[84:87]
	v_mfma_f32_16x16x32_f16 v[88:91], v[210:213], v[136:139], v[88:91]
	s_setprio 0
	s_barrier
	s_mov_b32 m0, s15
	v_lshl_add_u64 v[10:11], v[4:5], 0, s[42:43]
	ds_read_b128 v[92:95], v129 offset:49152
	ds_read_b128 v[214:217], v129 offset:50176
	ds_read_b128 v[218:221], v129 offset:51200
	ds_read_b128 v[222:225], v129 offset:52224
	global_load_lds_dwordx4 v[10:11], off
	v_lshl_add_u64 v[4:5], v[4:5], 0, s[96:97]
	s_mov_b32 m0, s14
	s_nop 0
	global_load_lds_dwordx4 v[4:5], off
	s_barrier
	s_waitcnt lgkmcnt(0)
	s_setprio 1
	s_waitcnt lgkmcnt(0)
	v_mfma_f32_16x16x32_f16 v[112:115], v[140:143], v[92:95], v[112:115]
	v_mfma_f32_16x16x32_f16 v[32:35], v[140:143], v[218:221], v[32:35]
	v_mfma_f32_16x16x32_f16 v[36:39], v[190:193], v[92:95], v[36:39]
	v_mfma_f32_16x16x32_f16 v[40:43], v[190:193], v[218:221], v[40:43]
	v_mfma_f32_16x16x32_f16 v[44:47], v[198:201], v[92:95], v[44:47]
	v_mfma_f32_16x16x32_f16 v[48:51], v[198:201], v[218:221], v[48:51]
	v_mfma_f32_16x16x32_f16 v[52:55], v[206:209], v[92:95], v[52:55]
	v_mfma_f32_16x16x32_f16 v[56:59], v[206:209], v[218:221], v[56:59]
	v_mfma_f32_16x16x32_f16 v[112:115], v[144:147], v[214:217], v[112:115]
	v_mfma_f32_16x16x32_f16 v[32:35], v[144:147], v[222:225], v[32:35]
	v_mfma_f32_16x16x32_f16 v[36:39], v[194:197], v[214:217], v[36:39]
	v_mfma_f32_16x16x32_f16 v[40:43], v[194:197], v[222:225], v[40:43]
	v_mfma_f32_16x16x32_f16 v[44:47], v[202:205], v[214:217], v[44:47]
	v_mfma_f32_16x16x32_f16 v[48:51], v[202:205], v[222:225], v[48:51]
	v_mfma_f32_16x16x32_f16 v[52:55], v[210:213], v[214:217], v[52:55]
	v_mfma_f32_16x16x32_f16 v[56:59], v[210:213], v[222:225], v[56:59]
	s_setprio 0
	s_mov_b32 m0, s12
	v_lshl_add_u64 v[4:5], v[0:1], 0, s[42:43]
	s_barrier
;   #define STAGE(P,BASE,LD,br,kt) do{ const HALF* _u=(BASE)+(long)(br)*(((&(LD))==&lda)?lda_u:(LD))+(long)(kt)*G_BK; \
;     for(int _i=0;_i<2;++_i){ \
;       __builtin_amdgcn_global_load_lds((const unsigned*)(_u+(long)_i*(((&(LD))==&lda)?stepa:stepb)+((&(LD))==&lda?oa0:ob0)), \
;         (unsigned*)((char*)(P)+t5*16+_i*8192),16,0,0);}}while(0)
;   #define LDA(dst,b,h) for(int m=0;m<4;++m)for(int k=0;k<2;++k) \
;     dst[m][k]=*reinterpret_cast<const h8*>(la+(((b)*2+(h))*16384+m*2048+k*1024))
;   #define LDB(dst,b,h) for(int n=0;n<2;++n)for(int k=0;k<2;++k) \
;     dst[n][k]=*reinterpret_cast<const h8*>(lb+(((b)*2+(h))*16384+n*2048+k*1024))
;   #define MMA(ai,bj,At,Bt_) do{__builtin_amdgcn_s_setprio(1); \
;     for(int m=0;m<4;++m)for(int n=0;n<2;++n)for(int k=0;k<2;++k) \
;       acc[ai][bj][m][n]=__builtin_amdgcn_mfma_f32_16x16x32_f16(At[m][k],Bt_[n][k],acc[ai][bj][m][n],0,0,0); \
;     __builtin_amdgcn_s_setprio(0);}while(0)
;   #define WAIT_V(n) asm volatile("s_waitcnt vmcnt(" #n ")":::"memory")
;   #define WAIT_L(n) asm volatile("s_waitcnt lgkmcnt(" #n ")":::"memory")
;   #define BAR __builtin_amdgcn_s_barrier()
;   #define SCHED __builtin_amdgcn_sched_barrier(0)
;     ...
;     LDA(At,1,1); STAGE(SA(1,0),A,lda,0,t+3);
;     BAR; WAIT_L(0); MMA(1,0,At,B0); BAR; SCHED;
;     STAGE(SB(1,1),Bt,ldb,G_HALF,t+3);
;     WAIT_V(6); BAR; MMA(1,1,At,B1); BAR;
;   }
;   { LDB(B0,0,0); LDA(At,0,0); STAGE(SA(1,1),A,lda,G_HALF,nt-1);
;     BAR; WAIT_L(0); MMA(0,0,At,B0); BAR;
;     LDB(B1,0,1); BAR; WAIT_L(0); MMA(0,1,At,B1); BAR;
	ds_read_b128 v[140:143], v131 offset:49152
	ds_read_b128 v[144:147], v131 offset:50176
	ds_read_b128 v[190:193], v131 offset:51200
	ds_read_b128 v[194:197], v131 offset:52224
	ds_read_b128 v[198:201], v131 offset:53248
	ds_read_b128 v[202:205], v131 offset:54272
	ds_read_b128 v[206:209], v131 offset:55296
	ds_read_b128 v[210:213], v131 offset:56320
	global_load_lds_dwordx4 v[4:5], off
	v_lshl_add_u64 v[4:5], v[0:1], 0, s[96:97]
	s_mov_b32 m0, s7
	s_nop 0
	global_load_lds_dwordx4 v[4:5], off
	s_barrier
	s_waitcnt lgkmcnt(0)
	s_setprio 1
	s_waitcnt lgkmcnt(0)
	v_mfma_f32_16x16x32_f16 v[10:13], v[140:143], v[104:107], v[12:15]
	v_mfma_f32_16x16x32_f16 v[14:17], v[206:209], v[104:107], v[16:19]
	v_mfma_f32_16x16x32_f16 v[18:21], v[206:209], v[132:135], v[20:23]
	v_mfma_f32_16x16x32_f16 v[10:13], v[144:147], v[108:111], v[10:13]
	v_mfma_f32_16x16x32_f16 v[148:151], v[140:143], v[132:135], v[148:151]
	v_mfma_f32_16x16x32_f16 v[158:161], v[190:193], v[104:107], v[158:161]
	v_mfma_f32_16x16x32_f16 v[162:165], v[190:193], v[132:135], v[162:165]
	v_mfma_f32_16x16x32_f16 v[170:173], v[198:201], v[104:107], v[170:173]
	v_mfma_f32_16x16x32_f16 v[186:189], v[198:201], v[132:135], v[186:189]
	v_mfma_f32_16x16x32_f16 v[14:17], v[210:213], v[108:111], v[14:17]
	v_mfma_f32_16x16x32_f16 v[18:21], v[210:213], v[136:139], v[18:21]
	v_mfma_f32_16x16x32_f16 v[148:151], v[144:147], v[136:139], v[148:151]
	v_mfma_f32_16x16x32_f16 v[158:161], v[194:197], v[108:111], v[158:161]
	v_mfma_f32_16x16x32_f16 v[162:165], v[194:197], v[136:139], v[162:165]
	v_mfma_f32_16x16x32_f16 v[170:173], v[202:205], v[108:111], v[170:173]
	v_mfma_f32_16x16x32_f16 v[186:189], v[202:205], v[136:139], v[186:189]
	s_setprio 0
	s_barrier
	s_mov_b32 m0, s1
	v_lshl_add_u64 v[4:5], v[2:3], 0, s[42:43]
	global_load_lds_dwordx4 v[4:5], off
	v_lshl_add_u64 v[2:3], v[2:3], 0, s[96:97]
	s_mov_b32 m0, s0
	s_nop 0
	global_load_lds_dwordx4 v[2:3], off
	s_waitcnt vmcnt(6)
	s_barrier
	s_setprio 1
	v_mfma_f32_16x16x32_f16 v[2:5], v[140:143], v[92:95], v[24:27]
	v_mfma_f32_16x16x32_f16 v[22:25], v[140:143], v[218:221], v[28:31]
	v_mfma_f32_16x16x32_f16 v[26:29], v[190:193], v[92:95], v[60:63]
	v_mfma_f32_16x16x32_f16 v[60:63], v[190:193], v[218:221], v[116:119]
	v_mfma_f32_16x16x32_f16 v[104:107], v[198:201], v[92:95], v[120:123]
	v_mfma_f32_16x16x32_f16 v[108:111], v[198:201], v[218:221], v[124:127]
	v_mfma_f32_16x16x32_f16 v[92:95], v[206:209], v[92:95], v[96:99]
	v_mfma_f32_16x16x32_f16 v[96:99], v[206:209], v[218:221], v[100:103]
	v_mfma_f32_16x16x32_f16 v[2:5], v[144:147], v[214:217], v[2:5]
	v_mfma_f32_16x16x32_f16 v[22:25], v[144:147], v[222:225], v[22:25]
	v_mfma_f32_16x16x32_f16 v[26:29], v[194:197], v[214:217], v[26:29]
	v_mfma_f32_16x16x32_f16 v[60:63], v[194:197], v[222:225], v[60:63]
	v_mfma_f32_16x16x32_f16 v[104:107], v[202:205], v[214:217], v[104:107]
	v_mfma_f32_16x16x32_f16 v[108:111], v[202:205], v[222:225], v[108:111]
	v_mfma_f32_16x16x32_f16 v[92:95], v[210:213], v[214:217], v[92:95]
	v_mfma_f32_16x16x32_f16 v[96:99], v[210:213], v[222:225], v[96:99]
	s_setprio 0
	s_mov_b64 s[0:1], 0x40180
	s_mov_b32 m0, s13
	v_lshl_add_u64 v[30:31], v[0:1], 0, s[0:1]
	s_mov_b64 s[0:1], 0x60180
	s_barrier
	ds_read_b128 v[100:103], v129
	ds_read_b128 v[116:119], v129 offset:1024
	ds_read_b128 v[120:123], v129 offset:2048
	ds_read_b128 v[124:127], v129 offset:3072
	ds_read_b128 v[132:135], v131
	ds_read_b128 v[136:139], v131 offset:1024
	ds_read_b128 v[140:143], v131 offset:2048
	ds_read_b128 v[144:147], v131 offset:3072
	ds_read_b128 v[190:193], v131 offset:4096
	ds_read_b128 v[194:197], v131 offset:5120
	ds_read_b128 v[198:201], v131 offset:6144
	ds_read_b128 v[202:205], v131 offset:7168
	global_load_lds_dwordx4 v[30:31], off
	v_lshl_add_u64 v[0:1], v[0:1], 0, s[0:1]
	s_mov_b32 m0, s11
	s_nop 0
	global_load_lds_dwordx4 v[0:1], off
	s_barrier
	s_waitcnt lgkmcnt(0)
	s_setprio 1
	s_waitcnt lgkmcnt(0)
	v_mfma_f32_16x16x32_f16 v[6:9], v[132:135], v[100:103], v[6:9]
	v_mfma_f32_16x16x32_f16 v[64:67], v[132:135], v[120:123], v[64:67]
	v_mfma_f32_16x16x32_f16 v[68:71], v[140:143], v[100:103], v[68:71]
	v_mfma_f32_16x16x32_f16 v[72:75], v[140:143], v[120:123], v[72:75]
	v_mfma_f32_16x16x32_f16 v[76:79], v[190:193], v[100:103], v[76:79]
	v_mfma_f32_16x16x32_f16 v[80:83], v[190:193], v[120:123], v[80:83]
	v_mfma_f32_16x16x32_f16 v[84:87], v[198:201], v[100:103], v[84:87]
	v_mfma_f32_16x16x32_f16 v[88:91], v[198:201], v[120:123], v[88:91]
	v_mfma_f32_16x16x32_f16 v[6:9], v[136:139], v[116:119], v[6:9]
	v_mfma_f32_16x16x32_f16 v[64:67], v[136:139], v[124:127], v[64:67]
	v_mfma_f32_16x16x32_f16 v[68:71], v[144:147], v[116:119], v[68:71]
	v_mfma_f32_16x16x32_f16 v[72:75], v[144:147], v[124:127], v[72:75]
	v_mfma_f32_16x16x32_f16 v[76:79], v[194:197], v[116:119], v[76:79]
	v_mfma_f32_16x16x32_f16 v[80:83], v[194:197], v[124:127], v[80:83]
	v_mfma_f32_16x16x32_f16 v[84:87], v[202:205], v[116:119], v[84:87]
	v_mfma_f32_16x16x32_f16 v[88:91], v[202:205], v[124:127], v[88:91]
	s_setprio 0
	s_barrier
	ds_read_b128 v[206:209], v129 offset:16384
	ds_read_b128 v[210:213], v129 offset:17408
	ds_read_b128 v[214:217], v129 offset:18432
	ds_read_b128 v[218:221], v129 offset:19456
	s_barrier
;   #define LDA(dst,b,h) for(int m=0;m<4;++m)for(int k=0;k<2;++k) \
;     dst[m][k]=*reinterpret_cast<const h8*>(la+(((b)*2+(h))*16384+m*2048+k*1024))
;   #define LDB(dst,b,h) for(int n=0;n<2;++n)for(int k=0;k<2;++k) \
;     dst[n][k]=*reinterpret_cast<const h8*>(lb+(((b)*2+(h))*16384+n*2048+k*1024))
;   #define MMA(ai,bj,At,Bt_) do{__builtin_amdgcn_s_setprio(1); \
;     for(int m=0;m<4;++m)for(int n=0;n<2;++n)for(int k=0;k<2;++k) \
;       acc[ai][bj][m][n]=__builtin_amdgcn_mfma_f32_16x16x32_f16(At[m][k],Bt_[n][k],acc[ai][bj][m][n],0,0,0); \
;     __builtin_amdgcn_s_setprio(0);}while(0)
;   #define WAIT_V(n) asm volatile("s_waitcnt vmcnt(" #n ")":::"memory")
;   #define WAIT_L(n) asm volatile("s_waitcnt lgkmcnt(" #n ")":::"memory")
;   #define BAR __builtin_amdgcn_s_barrier()
;     ...
;     LDB(B1,0,1); BAR; WAIT_L(0); MMA(0,1,At,B1); BAR;
;     LDA(At,0,1); WAIT_V(4); BAR; WAIT_L(0); MMA(1,0,At,B0); MMA(1,1,At,B1); BAR; }
;   { LDB(B0,1,0); LDA(At,1,0); WAIT_V(2); BAR; WAIT_L(0); MMA(0,0,At,B0); BAR;
	s_waitcnt lgkmcnt(0)
	s_setprio 1
	s_waitcnt lgkmcnt(0)
	v_mfma_f32_16x16x32_f16 v[30:33], v[132:135], v[214:217], v[32:35]
	v_mfma_f32_16x16x32_f16 v[34:37], v[140:143], v[206:209], v[36:39]
	v_mfma_f32_16x16x32_f16 v[38:41], v[140:143], v[214:217], v[40:43]
	v_mfma_f32_16x16x32_f16 v[42:45], v[190:193], v[206:209], v[44:47]
	v_mfma_f32_16x16x32_f16 v[46:49], v[190:193], v[214:217], v[48:51]
	v_mfma_f32_16x16x32_f16 v[50:53], v[198:201], v[206:209], v[52:55]
	v_mfma_f32_16x16x32_f16 v[54:57], v[198:201], v[214:217], v[56:59]
	v_mfma_f32_16x16x32_f16 v[112:115], v[132:135], v[206:209], v[112:115]
	v_mfma_f32_16x16x32_f16 v[30:33], v[136:139], v[218:221], v[30:33]
	v_mfma_f32_16x16x32_f16 v[34:37], v[144:147], v[210:213], v[34:37]
	v_mfma_f32_16x16x32_f16 v[38:41], v[144:147], v[218:221], v[38:41]
	v_mfma_f32_16x16x32_f16 v[42:45], v[194:197], v[210:213], v[42:45]
	v_mfma_f32_16x16x32_f16 v[46:49], v[194:197], v[218:221], v[46:49]
	v_mfma_f32_16x16x32_f16 v[50:53], v[202:205], v[210:213], v[50:53]
	v_mfma_f32_16x16x32_f16 v[54:57], v[202:205], v[218:221], v[54:57]
	v_mfma_f32_16x16x32_f16 v[222:225], v[136:139], v[210:213], v[112:115]
	s_setprio 0
	s_barrier
	s_nop 0
	ds_read_b128 v[112:115], v131 offset:16384
	ds_read_b128 v[132:135], v131 offset:17408
	ds_read_b128 v[136:139], v131 offset:18432
	ds_read_b128 v[140:143], v131 offset:19456
	ds_read_b128 v[144:147], v131 offset:20480
	ds_read_b128 v[190:193], v131 offset:21504
	ds_read_b128 v[194:197], v131 offset:22528
	ds_read_b128 v[198:201], v131 offset:23552
	s_waitcnt vmcnt(4)
	s_barrier
	s_waitcnt lgkmcnt(0)
	s_setprio 1
	s_waitcnt lgkmcnt(0)
	v_mfma_f32_16x16x32_f16 v[10:13], v[112:115], v[100:103], v[10:13]
	v_mfma_f32_16x16x32_f16 v[14:17], v[194:197], v[100:103], v[14:17]
	v_mfma_f32_16x16x32_f16 v[18:21], v[194:197], v[120:123], v[18:21]
	v_mfma_f32_16x16x32_f16 v[10:13], v[132:135], v[116:119], v[10:13]
	v_mfma_f32_16x16x32_f16 v[148:151], v[112:115], v[120:123], v[148:151]
	v_mfma_f32_16x16x32_f16 v[158:161], v[136:139], v[100:103], v[158:161]
	v_mfma_f32_16x16x32_f16 v[162:165], v[136:139], v[120:123], v[162:165]
	v_mfma_f32_16x16x32_f16 v[170:173], v[144:147], v[100:103], v[170:173]
	v_mfma_f32_16x16x32_f16 v[186:189], v[144:147], v[120:123], v[186:189]
	v_mfma_f32_16x16x32_f16 v[14:17], v[198:201], v[116:119], v[14:17]
	v_mfma_f32_16x16x32_f16 v[18:21], v[198:201], v[124:127], v[18:21]
	v_mfma_f32_16x16x32_f16 v[148:151], v[132:135], v[124:127], v[148:151]
	v_mfma_f32_16x16x32_f16 v[158:161], v[140:143], v[116:119], v[158:161]
	v_mfma_f32_16x16x32_f16 v[162:165], v[140:143], v[124:127], v[162:165]
	v_mfma_f32_16x16x32_f16 v[170:173], v[190:193], v[116:119], v[170:173]
	v_mfma_f32_16x16x32_f16 v[186:189], v[190:193], v[124:127], v[186:189]
	s_setprio 0
	s_setprio 1
	v_mfma_f32_16x16x32_f16 v[0:3], v[112:115], v[206:209], v[2:5]
	v_mfma_f32_16x16x32_f16 v[22:25], v[112:115], v[214:217], v[22:25]
	v_mfma_f32_16x16x32_f16 v[26:29], v[136:139], v[206:209], v[26:29]
	v_mfma_f32_16x16x32_f16 v[0:3], v[132:135], v[210:213], v[0:3]
	v_mfma_f32_16x16x32_f16 v[22:25], v[132:135], v[218:221], v[22:25]
	v_mfma_f32_16x16x32_f16 v[132:135], v[140:143], v[210:213], v[26:29]
	v_mfma_f32_16x16x32_f16 v[26:29], v[136:139], v[214:217], v[60:63]
	v_mfma_f32_16x16x32_f16 v[136:139], v[140:143], v[218:221], v[26:29]
	v_mfma_f32_16x16x32_f16 v[26:29], v[144:147], v[206:209], v[104:107]
	v_mfma_f32_16x16x32_f16 v[140:143], v[190:193], v[210:213], v[26:29]
	v_mfma_f32_16x16x32_f16 v[26:29], v[144:147], v[214:217], v[108:111]
	v_mfma_f32_16x16x32_f16 v[144:147], v[190:193], v[218:221], v[26:29]
	v_mfma_f32_16x16x32_f16 v[26:29], v[194:197], v[206:209], v[92:95]
	v_mfma_f32_16x16x32_f16 v[190:193], v[198:201], v[210:213], v[26:29]
	v_mfma_f32_16x16x32_f16 v[26:29], v[194:197], v[214:217], v[96:99]
	v_mfma_f32_16x16x32_f16 v[194:197], v[198:201], v[218:221], v[26:29]
	s_setprio 0
	s_barrier
	s_nop 4
	ds_read_b128 v[26:29], v129 offset:32768
	ds_read_b128 v[198:201], v129 offset:33792
	ds_read_b128 v[202:205], v129 offset:34816
	ds_read_b128 v[206:209], v129 offset:35840
	ds_read_b128 v[58:61], v131 offset:32768
	ds_read_b128 v[210:213], v131 offset:33792
	ds_read_b128 v[214:217], v131 offset:34816
	ds_read_b128 v[218:221], v131 offset:35840
	ds_read_b128 v[226:229], v131 offset:36864
	ds_read_b128 v[230:233], v131 offset:37888
	ds_read_b128 v[234:237], v131 offset:38912
	ds_read_b128 v[238:241], v131 offset:39936
	s_waitcnt vmcnt(2)
	s_barrier
;   #define LDA(dst,b,h) for(int m=0;m<4;++m)for(int k=0;k<2;++k) \
;     dst[m][k]=*reinterpret_cast<const h8*>(la+(((b)*2+(h))*16384+m*2048+k*1024))
;   #define LDB(dst,b,h) for(int n=0;n<2;++n)for(int k=0;k<2;++k) \
;     dst[n][k]=*reinterpret_cast<const h8*>(lb+(((b)*2+(h))*16384+n*2048+k*1024))
;   #define MMA(ai,bj,At,Bt_) do{__builtin_amdgcn_s_setprio(1); \
;     for(int m=0;m<4;++m)for(int n=0;n<2;++n)for(int k=0;k<2;++k) \
;       acc[ai][bj][m][n]=__builtin_amdgcn_mfma_f32_16x16x32_f16(At[m][k],Bt_[n][k],acc[ai][bj][m][n],0,0,0); \
;     __builtin_amdgcn_s_setprio(0);}while(0)
;   #define WAIT_V(n) asm volatile("s_waitcnt vmcnt(" #n ")":::"memory")
;   #define WAIT_L(n) asm volatile("s_waitcnt lgkmcnt(" #n ")":::"memory")
;   #define BAR __builtin_amdgcn_s_barrier()
;     ...
;   { LDB(B0,1,0); LDA(At,1,0); WAIT_V(2); BAR; WAIT_L(0); MMA(0,0,At,B0); BAR;
;     LDB(B1,1,1); WAIT_V(0); BAR; WAIT_L(0); MMA(0,1,At,B1); BAR;
;     LDA(At,1,1); BAR; WAIT_L(0); MMA(1,0,At,B0); MMA(1,1,At,B1); BAR; }
;   if(wr==0)BAR;
	s_waitcnt lgkmcnt(0)
	s_setprio 1
	s_waitcnt lgkmcnt(0)
	v_mfma_f32_16x16x32_f16 v[4:7], v[58:61], v[26:29], v[6:9]
	v_mfma_f32_16x16x32_f16 v[124:127], v[210:213], v[198:201], v[4:7]
	v_mfma_f32_16x16x32_f16 v[4:7], v[58:61], v[202:205], v[64:67]
	v_mfma_f32_16x16x32_f16 v[120:123], v[210:213], v[206:209], v[4:7]
	v_mfma_f32_16x16x32_f16 v[4:7], v[214:217], v[26:29], v[68:71]
	v_mfma_f32_16x16x32_f16 v[116:119], v[218:221], v[198:201], v[4:7]
	v_mfma_f32_16x16x32_f16 v[4:7], v[214:217], v[202:205], v[72:75]
	v_mfma_f32_16x16x32_f16 v[112:115], v[218:221], v[206:209], v[4:7]
	v_mfma_f32_16x16x32_f16 v[4:7], v[226:229], v[26:29], v[76:79]
	v_mfma_f32_16x16x32_f16 v[108:111], v[230:233], v[198:201], v[4:7]
	v_mfma_f32_16x16x32_f16 v[4:7], v[226:229], v[202:205], v[80:83]
	v_mfma_f32_16x16x32_f16 v[104:107], v[230:233], v[206:209], v[4:7]
	v_mfma_f32_16x16x32_f16 v[4:7], v[234:237], v[26:29], v[84:87]
	v_mfma_f32_16x16x32_f16 v[100:103], v[238:241], v[198:201], v[4:7]
	v_mfma_f32_16x16x32_f16 v[4:7], v[234:237], v[202:205], v[88:91]
	v_mfma_f32_16x16x32_f16 v[96:99], v[238:241], v[206:209], v[4:7]
	s_setprio 0
	s_barrier
	s_nop 4
	ds_read_b128 v[4:7], v129 offset:49152
	ds_read_b128 v[242:245], v129 offset:50176
	ds_read_b128 v[246:249], v129 offset:51200
	ds_read_b128 v[250:253], v129 offset:52224
	s_waitcnt vmcnt(0)
	s_barrier
	s_waitcnt lgkmcnt(0)
	s_setprio 1
	s_waitcnt lgkmcnt(0)
	v_mfma_f32_16x16x32_f16 v[30:33], v[58:61], v[246:249], v[30:33]
	v_mfma_f32_16x16x32_f16 v[88:91], v[210:213], v[250:253], v[30:33]
	v_mfma_f32_16x16x32_f16 v[30:33], v[214:217], v[4:7], v[34:37]
	v_mfma_f32_16x16x32_f16 v[84:87], v[218:221], v[242:245], v[30:33]
	v_mfma_f32_16x16x32_f16 v[30:33], v[214:217], v[246:249], v[38:41]
	v_mfma_f32_16x16x32_f16 v[80:83], v[218:221], v[250:253], v[30:33]
	v_mfma_f32_16x16x32_f16 v[30:33], v[226:229], v[4:7], v[42:45]
	v_mfma_f32_16x16x32_f16 v[76:79], v[230:233], v[242:245], v[30:33]
	v_mfma_f32_16x16x32_f16 v[30:33], v[226:229], v[246:249], v[46:49]
	v_mfma_f32_16x16x32_f16 v[72:75], v[230:233], v[250:253], v[30:33]
	v_mfma_f32_16x16x32_f16 v[30:33], v[234:237], v[4:7], v[50:53]
	v_mfma_f32_16x16x32_f16 v[62:65], v[58:61], v[4:7], v[222:225]
	v_mfma_f32_16x16x32_f16 v[68:71], v[238:241], v[242:245], v[30:33]
	v_mfma_f32_16x16x32_f16 v[30:33], v[234:237], v[246:249], v[54:57]
	v_mfma_f32_16x16x32_f16 v[92:95], v[210:213], v[242:245], v[62:65]
	v_mfma_f32_16x16x32_f16 v[64:67], v[238:241], v[250:253], v[30:33]
	s_setprio 0
	s_barrier
	ds_read_b128 v[210:213], v131 offset:49152
	ds_read_b128 v[214:217], v131 offset:50176
	ds_read_b128 v[218:221], v131 offset:51200
	ds_read_b128 v[222:225], v131 offset:52224
	ds_read_b128 v[226:229], v131 offset:53248
	ds_read_b128 v[230:233], v131 offset:54272
	ds_read_b128 v[234:237], v131 offset:55296
	ds_read_b128 v[238:241], v131 offset:56320
	s_barrier
	s_waitcnt lgkmcnt(0)
	s_setprio 1
	s_waitcnt lgkmcnt(0)
	v_mfma_f32_16x16x32_f16 v[8:11], v[210:213], v[26:29], v[10:13]
	v_mfma_f32_16x16x32_f16 v[60:63], v[214:217], v[198:201], v[8:11]
	v_mfma_f32_16x16x32_f16 v[8:11], v[210:213], v[202:205], v[148:151]
	v_mfma_f32_16x16x32_f16 v[56:59], v[214:217], v[206:209], v[8:11]
	v_mfma_f32_16x16x32_f16 v[8:11], v[218:221], v[26:29], v[158:161]
	v_mfma_f32_16x16x32_f16 v[52:55], v[222:225], v[198:201], v[8:11]
	v_mfma_f32_16x16x32_f16 v[8:11], v[218:221], v[202:205], v[162:165]
	v_mfma_f32_16x16x32_f16 v[48:51], v[222:225], v[206:209], v[8:11]
	v_mfma_f32_16x16x32_f16 v[8:11], v[226:229], v[26:29], v[170:173]
	v_mfma_f32_16x16x32_f16 v[44:47], v[230:233], v[198:201], v[8:11]
	v_mfma_f32_16x16x32_f16 v[8:11], v[226:229], v[202:205], v[186:189]
	v_mfma_f32_16x16x32_f16 v[40:43], v[230:233], v[206:209], v[8:11]
	v_mfma_f32_16x16x32_f16 v[8:11], v[234:237], v[26:29], v[14:17]
	v_mfma_f32_16x16x32_f16 v[36:39], v[238:241], v[198:201], v[8:11]
	v_mfma_f32_16x16x32_f16 v[8:11], v[234:237], v[202:205], v[18:21]
	v_mfma_f32_16x16x32_f16 v[32:35], v[238:241], v[206:209], v[8:11]
	s_setprio 0
	s_setprio 1
	v_mfma_f32_16x16x32_f16 v[0:3], v[210:213], v[4:7], v[0:3]
	v_mfma_f32_16x16x32_f16 v[28:31], v[214:217], v[242:245], v[0:3]
	v_mfma_f32_16x16x32_f16 v[0:3], v[210:213], v[246:249], v[22:25]
	v_mfma_f32_16x16x32_f16 v[24:27], v[214:217], v[250:253], v[0:3]
	v_mfma_f32_16x16x32_f16 v[0:3], v[218:221], v[4:7], v[132:135]
	v_mfma_f32_16x16x32_f16 v[20:23], v[222:225], v[242:245], v[0:3]
	v_mfma_f32_16x16x32_f16 v[0:3], v[218:221], v[246:249], v[136:139]
	v_mfma_f32_16x16x32_f16 v[16:19], v[222:225], v[250:253], v[0:3]
	v_mfma_f32_16x16x32_f16 v[0:3], v[226:229], v[4:7], v[140:143]
	v_mfma_f32_16x16x32_f16 v[12:15], v[230:233], v[242:245], v[0:3]
	v_mfma_f32_16x16x32_f16 v[0:3], v[226:229], v[246:249], v[144:147]
	v_mfma_f32_16x16x32_f16 v[8:11], v[230:233], v[250:253], v[0:3]
	v_mfma_f32_16x16x32_f16 v[0:3], v[234:237], v[4:7], v[190:193]
	v_mfma_f32_16x16x32_f16 v[4:7], v[238:241], v[242:245], v[0:3]
	v_mfma_f32_16x16x32_f16 v[0:3], v[234:237], v[246:249], v[194:197]
	v_mfma_f32_16x16x32_f16 v[0:3], v[238:241], v[250:253], v[0:3]
	s_setprio 0
	s_movk_i32 s0, 0x100
	v_cmp_gt_u32_e32 vcc, s0, v128
	s_barrier
	s_and_saveexec_b64 s[0:1], vcc
	s_cbranch_execz .LBB0_382
	s_barrier

;   #define STAGE(P,BASE,LD,br,kt) do{ const HALF* _u=(BASE)+(long)(br)*(((&(LD))==&lda)?lda_u:(LD))+(long)(kt)*G_BK; \
;     for(int _i=0;_i<2;++_i){ \
;       __builtin_amdgcn_global_load_lds((const unsigned*)(_u+(long)_i*(((&(LD))==&lda)?stepa:stepb)+((&(LD))==&lda?oa0:ob0)), \
;         (unsigned*)((char*)(P)+t5*16+_i*8192),16,0,0);}}while(0)
;   #define LDA(dst,b,h) for(int m=0;m<4;++m)for(int k=0;k<2;++k) \
;     dst[m][k]=*reinterpret_cast<const h8*>(la+(((b)*2+(h))*16384+m*2048+k*1024))
;   #define LDB(dst,b,h) for(int n=0;n<2;++n)for(int k=0;k<2;++k) \
;     dst[n][k]=*reinterpret_cast<const h8*>(lb+(((b)*2+(h))*16384+n*2048+k*1024))
;   #define MMA(ai,bj,At,Bt_) do{__builtin_amdgcn_s_setprio(1); \
;     for(int m=0;m<4;++m)for(int n=0;n<2;++n)for(int k=0;k<2;++k) \
;       acc[ai][bj][m][n]=__builtin_amdgcn_mfma_f32_16x16x32_f16(At[m][k],Bt_[n][k],acc[ai][bj][m][n],0,0,0); \
;     __builtin_amdgcn_s_setprio(0);}while(0)
;   #define WAIT_V(n) asm volatile("s_waitcnt vmcnt(" #n ")":::"memory")
;   #define WAIT_L(n) asm volatile("s_waitcnt lgkmcnt(" #n ")":::"memory")
;   #define BAR __builtin_amdgcn_s_barrier()
;   #define SCHED __builtin_amdgcn_sched_barrier(0)
;     ...
;   {int _b=t5*16;int _r,_c;g_stage_rc(_b,_r,_c);
;     oa0=n2 ? (unsigned)((n2*(_r&63)+(_r>>6))*1024+_c) : (unsigned)(_r*lda+_c); ob0=(unsigned)(_r*ldb+_c);}
;   STAGE(SB(0,0),Bt,ldb,0,0); STAGE(SA(0,0),A,lda,0,0);
;   STAGE(SB(0,1),Bt,ldb,G_HALF,0); STAGE(SA(0,1),A,lda,G_HALF,0);
;   if(wr==1)BAR;
;   WAIT_V(4); BAR;
;   STAGE(SB(1,0),Bt,ldb,0,1); STAGE(SA(1,0),A,lda,0,1); STAGE(SB(1,1),Bt,ldb,G_HALF,1);
;   WAIT_V(6); BAR;
;   for(int t=0;t<nt-2;t+=2){
;     LDB(B0,0,0); SCHED; LDA(At,0,0); STAGE(SA(1,1),A,lda,G_HALF,t+1);
;     WAIT_L(8); BAR; WAIT_L(0); MMA(0,0,At,B0); BAR; SCHED;
;     LDB(B1,0,1); STAGE(SB(0,0),Bt,ldb,0,t+2);
;     BAR; WAIT_L(0); MMA(0,1,At,B1); BAR;
;     LDA(At,0,1); STAGE(SA(0,0),A,lda,0,t+2);
.LBB0_394:
	s_or_b64 exec, exec, s[2:3]
	v_lshlrev_b32_e32 v19, 6, v129
	v_lshlrev_b32_e32 v21, 2, v129
	v_and_b32_e32 v18, 48, v129
	v_and_b32_e32 v20, 0x3c0, v19
	v_and_b32_e32 v21, 32, v21
	v_bitop3_b32 v20, v20, v21, v18 bitop3:0x36
	v_lshlrev_b32_e32 v21, 13, v17
	v_add_u32_e32 v17, s29, v16
	v_and_b32_e32 v22, 0x3000, v19
	v_readfirstlane_b32 s16, v17
	v_add_u32_e32 v17, 0x2000, v17
	v_lshl_add_u64 v[18:19], v[4:5], 0, s[84:85]
	s_mov_b32 m0, s16
	s_mov_b64 s[20:21], 0x100080
	v_readfirstlane_b32 s15, v17
	v_add_u32_e32 v17, 0x8000, v12
	global_load_lds_dwordx4 v[18:19], off
	v_lshl_add_u64 v[18:19], v[4:5], 0, s[20:21]
	s_mov_b32 m0, s15
	v_readfirstlane_b32 s12, v17
	v_add_u32_e32 v17, 0xa000, v12
	global_load_lds_dwordx4 v[18:19], off
	v_lshl_add_u64 v[18:19], v[0:1], 0, s[84:85]
	s_mov_b32 m0, s12
	v_readfirstlane_b32 s11, v17
	global_load_lds_dwordx4 v[18:19], off
	v_lshl_add_u64 v[18:19], v[0:1], 0, s[20:21]
	s_mov_b32 m0, s11
	s_mov_b64 s[2:3], 0x200080
	v_add_u32_e32 v23, s62, v16
	global_load_lds_dwordx4 v[18:19], off
	v_lshl_add_u64 v[18:19], v[4:5], 0, s[2:3]
	v_readfirstlane_b32 s2, v23
	s_mov_b32 m0, s2
	s_mov_b64 s[18:19], 0x300080
	global_load_lds_dwordx4 v[18:19], off
	v_add_u32_e32 v18, 0x2000, v23
	v_lshl_add_u64 v[16:17], v[4:5], 0, s[18:19]
	v_readfirstlane_b32 s3, v18
	s_mov_b32 m0, s3
	v_add3_u32 v150, s95, v22, v20
	global_load_lds_dwordx4 v[16:17], off
	s_waitcnt vmcnt(10)
	s_barrier
	s_waitcnt vmcnt(6)
	s_barrier
	v_add3_u32 v151, 0, v21, v20
	ds_read_b128 v[16:19], v150
	ds_read_b128 v[20:23], v150 offset:1024
	ds_read_b128 v[24:27], v150 offset:2048
	ds_read_b128 v[28:31], v150 offset:3072
	v_add_u32_e32 v66, 0xc000, v12
	v_lshl_add_u64 v[64:65], v[6:7], 0, s[84:85]
	v_readfirstlane_b32 s14, v66
	v_add_u32_e32 v66, 0xe000, v12
	s_mov_b32 m0, s14
	v_readfirstlane_b32 s13, v66
	ds_read_b128 v[32:35], v151
	ds_read_b128 v[36:39], v151 offset:1024
	ds_read_b128 v[40:43], v151 offset:2048
	ds_read_b128 v[44:47], v151 offset:3072
	ds_read_b128 v[48:51], v151 offset:4096
	ds_read_b128 v[52:55], v151 offset:5120
	ds_read_b128 v[56:59], v151 offset:6144
	ds_read_b128 v[60:63], v151 offset:7168
	global_load_lds_dwordx4 v[64:65], off
	v_lshl_add_u64 v[64:65], v[6:7], 0, s[20:21]
	s_mov_b32 m0, s13
	s_nop 0
	global_load_lds_dwordx4 v[64:65], off
	s_waitcnt lgkmcnt(8)
	s_barrier
	s_waitcnt lgkmcnt(0)
	s_setprio 1
	s_waitcnt lgkmcnt(0)
	v_mfma_f32_16x16x32_f16 v[64:67], v[32:35], v[16:19], 0
	v_mfma_f32_16x16x32_f16 v[68:71], v[32:35], v[24:27], 0
	v_mfma_f32_16x16x32_f16 v[72:75], v[40:43], v[16:19], 0
	v_mfma_f32_16x16x32_f16 v[76:79], v[40:43], v[24:27], 0
	v_mfma_f32_16x16x32_f16 v[80:83], v[48:51], v[16:19], 0
	v_mfma_f32_16x16x32_f16 v[84:87], v[48:51], v[24:27], 0
	v_mfma_f32_16x16x32_f16 v[88:91], v[56:59], v[16:19], 0
	v_mfma_f32_16x16x32_f16 v[92:95], v[56:59], v[24:27], 0
	v_mfma_f32_16x16x32_f16 v[64:67], v[36:39], v[20:23], v[64:67]
	v_mfma_f32_16x16x32_f16 v[68:71], v[36:39], v[28:31], v[68:71]
	v_mfma_f32_16x16x32_f16 v[72:75], v[44:47], v[20:23], v[72:75]
	v_mfma_f32_16x16x32_f16 v[76:79], v[44:47], v[28:31], v[76:79]
	v_mfma_f32_16x16x32_f16 v[80:83], v[52:55], v[20:23], v[80:83]
	v_mfma_f32_16x16x32_f16 v[84:87], v[52:55], v[28:31], v[84:87]
	v_mfma_f32_16x16x32_f16 v[88:91], v[60:63], v[20:23], v[88:91]
	v_mfma_f32_16x16x32_f16 v[92:95], v[60:63], v[28:31], v[92:95]
	s_setprio 0
	s_barrier
	v_readfirstlane_b32 s17, v14
	v_lshl_add_u64 v[112:113], v[4:5], 0, s[92:93]
	s_mov_b32 m0, s17
	s_mov_b64 s[18:19], 0x100100
	v_readfirstlane_b32 s17, v15
	ds_read_b128 v[96:99], v150 offset:16384
	ds_read_b128 v[100:103], v150 offset:17408
	ds_read_b128 v[104:107], v150 offset:18432
	ds_read_b128 v[108:111], v150 offset:19456
	global_load_lds_dwordx4 v[112:113], off
	v_lshl_add_u64 v[112:113], v[4:5], 0, s[18:19]
	s_mov_b32 m0, s17
	s_nop 0
	global_load_lds_dwordx4 v[112:113], off
	s_barrier
	s_waitcnt lgkmcnt(0)
	s_setprio 1
	s_waitcnt lgkmcnt(0)
	v_mfma_f32_16x16x32_f16 v[112:115], v[32:35], v[96:99], 0
	v_mfma_f32_16x16x32_f16 v[32:35], v[32:35], v[104:107], 0
	v_mfma_f32_16x16x32_f16 v[112:115], v[36:39], v[100:103], v[112:115]
	v_mfma_f32_16x16x32_f16 v[32:35], v[36:39], v[108:111], v[32:35]
	v_mfma_f32_16x16x32_f16 v[36:39], v[40:43], v[96:99], 0
	v_mfma_f32_16x16x32_f16 v[40:43], v[40:43], v[104:107], 0
	v_mfma_f32_16x16x32_f16 v[36:39], v[44:47], v[100:103], v[36:39]
	v_mfma_f32_16x16x32_f16 v[40:43], v[44:47], v[108:111], v[40:43]
	v_mfma_f32_16x16x32_f16 v[44:47], v[48:51], v[96:99], 0
	v_mfma_f32_16x16x32_f16 v[48:51], v[48:51], v[104:107], 0
	v_mfma_f32_16x16x32_f16 v[44:47], v[52:55], v[100:103], v[44:47]
	v_mfma_f32_16x16x32_f16 v[48:51], v[52:55], v[108:111], v[48:51]
	v_mfma_f32_16x16x32_f16 v[52:55], v[56:59], v[96:99], 0
	v_mfma_f32_16x16x32_f16 v[56:59], v[56:59], v[104:107], 0
	v_mfma_f32_16x16x32_f16 v[52:55], v[60:63], v[100:103], v[52:55]
	v_mfma_f32_16x16x32_f16 v[56:59], v[60:63], v[108:111], v[56:59]
	s_setprio 0
	v_readfirstlane_b32 s17, v12
	v_lshl_add_u64 v[14:15], v[0:1], 0, s[92:93]
	s_mov_b32 m0, s17
	v_readfirstlane_b32 s17, v13
	s_barrier
	ds_read_b128 v[60:63], v151 offset:16384
	ds_read_b128 v[116:119], v151 offset:17408
	ds_read_b128 v[120:123], v151 offset:18432
	ds_read_b128 v[124:127], v151 offset:19456
	ds_read_b128 v[130:133], v151 offset:20480
	ds_read_b128 v[134:137], v151 offset:21504
	ds_read_b128 v[138:141], v151 offset:22528
	ds_read_b128 v[142:145], v151 offset:23552
	global_load_lds_dwordx4 v[14:15], off
	v_lshl_add_u64 v[14:15], v[0:1], 0, s[18:19]
	s_mov_b32 m0, s17
	s_nop 0
	global_load_lds_dwordx4 v[14:15], off
	s_barrier
;   #define STAGE(P,BASE,LD,br,kt) do{ const HALF* _u=(BASE)+(long)(br)*(((&(LD))==&lda)?lda_u:(LD))+(long)(kt)*G_BK; \
;     for(int _i=0;_i<2;++_i){ \
;       __builtin_amdgcn_global_load_lds((const unsigned*)(_u+(long)_i*(((&(LD))==&lda)?stepa:stepb)+((&(LD))==&lda?oa0:ob0)), \
;         (unsigned*)((char*)(P)+t5*16+_i*8192),16,0,0);}}while(0)
;   #define LDA(dst,b,h) for(int m=0;m<4;++m)for(int k=0;k<2;++k) \
;     dst[m][k]=*reinterpret_cast<const h8*>(la+(((b)*2+(h))*16384+m*2048+k*1024))
;   #define LDB(dst,b,h) for(int n=0;n<2;++n)for(int k=0;k<2;++k) \
;     dst[n][k]=*reinterpret_cast<const h8*>(lb+(((b)*2+(h))*16384+n*2048+k*1024))
;   #define MMA(ai,bj,At,Bt_) do{__builtin_amdgcn_s_setprio(1); \
;     for(int m=0;m<4;++m)for(int n=0;n<2;++n)for(int k=0;k<2;++k) \
;       acc[ai][bj][m][n]=__builtin_amdgcn_mfma_f32_16x16x32_f16(At[m][k],Bt_[n][k],acc[ai][bj][m][n],0,0,0); \
;     __builtin_amdgcn_s_setprio(0);}while(0)
;   #define WAIT_V(n) asm volatile("s_waitcnt vmcnt(" #n ")":::"memory")
;   #define WAIT_L(n) asm volatile("s_waitcnt lgkmcnt(" #n ")":::"memory")
;   #define BAR __builtin_amdgcn_s_barrier()
;   #define SCHED __builtin_amdgcn_sched_barrier(0)
;     ...
;     LDA(At,0,1); STAGE(SA(0,0),A,lda,0,t+2);
;     BAR; WAIT_L(0); MMA(1,0,At,B0); BAR; SCHED;
;     STAGE(SB(0,1),Bt,ldb,G_HALF,t+2);
;     WAIT_V(6); BAR; MMA(1,1,At,B1); BAR;
;     LDB(B0,1,0); SCHED; LDA(At,1,0); STAGE(SA(0,1),A,lda,G_HALF,t+2);
;     WAIT_L(8); BAR; WAIT_L(0); MMA(0,0,At,B0); BAR; SCHED;
;     LDB(B1,1,1); STAGE(SB(1,0),Bt,ldb,0,t+3);
;     BAR; WAIT_L(0); MMA(0,1,At,B1); BAR;
;     LDA(At,1,1); STAGE(SA(1,0),A,lda,0,t+3);
	s_waitcnt lgkmcnt(0)
	s_setprio 1
	s_waitcnt lgkmcnt(0)
	v_mfma_f32_16x16x32_f16 v[12:15], v[60:63], v[16:19], 0
	v_mfma_f32_16x16x32_f16 v[158:161], v[120:123], v[16:19], 0
	v_mfma_f32_16x16x32_f16 v[186:189], v[130:133], v[16:19], 0
	v_mfma_f32_16x16x32_f16 v[16:19], v[138:141], v[16:19], 0
	v_mfma_f32_16x16x32_f16 v[12:15], v[116:119], v[20:23], v[12:15]
	v_mfma_f32_16x16x32_f16 v[158:161], v[124:127], v[20:23], v[158:161]
	v_mfma_f32_16x16x32_f16 v[186:189], v[134:137], v[20:23], v[186:189]
	v_mfma_f32_16x16x32_f16 v[16:19], v[142:145], v[20:23], v[16:19]
	v_mfma_f32_16x16x32_f16 v[20:23], v[138:141], v[24:27], 0
	v_mfma_f32_16x16x32_f16 v[146:149], v[60:63], v[24:27], 0
	v_mfma_f32_16x16x32_f16 v[162:165], v[120:123], v[24:27], 0
	v_mfma_f32_16x16x32_f16 v[190:193], v[130:133], v[24:27], 0
	v_mfma_f32_16x16x32_f16 v[20:23], v[142:145], v[28:31], v[20:23]
	v_mfma_f32_16x16x32_f16 v[146:149], v[116:119], v[28:31], v[146:149]
	v_mfma_f32_16x16x32_f16 v[162:165], v[124:127], v[28:31], v[162:165]
	v_mfma_f32_16x16x32_f16 v[190:193], v[134:137], v[28:31], v[190:193]
	s_setprio 0
	s_barrier
	v_readfirstlane_b32 s17, v10
	v_lshl_add_u64 v[24:25], v[2:3], 0, s[92:93]
	s_mov_b32 m0, s17
	v_readfirstlane_b32 s17, v11
	global_load_lds_dwordx4 v[24:25], off
	v_lshl_add_u64 v[24:25], v[2:3], 0, s[18:19]
	s_mov_b32 m0, s17
	s_nop 0
	global_load_lds_dwordx4 v[24:25], off
	s_waitcnt vmcnt(6)
	s_barrier
	s_setprio 1
	v_mfma_f32_16x16x32_f16 v[24:27], v[60:63], v[96:99], 0
	v_mfma_f32_16x16x32_f16 v[28:31], v[60:63], v[104:107], 0
	v_mfma_f32_16x16x32_f16 v[24:27], v[116:119], v[100:103], v[24:27]
	v_mfma_f32_16x16x32_f16 v[28:31], v[116:119], v[108:111], v[28:31]
	v_mfma_f32_16x16x32_f16 v[60:63], v[120:123], v[96:99], 0
	v_mfma_f32_16x16x32_f16 v[116:119], v[120:123], v[104:107], 0
	v_mfma_f32_16x16x32_f16 v[120:123], v[130:133], v[96:99], 0
	v_mfma_f32_16x16x32_f16 v[96:99], v[138:141], v[96:99], 0
	v_mfma_f32_16x16x32_f16 v[60:63], v[124:127], v[100:103], v[60:63]
	v_mfma_f32_16x16x32_f16 v[116:119], v[124:127], v[108:111], v[116:119]
	v_mfma_f32_16x16x32_f16 v[120:123], v[134:137], v[100:103], v[120:123]
	v_mfma_f32_16x16x32_f16 v[124:127], v[130:133], v[104:107], 0
	v_mfma_f32_16x16x32_f16 v[96:99], v[142:145], v[100:103], v[96:99]
	v_mfma_f32_16x16x32_f16 v[100:103], v[138:141], v[104:107], 0
	v_mfma_f32_16x16x32_f16 v[124:127], v[134:137], v[108:111], v[124:127]
	v_mfma_f32_16x16x32_f16 v[100:103], v[142:145], v[108:111], v[100:103]
	s_setprio 0
	s_barrier
	ds_read_b128 v[104:107], v150 offset:32768
	ds_read_b128 v[108:111], v150 offset:33792
	ds_read_b128 v[130:133], v150 offset:34816
	ds_read_b128 v[134:137], v150 offset:35840
	v_readfirstlane_b32 s17, v8
	v_lshl_add_u64 v[10:11], v[6:7], 0, s[92:93]
	s_mov_b32 m0, s17
	v_readfirstlane_b32 s17, v9
	ds_read_b128 v[138:141], v151 offset:32768
	ds_read_b128 v[142:145], v151 offset:33792
	ds_read_b128 v[194:197], v151 offset:34816
	ds_read_b128 v[198:201], v151 offset:35840
	ds_read_b128 v[202:205], v151 offset:36864
	ds_read_b128 v[206:209], v151 offset:37888
	ds_read_b128 v[210:213], v151 offset:38912
	ds_read_b128 v[214:217], v151 offset:39936
	global_load_lds_dwordx4 v[10:11], off
	v_lshl_add_u64 v[6:7], v[6:7], 0, s[18:19]
	s_mov_b32 m0, s17
	s_nop 0
	global_load_lds_dwordx4 v[6:7], off
	s_waitcnt lgkmcnt(8)
	s_barrier
	s_waitcnt lgkmcnt(0)
	s_setprio 1
	s_waitcnt lgkmcnt(0)
	v_mfma_f32_16x16x32_f16 v[6:9], v[138:141], v[104:107], v[64:67]
	v_mfma_f32_16x16x32_f16 v[64:67], v[138:141], v[130:133], v[68:71]
	v_mfma_f32_16x16x32_f16 v[68:71], v[194:197], v[104:107], v[72:75]
	v_mfma_f32_16x16x32_f16 v[72:75], v[194:197], v[130:133], v[76:79]
	v_mfma_f32_16x16x32_f16 v[76:79], v[202:205], v[104:107], v[80:83]
	v_mfma_f32_16x16x32_f16 v[80:83], v[202:205], v[130:133], v[84:87]
	v_mfma_f32_16x16x32_f16 v[84:87], v[210:213], v[104:107], v[88:91]
	v_mfma_f32_16x16x32_f16 v[88:91], v[210:213], v[130:133], v[92:95]
	v_mfma_f32_16x16x32_f16 v[6:9], v[142:145], v[108:111], v[6:9]
	v_mfma_f32_16x16x32_f16 v[64:67], v[142:145], v[134:137], v[64:67]
	v_mfma_f32_16x16x32_f16 v[68:71], v[198:201], v[108:111], v[68:71]
	v_mfma_f32_16x16x32_f16 v[72:75], v[198:201], v[134:137], v[72:75]
	v_mfma_f32_16x16x32_f16 v[76:79], v[206:209], v[108:111], v[76:79]
	v_mfma_f32_16x16x32_f16 v[80:83], v[206:209], v[134:137], v[80:83]
	v_mfma_f32_16x16x32_f16 v[84:87], v[214:217], v[108:111], v[84:87]
	v_mfma_f32_16x16x32_f16 v[88:91], v[214:217], v[134:137], v[88:91]
	s_setprio 0
	s_barrier
	s_mov_b32 m0, s16
	v_lshl_add_u64 v[10:11], v[4:5], 0, s[42:43]
	s_mov_b64 s[16:17], 0x100180
	ds_read_b128 v[92:95], v150 offset:49152
	ds_read_b128 v[218:221], v150 offset:50176
	ds_read_b128 v[222:225], v150 offset:51200
	ds_read_b128 v[226:229], v150 offset:52224
	global_load_lds_dwordx4 v[10:11], off
	v_lshl_add_u64 v[4:5], v[4:5], 0, s[16:17]
	s_mov_b32 m0, s15
	s_nop 0
	global_load_lds_dwordx4 v[4:5], off
	s_barrier
	s_waitcnt lgkmcnt(0)
	s_setprio 1
	s_waitcnt lgkmcnt(0)
	v_mfma_f32_16x16x32_f16 v[112:115], v[138:141], v[92:95], v[112:115]
	v_mfma_f32_16x16x32_f16 v[32:35], v[138:141], v[222:225], v[32:35]
	v_mfma_f32_16x16x32_f16 v[36:39], v[194:197], v[92:95], v[36:39]
	v_mfma_f32_16x16x32_f16 v[40:43], v[194:197], v[222:225], v[40:43]
	v_mfma_f32_16x16x32_f16 v[44:47], v[202:205], v[92:95], v[44:47]
	v_mfma_f32_16x16x32_f16 v[48:51], v[202:205], v[222:225], v[48:51]
	v_mfma_f32_16x16x32_f16 v[52:55], v[210:213], v[92:95], v[52:55]
	v_mfma_f32_16x16x32_f16 v[56:59], v[210:213], v[222:225], v[56:59]
	v_mfma_f32_16x16x32_f16 v[112:115], v[142:145], v[218:221], v[112:115]
	v_mfma_f32_16x16x32_f16 v[32:35], v[142:145], v[226:229], v[32:35]
	v_mfma_f32_16x16x32_f16 v[36:39], v[198:201], v[218:221], v[36:39]
	v_mfma_f32_16x16x32_f16 v[40:43], v[198:201], v[226:229], v[40:43]
	v_mfma_f32_16x16x32_f16 v[44:47], v[206:209], v[218:221], v[44:47]
	v_mfma_f32_16x16x32_f16 v[48:51], v[206:209], v[226:229], v[48:51]
	v_mfma_f32_16x16x32_f16 v[52:55], v[214:217], v[218:221], v[52:55]
	v_mfma_f32_16x16x32_f16 v[56:59], v[214:217], v[226:229], v[56:59]
	s_setprio 0
	s_mov_b32 m0, s12
	v_lshl_add_u64 v[4:5], v[0:1], 0, s[42:43]
	s_barrier
;   #define STAGE(P,BASE,LD,br,kt) do{ const HALF* _u=(BASE)+(long)(br)*(((&(LD))==&lda)?lda_u:(LD))+(long)(kt)*G_BK; \
;     for(int _i=0;_i<2;++_i){ \
;       __builtin_amdgcn_global_load_lds((const unsigned*)(_u+(long)_i*(((&(LD))==&lda)?stepa:stepb)+((&(LD))==&lda?oa0:ob0)), \
;         (unsigned*)((char*)(P)+t5*16+_i*8192),16,0,0);}}while(0)
;   #define LDA(dst,b,h) for(int m=0;m<4;++m)for(int k=0;k<2;++k) \
;     dst[m][k]=*reinterpret_cast<const h8*>(la+(((b)*2+(h))*16384+m*2048+k*1024))
;   #define LDB(dst,b,h) for(int n=0;n<2;++n)for(int k=0;k<2;++k) \
;     dst[n][k]=*reinterpret_cast<const h8*>(lb+(((b)*2+(h))*16384+n*2048+k*1024))
;   #define MMA(ai,bj,At,Bt_) do{__builtin_amdgcn_s_setprio(1); \
;     for(int m=0;m<4;++m)for(int n=0;n<2;++n)for(int k=0;k<2;++k) \
;       acc[ai][bj][m][n]=__builtin_amdgcn_mfma_f32_16x16x32_f16(At[m][k],Bt_[n][k],acc[ai][bj][m][n],0,0,0); \
;     __builtin_amdgcn_s_setprio(0);}while(0)
;   #define WAIT_V(n) asm volatile("s_waitcnt vmcnt(" #n ")":::"memory")
;   #define WAIT_L(n) asm volatile("s_waitcnt lgkmcnt(" #n ")":::"memory")
;   #define BAR __builtin_amdgcn_s_barrier()
;   #define SCHED __builtin_amdgcn_sched_barrier(0)
;     ...
;     LDA(At,1,1); STAGE(SA(1,0),A,lda,0,t+3);
;     BAR; WAIT_L(0); MMA(1,0,At,B0); BAR; SCHED;
;     STAGE(SB(1,1),Bt,ldb,G_HALF,t+3);
;     WAIT_V(6); BAR; MMA(1,1,At,B1); BAR;
;   }
;   { LDB(B0,0,0); LDA(At,0,0); STAGE(SA(1,1),A,lda,G_HALF,nt-1);
;     BAR; WAIT_L(0); MMA(0,0,At,B0); BAR;
;     LDB(B1,0,1); BAR; WAIT_L(0); MMA(0,1,At,B1); BAR;
	ds_read_b128 v[138:141], v151 offset:49152
	ds_read_b128 v[142:145], v151 offset:50176
	ds_read_b128 v[194:197], v151 offset:51200
	ds_read_b128 v[198:201], v151 offset:52224
	ds_read_b128 v[202:205], v151 offset:53248
	ds_read_b128 v[206:209], v151 offset:54272
	ds_read_b128 v[210:213], v151 offset:55296
	ds_read_b128 v[214:217], v151 offset:56320
	global_load_lds_dwordx4 v[4:5], off
	v_lshl_add_u64 v[4:5], v[0:1], 0, s[16:17]
	s_mov_b32 m0, s11
	s_nop 0
	global_load_lds_dwordx4 v[4:5], off
	s_barrier
	s_waitcnt lgkmcnt(0)
	s_setprio 1
	s_waitcnt lgkmcnt(0)
	v_mfma_f32_16x16x32_f16 v[10:13], v[138:141], v[104:107], v[12:15]
	v_mfma_f32_16x16x32_f16 v[14:17], v[210:213], v[104:107], v[16:19]
	v_mfma_f32_16x16x32_f16 v[18:21], v[210:213], v[130:133], v[20:23]
	v_mfma_f32_16x16x32_f16 v[10:13], v[142:145], v[108:111], v[10:13]
	v_mfma_f32_16x16x32_f16 v[146:149], v[138:141], v[130:133], v[146:149]
	v_mfma_f32_16x16x32_f16 v[158:161], v[194:197], v[104:107], v[158:161]
	v_mfma_f32_16x16x32_f16 v[162:165], v[194:197], v[130:133], v[162:165]
	v_mfma_f32_16x16x32_f16 v[186:189], v[202:205], v[104:107], v[186:189]
	v_mfma_f32_16x16x32_f16 v[190:193], v[202:205], v[130:133], v[190:193]
	v_mfma_f32_16x16x32_f16 v[14:17], v[214:217], v[108:111], v[14:17]
	v_mfma_f32_16x16x32_f16 v[18:21], v[214:217], v[134:137], v[18:21]
	v_mfma_f32_16x16x32_f16 v[146:149], v[142:145], v[134:137], v[146:149]
	v_mfma_f32_16x16x32_f16 v[158:161], v[198:201], v[108:111], v[158:161]
	v_mfma_f32_16x16x32_f16 v[162:165], v[198:201], v[134:137], v[162:165]
	v_mfma_f32_16x16x32_f16 v[186:189], v[206:209], v[108:111], v[186:189]
	v_mfma_f32_16x16x32_f16 v[190:193], v[206:209], v[134:137], v[190:193]
	s_setprio 0
	s_barrier
	s_mov_b32 m0, s2
	v_lshl_add_u64 v[4:5], v[2:3], 0, s[42:43]
	global_load_lds_dwordx4 v[4:5], off
	v_lshl_add_u64 v[2:3], v[2:3], 0, s[16:17]
	s_mov_b32 m0, s3
	s_nop 0
	global_load_lds_dwordx4 v[2:3], off
	s_waitcnt vmcnt(6)
	s_barrier
	s_setprio 1
	v_mfma_f32_16x16x32_f16 v[2:5], v[138:141], v[92:95], v[24:27]
	v_mfma_f32_16x16x32_f16 v[22:25], v[138:141], v[222:225], v[28:31]
	v_mfma_f32_16x16x32_f16 v[26:29], v[194:197], v[92:95], v[60:63]
	v_mfma_f32_16x16x32_f16 v[60:63], v[194:197], v[222:225], v[116:119]
	v_mfma_f32_16x16x32_f16 v[104:107], v[202:205], v[92:95], v[120:123]
	v_mfma_f32_16x16x32_f16 v[108:111], v[202:205], v[222:225], v[124:127]
	v_mfma_f32_16x16x32_f16 v[92:95], v[210:213], v[92:95], v[96:99]
	v_mfma_f32_16x16x32_f16 v[96:99], v[210:213], v[222:225], v[100:103]
	v_mfma_f32_16x16x32_f16 v[2:5], v[142:145], v[218:221], v[2:5]
	v_mfma_f32_16x16x32_f16 v[22:25], v[142:145], v[226:229], v[22:25]
	v_mfma_f32_16x16x32_f16 v[26:29], v[198:201], v[218:221], v[26:29]
	v_mfma_f32_16x16x32_f16 v[60:63], v[198:201], v[226:229], v[60:63]
	v_mfma_f32_16x16x32_f16 v[104:107], v[206:209], v[218:221], v[104:107]
	v_mfma_f32_16x16x32_f16 v[108:111], v[206:209], v[226:229], v[108:111]
	v_mfma_f32_16x16x32_f16 v[92:95], v[214:217], v[218:221], v[92:95]
	v_mfma_f32_16x16x32_f16 v[96:99], v[214:217], v[226:229], v[96:99]
	s_setprio 0
	s_mov_b64 s[2:3], 0x200180
	s_mov_b32 m0, s14
	v_lshl_add_u64 v[30:31], v[0:1], 0, s[2:3]
	s_mov_b64 s[2:3], 0x300180
	s_barrier
	ds_read_b128 v[100:103], v150
	ds_read_b128 v[116:119], v150 offset:1024
	ds_read_b128 v[120:123], v150 offset:2048
	ds_read_b128 v[124:127], v150 offset:3072
	ds_read_b128 v[130:133], v151
	ds_read_b128 v[134:137], v151 offset:1024
	ds_read_b128 v[138:141], v151 offset:2048
	ds_read_b128 v[142:145], v151 offset:3072
	ds_read_b128 v[194:197], v151 offset:4096
	ds_read_b128 v[198:201], v151 offset:5120
	ds_read_b128 v[202:205], v151 offset:6144
	ds_read_b128 v[206:209], v151 offset:7168
	global_load_lds_dwordx4 v[30:31], off
	v_lshl_add_u64 v[0:1], v[0:1], 0, s[2:3]
	s_mov_b32 m0, s13
	s_nop 0
	global_load_lds_dwordx4 v[0:1], off
	s_barrier
	s_waitcnt lgkmcnt(0)
	s_setprio 1
	s_waitcnt lgkmcnt(0)
	v_mfma_f32_16x16x32_f16 v[6:9], v[130:133], v[100:103], v[6:9]
	v_mfma_f32_16x16x32_f16 v[64:67], v[130:133], v[120:123], v[64:67]
	v_mfma_f32_16x16x32_f16 v[68:71], v[138:141], v[100:103], v[68:71]
	v_mfma_f32_16x16x32_f16 v[72:75], v[138:141], v[120:123], v[72:75]
	v_mfma_f32_16x16x32_f16 v[76:79], v[194:197], v[100:103], v[76:79]
	v_mfma_f32_16x16x32_f16 v[80:83], v[194:197], v[120:123], v[80:83]
	v_mfma_f32_16x16x32_f16 v[84:87], v[202:205], v[100:103], v[84:87]
	v_mfma_f32_16x16x32_f16 v[88:91], v[202:205], v[120:123], v[88:91]
	v_mfma_f32_16x16x32_f16 v[6:9], v[134:137], v[116:119], v[6:9]
	v_mfma_f32_16x16x32_f16 v[64:67], v[134:137], v[124:127], v[64:67]
	v_mfma_f32_16x16x32_f16 v[68:71], v[142:145], v[116:119], v[68:71]
	v_mfma_f32_16x16x32_f16 v[72:75], v[142:145], v[124:127], v[72:75]
	v_mfma_f32_16x16x32_f16 v[76:79], v[198:201], v[116:119], v[76:79]
	v_mfma_f32_16x16x32_f16 v[80:83], v[198:201], v[124:127], v[80:83]
	v_mfma_f32_16x16x32_f16 v[84:87], v[206:209], v[116:119], v[84:87]
	v_mfma_f32_16x16x32_f16 v[88:91], v[206:209], v[124:127], v[88:91]
	s_setprio 0
	s_barrier
	ds_read_b128 v[210:213], v150 offset:16384
	ds_read_b128 v[214:217], v150 offset:17408
	ds_read_b128 v[218:221], v150 offset:18432
	ds_read_b128 v[222:225], v150 offset:19456
	s_barrier
;   #define LDA(dst,b,h) for(int m=0;m<4;++m)for(int k=0;k<2;++k) \
;     dst[m][k]=*reinterpret_cast<const h8*>(la+(((b)*2+(h))*16384+m*2048+k*1024))
;   #define LDB(dst,b,h) for(int n=0;n<2;++n)for(int k=0;k<2;++k) \
;     dst[n][k]=*reinterpret_cast<const h8*>(lb+(((b)*2+(h))*16384+n*2048+k*1024))
;   #define MMA(ai,bj,At,Bt_) do{__builtin_amdgcn_s_setprio(1); \
;     for(int m=0;m<4;++m)for(int n=0;n<2;++n)for(int k=0;k<2;++k) \
;       acc[ai][bj][m][n]=__builtin_amdgcn_mfma_f32_16x16x32_f16(At[m][k],Bt_[n][k],acc[ai][bj][m][n],0,0,0); \
;     __builtin_amdgcn_s_setprio(0);}while(0)
;   #define WAIT_V(n) asm volatile("s_waitcnt vmcnt(" #n ")":::"memory")
;   #define WAIT_L(n) asm volatile("s_waitcnt lgkmcnt(" #n ")":::"memory")
;   #define BAR __builtin_amdgcn_s_barrier()
;     ...
;     LDB(B1,0,1); BAR; WAIT_L(0); MMA(0,1,At,B1); BAR;
;     LDA(At,0,1); WAIT_V(4); BAR; WAIT_L(0); MMA(1,0,At,B0); MMA(1,1,At,B1); BAR; }
;   { LDB(B0,1,0); LDA(At,1,0); WAIT_V(2); BAR; WAIT_L(0); MMA(0,0,At,B0); BAR;
	s_waitcnt lgkmcnt(0)
	s_setprio 1
	s_waitcnt lgkmcnt(0)
	v_mfma_f32_16x16x32_f16 v[30:33], v[130:133], v[218:221], v[32:35]
	v_mfma_f32_16x16x32_f16 v[34:37], v[138:141], v[210:213], v[36:39]
	v_mfma_f32_16x16x32_f16 v[38:41], v[138:141], v[218:221], v[40:43]
	v_mfma_f32_16x16x32_f16 v[42:45], v[194:197], v[210:213], v[44:47]
	v_mfma_f32_16x16x32_f16 v[46:49], v[194:197], v[218:221], v[48:51]
	v_mfma_f32_16x16x32_f16 v[50:53], v[202:205], v[210:213], v[52:55]
	v_mfma_f32_16x16x32_f16 v[54:57], v[202:205], v[218:221], v[56:59]
	v_mfma_f32_16x16x32_f16 v[112:115], v[130:133], v[210:213], v[112:115]
	v_mfma_f32_16x16x32_f16 v[30:33], v[134:137], v[222:225], v[30:33]
	v_mfma_f32_16x16x32_f16 v[34:37], v[142:145], v[214:217], v[34:37]
	v_mfma_f32_16x16x32_f16 v[38:41], v[142:145], v[222:225], v[38:41]
	v_mfma_f32_16x16x32_f16 v[42:45], v[198:201], v[214:217], v[42:45]
	v_mfma_f32_16x16x32_f16 v[46:49], v[198:201], v[222:225], v[46:49]
	v_mfma_f32_16x16x32_f16 v[50:53], v[206:209], v[214:217], v[50:53]
	v_mfma_f32_16x16x32_f16 v[54:57], v[206:209], v[222:225], v[54:57]
	v_mfma_f32_16x16x32_f16 v[226:229], v[134:137], v[214:217], v[112:115]
	s_setprio 0
	s_barrier
	s_nop 0
	ds_read_b128 v[112:115], v151 offset:16384
	ds_read_b128 v[130:133], v151 offset:17408
	ds_read_b128 v[134:137], v151 offset:18432
	ds_read_b128 v[138:141], v151 offset:19456
	ds_read_b128 v[142:145], v151 offset:20480
	ds_read_b128 v[194:197], v151 offset:21504
	ds_read_b128 v[198:201], v151 offset:22528
	ds_read_b128 v[202:205], v151 offset:23552
	s_waitcnt vmcnt(4)
	s_barrier
	s_waitcnt lgkmcnt(0)
	s_setprio 1
	s_waitcnt lgkmcnt(0)
	v_mfma_f32_16x16x32_f16 v[10:13], v[112:115], v[100:103], v[10:13]
	v_mfma_f32_16x16x32_f16 v[14:17], v[198:201], v[100:103], v[14:17]
	v_mfma_f32_16x16x32_f16 v[18:21], v[198:201], v[120:123], v[18:21]
	v_mfma_f32_16x16x32_f16 v[10:13], v[130:133], v[116:119], v[10:13]
	v_mfma_f32_16x16x32_f16 v[146:149], v[112:115], v[120:123], v[146:149]
	v_mfma_f32_16x16x32_f16 v[158:161], v[134:137], v[100:103], v[158:161]
	v_mfma_f32_16x16x32_f16 v[162:165], v[134:137], v[120:123], v[162:165]
	v_mfma_f32_16x16x32_f16 v[186:189], v[142:145], v[100:103], v[186:189]
	v_mfma_f32_16x16x32_f16 v[190:193], v[142:145], v[120:123], v[190:193]
	v_mfma_f32_16x16x32_f16 v[14:17], v[202:205], v[116:119], v[14:17]
	v_mfma_f32_16x16x32_f16 v[18:21], v[202:205], v[124:127], v[18:21]
	v_mfma_f32_16x16x32_f16 v[146:149], v[130:133], v[124:127], v[146:149]
	v_mfma_f32_16x16x32_f16 v[158:161], v[138:141], v[116:119], v[158:161]
	v_mfma_f32_16x16x32_f16 v[162:165], v[138:141], v[124:127], v[162:165]
	v_mfma_f32_16x16x32_f16 v[186:189], v[194:197], v[116:119], v[186:189]
	v_mfma_f32_16x16x32_f16 v[190:193], v[194:197], v[124:127], v[190:193]
	s_setprio 0
	s_setprio 1
	v_mfma_f32_16x16x32_f16 v[0:3], v[112:115], v[210:213], v[2:5]
	v_mfma_f32_16x16x32_f16 v[22:25], v[112:115], v[218:221], v[22:25]
	v_mfma_f32_16x16x32_f16 v[26:29], v[134:137], v[210:213], v[26:29]
	v_mfma_f32_16x16x32_f16 v[0:3], v[130:133], v[214:217], v[0:3]
	v_mfma_f32_16x16x32_f16 v[22:25], v[130:133], v[222:225], v[22:25]
	v_mfma_f32_16x16x32_f16 v[130:133], v[138:141], v[214:217], v[26:29]
	v_mfma_f32_16x16x32_f16 v[26:29], v[134:137], v[218:221], v[60:63]
	v_mfma_f32_16x16x32_f16 v[134:137], v[138:141], v[222:225], v[26:29]
	v_mfma_f32_16x16x32_f16 v[26:29], v[142:145], v[210:213], v[104:107]
	v_mfma_f32_16x16x32_f16 v[138:141], v[194:197], v[214:217], v[26:29]
	v_mfma_f32_16x16x32_f16 v[26:29], v[142:145], v[218:221], v[108:111]
	v_mfma_f32_16x16x32_f16 v[142:145], v[194:197], v[222:225], v[26:29]
	v_mfma_f32_16x16x32_f16 v[26:29], v[198:201], v[210:213], v[92:95]
	v_mfma_f32_16x16x32_f16 v[194:197], v[202:205], v[214:217], v[26:29]
	v_mfma_f32_16x16x32_f16 v[26:29], v[198:201], v[218:221], v[96:99]
	v_mfma_f32_16x16x32_f16 v[198:201], v[202:205], v[222:225], v[26:29]
	s_setprio 0
	s_barrier
	s_nop 4
	ds_read_b128 v[26:29], v150 offset:32768
	ds_read_b128 v[202:205], v150 offset:33792
	ds_read_b128 v[206:209], v150 offset:34816
	ds_read_b128 v[210:213], v150 offset:35840
	ds_read_b128 v[58:61], v151 offset:32768
	ds_read_b128 v[92:95], v151 offset:33792
	ds_read_b128 v[214:217], v151 offset:34816
	ds_read_b128 v[218:221], v151 offset:35840
	ds_read_b128 v[222:225], v151 offset:36864
	ds_read_b128 v[230:233], v151 offset:37888
	ds_read_b128 v[234:237], v151 offset:38912
	ds_read_b128 v[238:241], v151 offset:39936
	s_waitcnt vmcnt(2)
	s_barrier
;   #define LDA(dst,b,h) for(int m=0;m<4;++m)for(int k=0;k<2;++k) \
;     dst[m][k]=*reinterpret_cast<const h8*>(la+(((b)*2+(h))*16384+m*2048+k*1024))
;   #define LDB(dst,b,h) for(int n=0;n<2;++n)for(int k=0;k<2;++k) \
;     dst[n][k]=*reinterpret_cast<const h8*>(lb+(((b)*2+(h))*16384+n*2048+k*1024))
;   #define MMA(ai,bj,At,Bt_) do{__builtin_amdgcn_s_setprio(1); \
;     for(int m=0;m<4;++m)for(int n=0;n<2;++n)for(int k=0;k<2;++k) \
;       acc[ai][bj][m][n]=__builtin_amdgcn_mfma_f32_16x16x32_f16(At[m][k],Bt_[n][k],acc[ai][bj][m][n],0,0,0); \
;     __builtin_amdgcn_s_setprio(0);}while(0)
;   #define WAIT_V(n) asm volatile("s_waitcnt vmcnt(" #n ")":::"memory")
;   #define WAIT_L(n) asm volatile("s_waitcnt lgkmcnt(" #n ")":::"memory")
;   #define BAR __builtin_amdgcn_s_barrier()
;     ...
;   { LDB(B0,1,0); LDA(At,1,0); WAIT_V(2); BAR; WAIT_L(0); MMA(0,0,At,B0); BAR;
;     LDB(B1,1,1); WAIT_V(0); BAR; WAIT_L(0); MMA(0,1,At,B1); BAR;
;     LDA(At,1,1); BAR; WAIT_L(0); MMA(1,0,At,B0); MMA(1,1,At,B1); BAR; }
;   if(wr==0)BAR;
	s_waitcnt lgkmcnt(0)
	s_setprio 1
	s_waitcnt lgkmcnt(0)
	v_mfma_f32_16x16x32_f16 v[4:7], v[58:61], v[26:29], v[6:9]
	v_mfma_f32_16x16x32_f16 v[124:127], v[92:95], v[202:205], v[4:7]
	v_mfma_f32_16x16x32_f16 v[4:7], v[58:61], v[206:209], v[64:67]
	v_mfma_f32_16x16x32_f16 v[120:123], v[92:95], v[210:213], v[4:7]
	v_mfma_f32_16x16x32_f16 v[4:7], v[214:217], v[26:29], v[68:71]
	v_mfma_f32_16x16x32_f16 v[116:119], v[218:221], v[202:205], v[4:7]
	v_mfma_f32_16x16x32_f16 v[4:7], v[214:217], v[206:209], v[72:75]
	v_mfma_f32_16x16x32_f16 v[112:115], v[218:221], v[210:213], v[4:7]
	v_mfma_f32_16x16x32_f16 v[4:7], v[222:225], v[26:29], v[76:79]
	v_mfma_f32_16x16x32_f16 v[108:111], v[230:233], v[202:205], v[4:7]
	v_mfma_f32_16x16x32_f16 v[4:7], v[222:225], v[206:209], v[80:83]
	v_mfma_f32_16x16x32_f16 v[100:103], v[230:233], v[210:213], v[4:7]
	v_mfma_f32_16x16x32_f16 v[4:7], v[234:237], v[26:29], v[84:87]
	v_mfma_f32_16x16x32_f16 v[96:99], v[238:241], v[202:205], v[4:7]
	v_mfma_f32_16x16x32_f16 v[4:7], v[234:237], v[206:209], v[88:91]
	v_mfma_f32_16x16x32_f16 v[88:91], v[238:241], v[210:213], v[4:7]
	s_setprio 0
	s_barrier
	s_nop 4
	ds_read_b128 v[4:7], v150 offset:49152
	ds_read_b128 v[242:245], v150 offset:50176
	ds_read_b128 v[246:249], v150 offset:51200
	ds_read_b128 v[250:253], v150 offset:52224
	s_waitcnt vmcnt(0)
	s_barrier
	s_waitcnt lgkmcnt(0)
	s_setprio 1
	s_waitcnt lgkmcnt(0)
	v_mfma_f32_16x16x32_f16 v[62:65], v[58:61], v[4:7], v[226:229]
	v_mfma_f32_16x16x32_f16 v[30:33], v[58:61], v[246:249], v[30:33]
	v_mfma_f32_16x16x32_f16 v[104:107], v[92:95], v[242:245], v[62:65]
	v_mfma_f32_16x16x32_f16 v[92:95], v[92:95], v[250:253], v[30:33]
	v_mfma_f32_16x16x32_f16 v[30:33], v[214:217], v[4:7], v[34:37]
	v_mfma_f32_16x16x32_f16 v[84:87], v[218:221], v[242:245], v[30:33]
	v_mfma_f32_16x16x32_f16 v[30:33], v[214:217], v[246:249], v[38:41]
	v_mfma_f32_16x16x32_f16 v[80:83], v[218:221], v[250:253], v[30:33]
	v_mfma_f32_16x16x32_f16 v[30:33], v[222:225], v[4:7], v[42:45]
	v_mfma_f32_16x16x32_f16 v[76:79], v[230:233], v[242:245], v[30:33]
	v_mfma_f32_16x16x32_f16 v[30:33], v[222:225], v[246:249], v[46:49]
	v_mfma_f32_16x16x32_f16 v[68:71], v[230:233], v[250:253], v[30:33]
	v_mfma_f32_16x16x32_f16 v[30:33], v[234:237], v[4:7], v[50:53]
	v_mfma_f32_16x16x32_f16 v[60:63], v[238:241], v[242:245], v[30:33]
	v_mfma_f32_16x16x32_f16 v[30:33], v[234:237], v[246:249], v[54:57]
	v_mfma_f32_16x16x32_f16 v[48:51], v[238:241], v[250:253], v[30:33]
	s_setprio 0
	s_barrier
	ds_read_b128 v[214:217], v151 offset:49152
	ds_read_b128 v[218:221], v151 offset:50176
	ds_read_b128 v[222:225], v151 offset:51200
	ds_read_b128 v[226:229], v151 offset:52224
	ds_read_b128 v[230:233], v151 offset:53248
	ds_read_b128 v[234:237], v151 offset:54272
	ds_read_b128 v[238:241], v151 offset:55296
	ds_read_b128 v[170:173], v151 offset:56320
	s_barrier
	s_waitcnt lgkmcnt(0)
	s_setprio 1
	s_waitcnt lgkmcnt(0)
	v_mfma_f32_16x16x32_f16 v[8:11], v[214:217], v[26:29], v[10:13]
	v_mfma_f32_16x16x32_f16 v[72:75], v[218:221], v[202:205], v[8:11]
	v_mfma_f32_16x16x32_f16 v[8:11], v[214:217], v[206:209], v[146:149]
	v_mfma_f32_16x16x32_f16 v[64:67], v[218:221], v[210:213], v[8:11]
	v_mfma_f32_16x16x32_f16 v[8:11], v[222:225], v[26:29], v[158:161]
	v_mfma_f32_16x16x32_f16 v[56:59], v[226:229], v[202:205], v[8:11]
	v_mfma_f32_16x16x32_f16 v[8:11], v[222:225], v[206:209], v[162:165]
	v_mfma_f32_16x16x32_f16 v[52:55], v[226:229], v[210:213], v[8:11]
	v_mfma_f32_16x16x32_f16 v[8:11], v[230:233], v[26:29], v[186:189]
	v_mfma_f32_16x16x32_f16 v[44:47], v[234:237], v[202:205], v[8:11]
	v_mfma_f32_16x16x32_f16 v[8:11], v[230:233], v[206:209], v[190:193]
	v_mfma_f32_16x16x32_f16 v[40:43], v[234:237], v[210:213], v[8:11]
	v_mfma_f32_16x16x32_f16 v[8:11], v[238:241], v[26:29], v[14:17]
	v_mfma_f32_16x16x32_f16 v[36:39], v[170:173], v[202:205], v[8:11]
	v_mfma_f32_16x16x32_f16 v[8:11], v[238:241], v[206:209], v[18:21]
	v_mfma_f32_16x16x32_f16 v[32:35], v[170:173], v[210:213], v[8:11]
	s_setprio 0
	s_setprio 1
	v_mfma_f32_16x16x32_f16 v[0:3], v[214:217], v[4:7], v[0:3]
	v_mfma_f32_16x16x32_f16 v[28:31], v[218:221], v[242:245], v[0:3]
	v_mfma_f32_16x16x32_f16 v[0:3], v[214:217], v[246:249], v[22:25]
	v_mfma_f32_16x16x32_f16 v[24:27], v[218:221], v[250:253], v[0:3]
	v_mfma_f32_16x16x32_f16 v[0:3], v[222:225], v[4:7], v[130:133]
	v_mfma_f32_16x16x32_f16 v[20:23], v[226:229], v[242:245], v[0:3]
	v_mfma_f32_16x16x32_f16 v[0:3], v[222:225], v[246:249], v[134:137]
	v_mfma_f32_16x16x32_f16 v[16:19], v[226:229], v[250:253], v[0:3]
	v_mfma_f32_16x16x32_f16 v[0:3], v[230:233], v[4:7], v[138:141]
	v_mfma_f32_16x16x32_f16 v[12:15], v[234:237], v[242:245], v[0:3]
	v_mfma_f32_16x16x32_f16 v[0:3], v[230:233], v[246:249], v[142:145]
	v_mfma_f32_16x16x32_f16 v[8:11], v[234:237], v[250:253], v[0:3]
	v_mfma_f32_16x16x32_f16 v[0:3], v[238:241], v[4:7], v[194:197]
	v_mfma_f32_16x16x32_f16 v[4:7], v[170:173], v[242:245], v[0:3]
	v_mfma_f32_16x16x32_f16 v[0:3], v[238:241], v[246:249], v[198:201]
	v_mfma_f32_16x16x32_f16 v[0:3], v[170:173], v[250:253], v[0:3]
	s_setprio 0
	s_movk_i32 s2, 0x100
	v_cmp_gt_u32_e32 vcc, s2, v129
	s_barrier
	s_and_saveexec_b64 s[2:3], vcc
	s_cbranch_execz .LBB0_396
	s_barrier

;   #define STAGE(P,BASE,LD,br,kt) do{ const HALF* _u=(BASE)+(long)(br)*(((&(LD))==&lda)?lda_u:(LD))+(long)(kt)*G_BK; \
;     for(int _i=0;_i<2;++_i){ \
;       __builtin_amdgcn_global_load_lds((const unsigned*)(_u+(long)_i*(((&(LD))==&lda)?stepa:stepb)+((&(LD))==&lda?oa0:ob0)), \
;         (unsigned*)((char*)(P)+t5*16+_i*8192),16,0,0);}}while(0)
;   #define LDA(dst,b,h) for(int m=0;m<4;++m)for(int k=0;k<2;++k) \
;     dst[m][k]=*reinterpret_cast<const h8*>(la+(((b)*2+(h))*16384+m*2048+k*1024))
;   #define LDB(dst,b,h) for(int n=0;n<2;++n)for(int k=0;k<2;++k) \
;     dst[n][k]=*reinterpret_cast<const h8*>(lb+(((b)*2+(h))*16384+n*2048+k*1024))
;   #define MMA(ai,bj,At,Bt_) do{__builtin_amdgcn_s_setprio(1); \
;     for(int m=0;m<4;++m)for(int n=0;n<2;++n)for(int k=0;k<2;++k) \
;       acc[ai][bj][m][n]=__builtin_amdgcn_mfma_f32_16x16x32_f16(At[m][k],Bt_[n][k],acc[ai][bj][m][n],0,0,0); \
;     __builtin_amdgcn_s_setprio(0);}while(0)
;   #define WAIT_V(n) asm volatile("s_waitcnt vmcnt(" #n ")":::"memory")
;   #define WAIT_L(n) asm volatile("s_waitcnt lgkmcnt(" #n ")":::"memory")
;   #define BAR __builtin_amdgcn_s_barrier()
;   #define SCHED __builtin_amdgcn_sched_barrier(0)
;     ...
;   {int _b=t5*16;int _r,_c;g_stage_rc(_b,_r,_c);
;     oa0=n2 ? (unsigned)((n2*(_r&63)+(_r>>6))*1024+_c) : (unsigned)(_r*lda+_c); ob0=(unsigned)(_r*ldb+_c);}
;   STAGE(SB(0,0),Bt,ldb,0,0); STAGE(SA(0,0),A,lda,0,0);
;   STAGE(SB(0,1),Bt,ldb,G_HALF,0); STAGE(SA(0,1),A,lda,G_HALF,0);
;   if(wr==1)BAR;
;   WAIT_V(4); BAR;
;   STAGE(SB(1,0),Bt,ldb,0,1); STAGE(SA(1,0),A,lda,0,1); STAGE(SB(1,1),Bt,ldb,G_HALF,1);
;   WAIT_V(6); BAR;
;   for(int t=0;t<nt-2;t+=2){
;     LDB(B0,0,0); SCHED; LDA(At,0,0); STAGE(SA(1,1),A,lda,G_HALF,t+1);
;     WAIT_L(8); BAR; WAIT_L(0); MMA(0,0,At,B0); BAR; SCHED;
;     LDB(B1,0,1); STAGE(SB(0,0),Bt,ldb,0,t+2);
;     BAR; WAIT_L(0); MMA(0,1,At,B1); BAR;
;     LDA(At,0,1); STAGE(SA(0,0),A,lda,0,t+2);
.LBB0_479:
	s_or_b64 exec, exec, s[6:7]
	s_mov_b32 s6, 0x3f2aaada
	v_pk_fma_f32 v[94:95], v[88:89], v[0:1], s[6:7] op_sel_hi:[1,1,0]
	s_mov_b32 s6, 0xb102e308
	v_pk_fma_f32 v[92:93], v[80:81], s[6:7], v[2:3] op_sel_hi:[1,0,1]
	v_lshlrev_b32_e32 v1, 6, v122
	v_lshlrev_b32_e32 v3, 2, v122
	v_add_u32_e32 v22, s29, v12
	v_and_b32_e32 v0, 48, v122
	v_and_b32_e32 v2, 0x3c0, v1
	v_and_b32_e32 v3, 32, v3
	v_readfirstlane_b32 s77, v22
	v_add_u32_e32 v22, 0x2000, v22
	v_bitop3_b32 v2, v2, v3, v0 bitop3:0x36
	v_lshlrev_b32_e32 v3, 13, v14
	v_and_b32_e32 v14, 0x3000, v1
	v_lshl_add_u64 v[0:1], v[4:5], 0, s[84:85]
	s_mov_b32 m0, s77
	s_mov_b64 s[6:7], 0x20080
	v_readfirstlane_b32 s76, v22
	v_add_u32_e32 v22, 0x8000, v20
	global_load_lds_dwordx4 v[0:1], off
	v_lshl_add_u64 v[0:1], v[4:5], 0, s[6:7]
	s_mov_b32 m0, s76
	v_readfirstlane_b32 s44, v22
	v_add_u32_e32 v22, 0xa000, v20
	global_load_lds_dwordx4 v[0:1], off
	v_lshl_add_u64 v[0:1], v[6:7], 0, s[84:85]
	s_mov_b32 m0, s44
	s_mov_b64 s[70:71], 0x8080
	v_readfirstlane_b32 s22, v22
	s_add_u32 s6, s10, 0x40080
	v_add_u32_e32 v12, s62, v12
	global_load_lds_dwordx4 v[0:1], off
	v_lshl_add_u64 v[0:1], v[6:7], 0, s[70:71]
	s_mov_b32 m0, s22
	s_addc_u32 s7, s11, 0
	v_readfirstlane_b32 s13, v12
	v_add_u32_e32 v12, 0x2000, v12
	global_load_lds_dwordx4 v[0:1], off
	v_lshl_add_u64 v[0:1], v[152:153], 1, s[6:7]
	s_mov_b32 m0, s13
	v_readfirstlane_b32 s12, v12
	global_load_lds_dwordx4 v[0:1], off
	v_lshl_add_u64 v[0:1], v[0:1], 0, s[68:69]
	s_mov_b32 m0, s12
	v_add3_u32 v81, s95, v14, v2
	global_load_lds_dwordx4 v[0:1], off
	s_waitcnt vmcnt(10)
	s_barrier
	s_waitcnt vmcnt(6)
	s_barrier
	v_add3_u32 v123, 0, v3, v2
	ds_read_b128 v[0:3], v81
	ds_read_b128 v[22:25], v81 offset:1024
	ds_read_b128 v[26:29], v81 offset:2048
	ds_read_b128 v[30:33], v81 offset:3072
	v_add_u32_e32 v12, 0xc000, v20
	v_lshl_add_u64 v[66:67], v[10:11], 0, s[84:85]
	v_readfirstlane_b32 s80, v12
	s_mov_b32 m0, s80
	v_add_u32_e32 v12, 0xe000, v20
	ds_read_b128 v[34:37], v123
	ds_read_b128 v[38:41], v123 offset:1024
	ds_read_b128 v[42:45], v123 offset:2048
	ds_read_b128 v[46:49], v123 offset:3072
	ds_read_b128 v[50:53], v123 offset:4096
	ds_read_b128 v[54:57], v123 offset:5120
	ds_read_b128 v[58:61], v123 offset:6144
	ds_read_b128 v[62:65], v123 offset:7168
	global_load_lds_dwordx4 v[66:67], off
	v_lshl_add_u64 v[66:67], v[10:11], 0, s[70:71]
	v_readfirstlane_b32 s71, v12
	s_mov_b32 m0, s71
	s_nop 0
	global_load_lds_dwordx4 v[66:67], off
	s_waitcnt lgkmcnt(8)
	s_barrier
	s_waitcnt lgkmcnt(0)
	s_setprio 1
	s_waitcnt lgkmcnt(0)
	v_mfma_f32_16x16x32_f16 v[66:69], v[34:37], v[0:3], 0
	v_mfma_f32_16x16x32_f16 v[76:79], v[34:37], v[26:29], 0
	v_mfma_f32_16x16x32_f16 v[84:87], v[42:45], v[0:3], 0
	v_mfma_f32_16x16x32_f16 v[96:99], v[42:45], v[26:29], 0
	v_mfma_f32_16x16x32_f16 v[100:103], v[50:53], v[0:3], 0
	v_mfma_f32_16x16x32_f16 v[104:107], v[50:53], v[26:29], 0
	v_mfma_f32_16x16x32_f16 v[108:111], v[58:61], v[0:3], 0
	v_mfma_f32_16x16x32_f16 v[112:115], v[58:61], v[26:29], 0
	v_mfma_f32_16x16x32_f16 v[66:69], v[38:41], v[22:25], v[66:69]
	v_mfma_f32_16x16x32_f16 v[76:79], v[38:41], v[30:33], v[76:79]
	v_mfma_f32_16x16x32_f16 v[84:87], v[46:49], v[22:25], v[84:87]
	v_mfma_f32_16x16x32_f16 v[96:99], v[46:49], v[30:33], v[96:99]
	v_mfma_f32_16x16x32_f16 v[100:103], v[54:57], v[22:25], v[100:103]
	v_mfma_f32_16x16x32_f16 v[104:107], v[54:57], v[30:33], v[104:107]
	v_mfma_f32_16x16x32_f16 v[108:111], v[62:65], v[22:25], v[108:111]
	v_mfma_f32_16x16x32_f16 v[112:115], v[62:65], v[30:33], v[112:115]
	s_setprio 0
	s_barrier
	v_readfirstlane_b32 s81, v13
	v_lshl_add_u64 v[70:71], v[4:5], 0, s[92:93]
	s_mov_b32 m0, s81
	v_readfirstlane_b32 s81, v15
	ds_read_b128 v[116:119], v81 offset:16384
	ds_read_b128 v[124:127], v81 offset:17408
	ds_read_b128 v[128:131], v81 offset:18432
	ds_read_b128 v[132:135], v81 offset:19456
	global_load_lds_dwordx4 v[70:71], off
	v_lshl_add_u64 v[12:13], v[4:5], 0, s[66:67]
	s_mov_b32 m0, s81
	s_nop 0
	global_load_lds_dwordx4 v[12:13], off
	s_barrier
	s_waitcnt lgkmcnt(0)
	s_setprio 1
	s_waitcnt lgkmcnt(0)
	v_mfma_f32_16x16x32_f16 v[12:15], v[34:37], v[116:119], 0
	v_mfma_f32_16x16x32_f16 v[34:37], v[34:37], v[128:131], 0
	v_mfma_f32_16x16x32_f16 v[12:15], v[38:41], v[124:127], v[12:15]
	v_mfma_f32_16x16x32_f16 v[34:37], v[38:41], v[132:135], v[34:37]
	v_mfma_f32_16x16x32_f16 v[38:41], v[42:45], v[116:119], 0
	v_mfma_f32_16x16x32_f16 v[42:45], v[42:45], v[128:131], 0
	v_mfma_f32_16x16x32_f16 v[38:41], v[46:49], v[124:127], v[38:41]
	v_mfma_f32_16x16x32_f16 v[42:45], v[46:49], v[132:135], v[42:45]
	v_mfma_f32_16x16x32_f16 v[46:49], v[50:53], v[116:119], 0
	v_mfma_f32_16x16x32_f16 v[50:53], v[50:53], v[128:131], 0
	v_mfma_f32_16x16x32_f16 v[46:49], v[54:57], v[124:127], v[46:49]
	v_mfma_f32_16x16x32_f16 v[50:53], v[54:57], v[132:135], v[50:53]
	v_mfma_f32_16x16x32_f16 v[54:57], v[58:61], v[116:119], 0
	v_mfma_f32_16x16x32_f16 v[58:61], v[58:61], v[128:131], 0
	v_mfma_f32_16x16x32_f16 v[54:57], v[62:65], v[124:127], v[54:57]
	v_mfma_f32_16x16x32_f16 v[58:61], v[62:65], v[132:135], v[58:61]
	s_setprio 0
	v_readfirstlane_b32 s81, v20
	v_lshl_add_u64 v[70:71], v[6:7], 0, s[92:93]
	s_mov_b32 m0, s81
	s_mov_b64 s[68:69], 0x8100
	v_readfirstlane_b32 s81, v21
	s_barrier
	ds_read_b128 v[62:65], v123 offset:16384
	ds_read_b128 v[136:139], v123 offset:17408
	ds_read_b128 v[140:143], v123 offset:18432
	ds_read_b128 v[144:147], v123 offset:19456
	ds_read_b128 v[148:151], v123 offset:20480
	ds_read_b128 v[158:161], v123 offset:21504
	ds_read_b128 v[162:165], v123 offset:22528
	ds_read_b128 v[170:173], v123 offset:23552
	global_load_lds_dwordx4 v[70:71], off
	v_lshl_add_u64 v[70:71], v[6:7], 0, s[68:69]
	s_mov_b32 m0, s81
	s_nop 0
	global_load_lds_dwordx4 v[70:71], off
	s_barrier
;   #define STAGE(P,BASE,LD,br,kt) do{ const HALF* _u=(BASE)+(long)(br)*(((&(LD))==&lda)?lda_u:(LD))+(long)(kt)*G_BK; \
;     for(int _i=0;_i<2;++_i){ \
;       __builtin_amdgcn_global_load_lds((const unsigned*)(_u+(long)_i*(((&(LD))==&lda)?stepa:stepb)+((&(LD))==&lda?oa0:ob0)), \
;         (unsigned*)((char*)(P)+t5*16+_i*8192),16,0,0);}}while(0)
;   #define LDA(dst,b,h) for(int m=0;m<4;++m)for(int k=0;k<2;++k) \
;     dst[m][k]=*reinterpret_cast<const h8*>(la+(((b)*2+(h))*16384+m*2048+k*1024))
;   #define LDB(dst,b,h) for(int n=0;n<2;++n)for(int k=0;k<2;++k) \
;     dst[n][k]=*reinterpret_cast<const h8*>(lb+(((b)*2+(h))*16384+n*2048+k*1024))
;   #define MMA(ai,bj,At,Bt_) do{__builtin_amdgcn_s_setprio(1); \
;     for(int m=0;m<4;++m)for(int n=0;n<2;++n)for(int k=0;k<2;++k) \
;       acc[ai][bj][m][n]=__builtin_amdgcn_mfma_f32_16x16x32_f16(At[m][k],Bt_[n][k],acc[ai][bj][m][n],0,0,0); \
;     __builtin_amdgcn_s_setprio(0);}while(0)
;   #define WAIT_V(n) asm volatile("s_waitcnt vmcnt(" #n ")":::"memory")
;   #define WAIT_L(n) asm volatile("s_waitcnt lgkmcnt(" #n ")":::"memory")
;   #define BAR __builtin_amdgcn_s_barrier()
;   #define SCHED __builtin_amdgcn_sched_barrier(0)
;     ...
;     LDA(At,0,1); STAGE(SA(0,0),A,lda,0,t+2);
;     BAR; WAIT_L(0); MMA(1,0,At,B0); BAR; SCHED;
;     STAGE(SB(0,1),Bt,ldb,G_HALF,t+2);
;     WAIT_V(6); BAR; MMA(1,1,At,B1); BAR;
;     LDB(B0,1,0); SCHED; LDA(At,1,0); STAGE(SA(0,1),A,lda,G_HALF,t+2);
;     WAIT_L(8); BAR; WAIT_L(0); MMA(0,0,At,B0); BAR; SCHED;
;     LDB(B1,1,1); STAGE(SB(1,0),Bt,ldb,0,t+3);
;     BAR; WAIT_L(0); MMA(0,1,At,B1); BAR;
;     LDA(At,1,1); STAGE(SA(1,0),A,lda,0,t+3);
	s_waitcnt lgkmcnt(0)
	s_setprio 1
	s_waitcnt lgkmcnt(0)
	v_mfma_f32_16x16x32_f16 v[186:189], v[62:65], v[0:3], 0
	v_mfma_f32_16x16x32_f16 v[194:197], v[140:143], v[0:3], 0
	v_mfma_f32_16x16x32_f16 v[202:205], v[148:151], v[0:3], 0
	v_mfma_f32_16x16x32_f16 v[0:3], v[162:165], v[0:3], 0
	v_mfma_f32_16x16x32_f16 v[186:189], v[136:139], v[22:25], v[186:189]
	v_mfma_f32_16x16x32_f16 v[194:197], v[144:147], v[22:25], v[194:197]
	v_mfma_f32_16x16x32_f16 v[202:205], v[158:161], v[22:25], v[202:205]
	v_mfma_f32_16x16x32_f16 v[0:3], v[170:173], v[22:25], v[0:3]
	v_mfma_f32_16x16x32_f16 v[20:23], v[162:165], v[26:29], 0
	v_mfma_f32_16x16x32_f16 v[190:193], v[62:65], v[26:29], 0
	v_mfma_f32_16x16x32_f16 v[198:201], v[140:143], v[26:29], 0
	v_mfma_f32_16x16x32_f16 v[206:209], v[148:151], v[26:29], 0
	v_mfma_f32_16x16x32_f16 v[20:23], v[170:173], v[30:33], v[20:23]
	v_mfma_f32_16x16x32_f16 v[190:193], v[136:139], v[30:33], v[190:193]
	v_mfma_f32_16x16x32_f16 v[198:201], v[144:147], v[30:33], v[198:201]
	v_mfma_f32_16x16x32_f16 v[206:209], v[158:161], v[30:33], v[206:209]
	s_setprio 0
	s_barrier
	v_readfirstlane_b32 s81, v18
	v_lshl_add_u64 v[24:25], v[8:9], 0, s[92:93]
	s_mov_b32 m0, s81
	v_readfirstlane_b32 s81, v19
	global_load_lds_dwordx4 v[24:25], off
	v_lshl_add_u64 v[24:25], v[8:9], 0, s[66:67]
	s_mov_b32 m0, s81
	s_nop 0
	global_load_lds_dwordx4 v[24:25], off
	s_waitcnt vmcnt(6)
	s_barrier
	s_setprio 1
	v_mfma_f32_16x16x32_f16 v[24:27], v[62:65], v[116:119], 0
	v_mfma_f32_16x16x32_f16 v[28:31], v[62:65], v[128:131], 0
	v_mfma_f32_16x16x32_f16 v[24:27], v[136:139], v[124:127], v[24:27]
	v_mfma_f32_16x16x32_f16 v[28:31], v[136:139], v[132:135], v[28:31]
	v_mfma_f32_16x16x32_f16 v[62:65], v[140:143], v[116:119], 0
	v_mfma_f32_16x16x32_f16 v[136:139], v[140:143], v[128:131], 0
	v_mfma_f32_16x16x32_f16 v[62:65], v[144:147], v[124:127], v[62:65]
	v_mfma_f32_16x16x32_f16 v[136:139], v[144:147], v[132:135], v[136:139]
	v_mfma_f32_16x16x32_f16 v[140:143], v[148:151], v[116:119], 0
	v_mfma_f32_16x16x32_f16 v[144:147], v[148:151], v[128:131], 0
	v_mfma_f32_16x16x32_f16 v[116:119], v[162:165], v[116:119], 0
	v_mfma_f32_16x16x32_f16 v[140:143], v[158:161], v[124:127], v[140:143]
	v_mfma_f32_16x16x32_f16 v[144:147], v[158:161], v[132:135], v[144:147]
	v_mfma_f32_16x16x32_f16 v[116:119], v[170:173], v[124:127], v[116:119]
	v_mfma_f32_16x16x32_f16 v[124:127], v[162:165], v[128:131], 0
	v_mfma_f32_16x16x32_f16 v[124:127], v[170:173], v[132:135], v[124:127]
	s_setprio 0
	s_barrier
	ds_read_b128 v[128:131], v81 offset:32768
	ds_read_b128 v[132:135], v81 offset:33792
	ds_read_b128 v[148:151], v81 offset:34816
	ds_read_b128 v[158:161], v81 offset:35840
	v_readfirstlane_b32 s81, v16
	v_lshl_add_u64 v[18:19], v[10:11], 0, s[92:93]
	s_mov_b32 m0, s81
	v_readfirstlane_b32 s81, v17
	ds_read_b128 v[162:165], v123 offset:32768
	ds_read_b128 v[170:173], v123 offset:33792
	ds_read_b128 v[210:213], v123 offset:34816
	ds_read_b128 v[214:217], v123 offset:35840
	ds_read_b128 v[218:221], v123 offset:36864
	ds_read_b128 v[222:225], v123 offset:37888
	ds_read_b128 v[226:229], v123 offset:38912
	ds_read_b128 v[230:233], v123 offset:39936
	global_load_lds_dwordx4 v[18:19], off
	v_lshl_add_u64 v[10:11], v[10:11], 0, s[68:69]
	s_mov_b32 m0, s81
	s_nop 0
	global_load_lds_dwordx4 v[10:11], off
	s_waitcnt lgkmcnt(8)
	s_barrier
	s_waitcnt lgkmcnt(0)
	s_setprio 1
	s_waitcnt lgkmcnt(0)
	v_mfma_f32_16x16x32_f16 v[16:19], v[162:165], v[128:131], v[66:69]
	v_mfma_f32_16x16x32_f16 v[66:69], v[162:165], v[148:151], v[76:79]
	v_mfma_f32_16x16x32_f16 v[76:79], v[210:213], v[128:131], v[84:87]
	v_mfma_f32_16x16x32_f16 v[84:87], v[210:213], v[148:151], v[96:99]
	v_mfma_f32_16x16x32_f16 v[96:99], v[218:221], v[128:131], v[100:103]
	v_mfma_f32_16x16x32_f16 v[100:103], v[218:221], v[148:151], v[104:107]
	v_mfma_f32_16x16x32_f16 v[104:107], v[226:229], v[128:131], v[108:111]
	v_mfma_f32_16x16x32_f16 v[108:111], v[226:229], v[148:151], v[112:115]
	v_mfma_f32_16x16x32_f16 v[16:19], v[170:173], v[132:135], v[16:19]
	v_mfma_f32_16x16x32_f16 v[66:69], v[170:173], v[158:161], v[66:69]
	v_mfma_f32_16x16x32_f16 v[76:79], v[214:217], v[132:135], v[76:79]
	v_mfma_f32_16x16x32_f16 v[84:87], v[214:217], v[158:161], v[84:87]
	v_mfma_f32_16x16x32_f16 v[96:99], v[222:225], v[132:135], v[96:99]
	v_mfma_f32_16x16x32_f16 v[100:103], v[222:225], v[158:161], v[100:103]
	v_mfma_f32_16x16x32_f16 v[104:107], v[230:233], v[132:135], v[104:107]
	v_mfma_f32_16x16x32_f16 v[108:111], v[230:233], v[158:161], v[108:111]
	s_setprio 0
	s_barrier
	s_mov_b32 m0, s77
	v_lshl_add_u64 v[10:11], v[4:5], 0, s[42:43]
	ds_read_b128 v[112:115], v81 offset:49152
	ds_read_b128 v[234:237], v81 offset:50176
	ds_read_b128 v[238:241], v81 offset:51200
	ds_read_b128 v[242:245], v81 offset:52224
	global_load_lds_dwordx4 v[10:11], off
	v_lshl_add_u64 v[4:5], v[4:5], 0, s[96:97]
	s_mov_b32 m0, s76
	s_nop 0
	global_load_lds_dwordx4 v[4:5], off
	s_barrier
	s_waitcnt lgkmcnt(0)
	s_setprio 1
	s_waitcnt lgkmcnt(0)
	v_mfma_f32_16x16x32_f16 v[10:13], v[162:165], v[112:115], v[12:15]
	v_mfma_f32_16x16x32_f16 v[32:35], v[162:165], v[238:241], v[34:37]
	v_mfma_f32_16x16x32_f16 v[36:39], v[210:213], v[112:115], v[38:41]
	v_mfma_f32_16x16x32_f16 v[40:43], v[210:213], v[238:241], v[42:45]
	v_mfma_f32_16x16x32_f16 v[44:47], v[218:221], v[112:115], v[46:49]
	v_mfma_f32_16x16x32_f16 v[48:51], v[218:221], v[238:241], v[50:53]
	v_mfma_f32_16x16x32_f16 v[52:55], v[226:229], v[112:115], v[54:57]
	v_mfma_f32_16x16x32_f16 v[56:59], v[226:229], v[238:241], v[58:61]
	v_mfma_f32_16x16x32_f16 v[10:13], v[170:173], v[234:237], v[10:13]
	v_mfma_f32_16x16x32_f16 v[32:35], v[170:173], v[242:245], v[32:35]
	v_mfma_f32_16x16x32_f16 v[36:39], v[214:217], v[234:237], v[36:39]
	v_mfma_f32_16x16x32_f16 v[40:43], v[214:217], v[242:245], v[40:43]
	v_mfma_f32_16x16x32_f16 v[44:47], v[222:225], v[234:237], v[44:47]
	v_mfma_f32_16x16x32_f16 v[48:51], v[222:225], v[242:245], v[48:51]
	v_mfma_f32_16x16x32_f16 v[52:55], v[230:233], v[234:237], v[52:55]
	v_mfma_f32_16x16x32_f16 v[56:59], v[230:233], v[242:245], v[56:59]
	s_setprio 0
	s_mov_b32 m0, s44
	v_lshl_add_u64 v[4:5], v[6:7], 0, s[42:43]
	s_mov_b64 s[68:69], 0x8180
	s_barrier
;   #define STAGE(P,BASE,LD,br,kt) do{ const HALF* _u=(BASE)+(long)(br)*(((&(LD))==&lda)?lda_u:(LD))+(long)(kt)*G_BK; \
;     for(int _i=0;_i<2;++_i){ \
;       __builtin_amdgcn_global_load_lds((const unsigned*)(_u+(long)_i*(((&(LD))==&lda)?stepa:stepb)+((&(LD))==&lda?oa0:ob0)), \
;         (unsigned*)((char*)(P)+t5*16+_i*8192),16,0,0);}}while(0)
;   #define LDA(dst,b,h) for(int m=0;m<4;++m)for(int k=0;k<2;++k) \
;     dst[m][k]=*reinterpret_cast<const h8*>(la+(((b)*2+(h))*16384+m*2048+k*1024))
;   #define LDB(dst,b,h) for(int n=0;n<2;++n)for(int k=0;k<2;++k) \
;     dst[n][k]=*reinterpret_cast<const h8*>(lb+(((b)*2+(h))*16384+n*2048+k*1024))
;   #define MMA(ai,bj,At,Bt_) do{__builtin_amdgcn_s_setprio(1); \
;     for(int m=0;m<4;++m)for(int n=0;n<2;++n)for(int k=0;k<2;++k) \
;       acc[ai][bj][m][n]=__builtin_amdgcn_mfma_f32_16x16x32_f16(At[m][k],Bt_[n][k],acc[ai][bj][m][n],0,0,0); \
;     __builtin_amdgcn_s_setprio(0);}while(0)
;   #define WAIT_V(n) asm volatile("s_waitcnt vmcnt(" #n ")":::"memory")
;   #define WAIT_L(n) asm volatile("s_waitcnt lgkmcnt(" #n ")":::"memory")
;   #define BAR __builtin_amdgcn_s_barrier()
;   #define SCHED __builtin_amdgcn_sched_barrier(0)
;     ...
;     LDA(At,1,1); STAGE(SA(1,0),A,lda,0,t+3);
;     BAR; WAIT_L(0); MMA(1,0,At,B0); BAR; SCHED;
;     STAGE(SB(1,1),Bt,ldb,G_HALF,t+3);
;     WAIT_V(6); BAR; MMA(1,1,At,B1); BAR;
;   }
;   { LDB(B0,0,0); LDA(At,0,0); STAGE(SA(1,1),A,lda,G_HALF,nt-1);
;     BAR; WAIT_L(0); MMA(0,0,At,B0); BAR;
;     LDB(B1,0,1); BAR; WAIT_L(0); MMA(0,1,At,B1); BAR;
	ds_read_b128 v[162:165], v123 offset:49152
	ds_read_b128 v[170:173], v123 offset:50176
	ds_read_b128 v[210:213], v123 offset:51200
	ds_read_b128 v[214:217], v123 offset:52224
	ds_read_b128 v[218:221], v123 offset:53248
	ds_read_b128 v[222:225], v123 offset:54272
	ds_read_b128 v[226:229], v123 offset:55296
	ds_read_b128 v[230:233], v123 offset:56320
	global_load_lds_dwordx4 v[4:5], off
	v_lshl_add_u64 v[4:5], v[6:7], 0, s[68:69]
	s_mov_b32 m0, s22
	s_nop 0
	global_load_lds_dwordx4 v[4:5], off
	s_barrier
	s_waitcnt lgkmcnt(0)
	s_setprio 1
	s_waitcnt lgkmcnt(0)
	v_mfma_f32_16x16x32_f16 v[0:3], v[226:229], v[128:131], v[0:3]
	v_mfma_f32_16x16x32_f16 v[20:23], v[226:229], v[148:151], v[20:23]
	v_mfma_f32_16x16x32_f16 v[186:189], v[162:165], v[128:131], v[186:189]
	v_mfma_f32_16x16x32_f16 v[190:193], v[162:165], v[148:151], v[190:193]
	v_mfma_f32_16x16x32_f16 v[194:197], v[210:213], v[128:131], v[194:197]
	v_mfma_f32_16x16x32_f16 v[198:201], v[210:213], v[148:151], v[198:201]
	v_mfma_f32_16x16x32_f16 v[202:205], v[218:221], v[128:131], v[202:205]
	v_mfma_f32_16x16x32_f16 v[206:209], v[218:221], v[148:151], v[206:209]
	v_mfma_f32_16x16x32_f16 v[0:3], v[230:233], v[132:135], v[0:3]
	v_mfma_f32_16x16x32_f16 v[20:23], v[230:233], v[158:161], v[20:23]
	v_mfma_f32_16x16x32_f16 v[186:189], v[170:173], v[132:135], v[186:189]
	v_mfma_f32_16x16x32_f16 v[190:193], v[170:173], v[158:161], v[190:193]
	v_mfma_f32_16x16x32_f16 v[194:197], v[214:217], v[132:135], v[194:197]
	v_mfma_f32_16x16x32_f16 v[198:201], v[214:217], v[158:161], v[198:201]
	v_mfma_f32_16x16x32_f16 v[202:205], v[222:225], v[132:135], v[202:205]
	v_mfma_f32_16x16x32_f16 v[206:209], v[222:225], v[158:161], v[206:209]
	s_setprio 0
	s_barrier
	s_mov_b32 m0, s13
	v_lshl_add_u64 v[4:5], v[8:9], 0, s[42:43]
	global_load_lds_dwordx4 v[4:5], off
	v_lshl_add_u64 v[4:5], v[8:9], 0, s[96:97]
	s_mov_b32 m0, s12
	s_nop 0
	global_load_lds_dwordx4 v[4:5], off
	s_waitcnt vmcnt(6)
	s_barrier
	s_setprio 1
	v_mfma_f32_16x16x32_f16 v[24:27], v[162:165], v[112:115], v[24:27]
	v_mfma_f32_16x16x32_f16 v[28:31], v[162:165], v[238:241], v[28:31]
	v_mfma_f32_16x16x32_f16 v[60:63], v[210:213], v[112:115], v[62:65]
	v_mfma_f32_16x16x32_f16 v[128:131], v[210:213], v[238:241], v[136:139]
	v_mfma_f32_16x16x32_f16 v[132:135], v[218:221], v[112:115], v[140:143]
	v_mfma_f32_16x16x32_f16 v[136:139], v[218:221], v[238:241], v[144:147]
	v_mfma_f32_16x16x32_f16 v[112:115], v[226:229], v[112:115], v[116:119]
	v_mfma_f32_16x16x32_f16 v[116:119], v[226:229], v[238:241], v[124:127]
	v_mfma_f32_16x16x32_f16 v[24:27], v[170:173], v[234:237], v[24:27]
	v_mfma_f32_16x16x32_f16 v[28:31], v[170:173], v[242:245], v[28:31]
	v_mfma_f32_16x16x32_f16 v[60:63], v[214:217], v[234:237], v[60:63]
	v_mfma_f32_16x16x32_f16 v[128:131], v[214:217], v[242:245], v[128:131]
	v_mfma_f32_16x16x32_f16 v[132:135], v[222:225], v[234:237], v[132:135]
	v_mfma_f32_16x16x32_f16 v[136:139], v[222:225], v[242:245], v[136:139]
	v_mfma_f32_16x16x32_f16 v[112:115], v[230:233], v[234:237], v[112:115]
	v_mfma_f32_16x16x32_f16 v[116:119], v[230:233], v[242:245], v[116:119]
	s_setprio 0
	s_mov_b64 s[12:13], 0x10180
	s_mov_b32 m0, s80
	v_lshl_add_u64 v[4:5], v[6:7], 0, s[12:13]
	s_mov_b64 s[12:13], 0x18180
	s_barrier
	ds_read_b128 v[124:127], v81
	ds_read_b128 v[140:143], v81 offset:1024
	ds_read_b128 v[144:147], v81 offset:2048
	ds_read_b128 v[148:151], v81 offset:3072
	ds_read_b128 v[158:161], v123
	ds_read_b128 v[162:165], v123 offset:1024
	ds_read_b128 v[170:173], v123 offset:2048
	ds_read_b128 v[210:213], v123 offset:3072
	ds_read_b128 v[214:217], v123 offset:4096
	ds_read_b128 v[218:221], v123 offset:5120
	ds_read_b128 v[222:225], v123 offset:6144
	ds_read_b128 v[226:229], v123 offset:7168
	global_load_lds_dwordx4 v[4:5], off
	v_lshl_add_u64 v[4:5], v[6:7], 0, s[12:13]
	s_mov_b32 m0, s71
	s_nop 0
	global_load_lds_dwordx4 v[4:5], off
	s_barrier
	s_waitcnt lgkmcnt(0)
	s_setprio 1
	s_waitcnt lgkmcnt(0)
	v_mfma_f32_16x16x32_f16 v[4:7], v[158:161], v[124:127], v[16:19]
	v_mfma_f32_16x16x32_f16 v[14:17], v[158:161], v[144:147], v[66:69]
	v_mfma_f32_16x16x32_f16 v[64:67], v[170:173], v[124:127], v[76:79]
	v_mfma_f32_16x16x32_f16 v[68:71], v[170:173], v[144:147], v[84:87]
	v_mfma_f32_16x16x32_f16 v[76:79], v[214:217], v[124:127], v[96:99]
	v_mfma_f32_16x16x32_f16 v[84:87], v[214:217], v[144:147], v[100:103]
	v_mfma_f32_16x16x32_f16 v[96:99], v[222:225], v[124:127], v[104:107]
	v_mfma_f32_16x16x32_f16 v[100:103], v[222:225], v[144:147], v[108:111]
	v_mfma_f32_16x16x32_f16 v[4:7], v[162:165], v[140:143], v[4:7]
	v_mfma_f32_16x16x32_f16 v[14:17], v[162:165], v[148:151], v[14:17]
	v_mfma_f32_16x16x32_f16 v[64:67], v[210:213], v[140:143], v[64:67]
	v_mfma_f32_16x16x32_f16 v[68:71], v[210:213], v[148:151], v[68:71]
	v_mfma_f32_16x16x32_f16 v[76:79], v[218:221], v[140:143], v[76:79]
	v_mfma_f32_16x16x32_f16 v[84:87], v[218:221], v[148:151], v[84:87]
	v_mfma_f32_16x16x32_f16 v[96:99], v[226:229], v[140:143], v[96:99]
	v_mfma_f32_16x16x32_f16 v[100:103], v[226:229], v[148:151], v[100:103]
	s_setprio 0
	s_barrier
	ds_read_b128 v[104:107], v81 offset:16384
	ds_read_b128 v[108:111], v81 offset:17408
	ds_read_b128 v[230:233], v81 offset:18432
	ds_read_b128 v[234:237], v81 offset:19456
	s_barrier
;   #define LDA(dst,b,h) for(int m=0;m<4;++m)for(int k=0;k<2;++k) \
;     dst[m][k]=*reinterpret_cast<const h8*>(la+(((b)*2+(h))*16384+m*2048+k*1024))
;   #define LDB(dst,b,h) for(int n=0;n<2;++n)for(int k=0;k<2;++k) \
;     dst[n][k]=*reinterpret_cast<const h8*>(lb+(((b)*2+(h))*16384+n*2048+k*1024))
;   #define MMA(ai,bj,At,Bt_) do{__builtin_amdgcn_s_setprio(1); \
;     for(int m=0;m<4;++m)for(int n=0;n<2;++n)for(int k=0;k<2;++k) \
;       acc[ai][bj][m][n]=__builtin_amdgcn_mfma_f32_16x16x32_f16(At[m][k],Bt_[n][k],acc[ai][bj][m][n],0,0,0); \
;     __builtin_amdgcn_s_setprio(0);}while(0)
;   #define WAIT_V(n) asm volatile("s_waitcnt vmcnt(" #n ")":::"memory")
;   #define WAIT_L(n) asm volatile("s_waitcnt lgkmcnt(" #n ")":::"memory")
;   #define BAR __builtin_amdgcn_s_barrier()
;     ...
;     LDB(B1,0,1); BAR; WAIT_L(0); MMA(0,1,At,B1); BAR;
;     LDA(At,0,1); WAIT_V(4); BAR; WAIT_L(0); MMA(1,0,At,B0); MMA(1,1,At,B1); BAR; }
;   { LDB(B0,1,0); LDA(At,1,0); WAIT_V(2); BAR; WAIT_L(0); MMA(0,0,At,B0); BAR;
	s_waitcnt lgkmcnt(0)
	s_setprio 1
	s_waitcnt lgkmcnt(0)
	v_mfma_f32_16x16x32_f16 v[8:11], v[158:161], v[104:107], v[10:13]
	v_mfma_f32_16x16x32_f16 v[238:241], v[162:165], v[108:111], v[8:11]
	v_mfma_f32_16x16x32_f16 v[8:11], v[158:161], v[230:233], v[32:35]
	v_mfma_f32_16x16x32_f16 v[32:35], v[162:165], v[234:237], v[8:11]
	v_mfma_f32_16x16x32_f16 v[8:11], v[170:173], v[104:107], v[36:39]
	v_mfma_f32_16x16x32_f16 v[158:161], v[210:213], v[108:111], v[8:11]
	v_mfma_f32_16x16x32_f16 v[8:11], v[170:173], v[230:233], v[40:43]
	v_mfma_f32_16x16x32_f16 v[40:43], v[210:213], v[234:237], v[8:11]
	v_mfma_f32_16x16x32_f16 v[8:11], v[214:217], v[104:107], v[44:47]
	v_mfma_f32_16x16x32_f16 v[162:165], v[218:221], v[108:111], v[8:11]
	v_mfma_f32_16x16x32_f16 v[8:11], v[214:217], v[230:233], v[48:51]
	v_mfma_f32_16x16x32_f16 v[48:51], v[218:221], v[234:237], v[8:11]
	v_mfma_f32_16x16x32_f16 v[8:11], v[222:225], v[104:107], v[52:55]
	v_mfma_f32_16x16x32_f16 v[170:173], v[226:229], v[108:111], v[8:11]
	v_mfma_f32_16x16x32_f16 v[8:11], v[222:225], v[230:233], v[56:59]
	v_mfma_f32_16x16x32_f16 v[56:59], v[226:229], v[234:237], v[8:11]
	s_setprio 0
	s_barrier
	s_nop 4
	ds_read_b128 v[8:11], v123 offset:16384
	ds_read_b128 v[36:39], v123 offset:17408
	ds_read_b128 v[44:47], v123 offset:18432
	ds_read_b128 v[52:55], v123 offset:19456
	ds_read_b128 v[210:213], v123 offset:20480
	ds_read_b128 v[214:217], v123 offset:21504
	ds_read_b128 v[218:221], v123 offset:22528
	ds_read_b128 v[222:225], v123 offset:23552
	s_waitcnt vmcnt(4)
	s_barrier
	s_waitcnt lgkmcnt(0)
	s_setprio 1
	s_waitcnt lgkmcnt(0)
	v_mfma_f32_16x16x32_f16 v[0:3], v[218:221], v[124:127], v[0:3]
	v_mfma_f32_16x16x32_f16 v[186:189], v[8:11], v[124:127], v[186:189]
	v_mfma_f32_16x16x32_f16 v[194:197], v[44:47], v[124:127], v[194:197]
	v_mfma_f32_16x16x32_f16 v[202:205], v[210:213], v[124:127], v[202:205]
	v_mfma_f32_16x16x32_f16 v[124:127], v[222:225], v[140:143], v[0:3]
	v_mfma_f32_16x16x32_f16 v[0:3], v[218:221], v[144:147], v[20:23]
	v_mfma_f32_16x16x32_f16 v[186:189], v[36:39], v[140:143], v[186:189]
	v_mfma_f32_16x16x32_f16 v[190:193], v[8:11], v[144:147], v[190:193]
	v_mfma_f32_16x16x32_f16 v[194:197], v[52:55], v[140:143], v[194:197]
	v_mfma_f32_16x16x32_f16 v[198:201], v[44:47], v[144:147], v[198:201]
	v_mfma_f32_16x16x32_f16 v[202:205], v[214:217], v[140:143], v[202:205]
	v_mfma_f32_16x16x32_f16 v[206:209], v[210:213], v[144:147], v[206:209]
	v_mfma_f32_16x16x32_f16 v[140:143], v[222:225], v[148:151], v[0:3]
	v_mfma_f32_16x16x32_f16 v[190:193], v[36:39], v[148:151], v[190:193]
	v_mfma_f32_16x16x32_f16 v[198:201], v[52:55], v[148:151], v[198:201]
	v_mfma_f32_16x16x32_f16 v[206:209], v[214:217], v[148:151], v[206:209]
	s_setprio 0
	s_setprio 1
	v_mfma_f32_16x16x32_f16 v[0:3], v[8:11], v[104:107], v[24:27]
	v_mfma_f32_16x16x32_f16 v[144:147], v[36:39], v[108:111], v[0:3]
	v_mfma_f32_16x16x32_f16 v[0:3], v[8:11], v[230:233], v[28:31]
	v_mfma_f32_16x16x32_f16 v[148:151], v[36:39], v[234:237], v[0:3]
	v_mfma_f32_16x16x32_f16 v[0:3], v[44:47], v[104:107], v[60:63]
	v_mfma_f32_16x16x32_f16 v[226:229], v[52:55], v[108:111], v[0:3]
	v_mfma_f32_16x16x32_f16 v[0:3], v[44:47], v[230:233], v[128:131]
	v_mfma_f32_16x16x32_f16 v[242:245], v[52:55], v[234:237], v[0:3]
	v_mfma_f32_16x16x32_f16 v[0:3], v[210:213], v[104:107], v[132:135]
	v_mfma_f32_16x16x32_f16 v[246:249], v[214:217], v[108:111], v[0:3]
	v_mfma_f32_16x16x32_f16 v[0:3], v[210:213], v[230:233], v[136:139]
	v_mfma_f32_16x16x32_f16 v[136:139], v[214:217], v[234:237], v[0:3]
	v_mfma_f32_16x16x32_f16 v[0:3], v[218:221], v[104:107], v[112:115]
	v_mfma_f32_16x16x32_f16 v[210:213], v[222:225], v[108:111], v[0:3]
	v_mfma_f32_16x16x32_f16 v[0:3], v[218:221], v[230:233], v[116:119]
	v_mfma_f32_16x16x32_f16 v[214:217], v[222:225], v[234:237], v[0:3]
	s_setprio 0
	s_barrier
	ds_read_b128 v[108:111], v81 offset:32768
	ds_read_b128 v[112:115], v81 offset:33792
	ds_read_b128 v[116:119], v81 offset:34816
	ds_read_b128 v[128:131], v81 offset:35840
	ds_read_b128 v[36:39], v123 offset:32768
	ds_read_b128 v[44:47], v123 offset:33792
	ds_read_b128 v[52:55], v123 offset:34816
	ds_read_b128 v[60:63], v123 offset:35840
	ds_read_b128 v[104:107], v123 offset:36864
	ds_read_b128 v[132:135], v123 offset:37888
	ds_read_b128 v[218:221], v123 offset:38912
	ds_read_b128 v[222:225], v123 offset:39936
	s_waitcnt vmcnt(2)
	s_barrier
;   #define LDA(dst,b,h) for(int m=0;m<4;++m)for(int k=0;k<2;++k) \
;     dst[m][k]=*reinterpret_cast<const h8*>(la+(((b)*2+(h))*16384+m*2048+k*1024))
;   #define LDB(dst,b,h) for(int n=0;n<2;++n)for(int k=0;k<2;++k) \
;     dst[n][k]=*reinterpret_cast<const h8*>(lb+(((b)*2+(h))*16384+n*2048+k*1024))
;   #define MMA(ai,bj,At,Bt_) do{__builtin_amdgcn_s_setprio(1); \
;     for(int m=0;m<4;++m)for(int n=0;n<2;++n)for(int k=0;k<2;++k) \
;       acc[ai][bj][m][n]=__builtin_amdgcn_mfma_f32_16x16x32_f16(At[m][k],Bt_[n][k],acc[ai][bj][m][n],0,0,0); \
;     __builtin_amdgcn_s_setprio(0);}while(0)
;   #define WAIT_V(n) asm volatile("s_waitcnt vmcnt(" #n ")":::"memory")
;   #define WAIT_L(n) asm volatile("s_waitcnt lgkmcnt(" #n ")":::"memory")
;   #define BAR __builtin_amdgcn_s_barrier()
;     ...
;   { LDB(B0,1,0); LDA(At,1,0); WAIT_V(2); BAR; WAIT_L(0); MMA(0,0,At,B0); BAR;
;     LDB(B1,1,1); WAIT_V(0); BAR; WAIT_L(0); MMA(0,1,At,B1); BAR;
;     LDA(At,1,1); BAR; WAIT_L(0); MMA(1,0,At,B0); MMA(1,1,At,B1); BAR; }
;   if(wr==0)BAR;
	s_waitcnt lgkmcnt(0)
	s_setprio 1
	s_waitcnt lgkmcnt(0)
	v_mfma_f32_16x16x32_f16 v[0:3], v[36:39], v[108:111], v[4:7]
	v_mfma_f32_16x16x32_f16 v[4:7], v[36:39], v[116:119], v[14:17]
	v_mfma_f32_16x16x32_f16 v[8:11], v[52:55], v[108:111], v[64:67]
	v_mfma_f32_16x16x32_f16 v[12:15], v[52:55], v[116:119], v[68:71]
	v_mfma_f32_16x16x32_f16 v[16:19], v[104:107], v[108:111], v[76:79]
	v_mfma_f32_16x16x32_f16 v[20:23], v[104:107], v[116:119], v[84:87]
	v_mfma_f32_16x16x32_f16 v[24:27], v[218:221], v[108:111], v[96:99]
	v_mfma_f32_16x16x32_f16 v[28:31], v[218:221], v[116:119], v[100:103]
	v_mfma_f32_16x16x32_f16 v[0:3], v[44:47], v[112:115], v[0:3]
	v_mfma_f32_16x16x32_f16 v[4:7], v[44:47], v[128:131], v[4:7]
	v_mfma_f32_16x16x32_f16 v[8:11], v[60:63], v[112:115], v[8:11]
	v_mfma_f32_16x16x32_f16 v[12:15], v[60:63], v[128:131], v[12:15]
	v_mfma_f32_16x16x32_f16 v[16:19], v[132:135], v[112:115], v[16:19]
	v_mfma_f32_16x16x32_f16 v[20:23], v[132:135], v[128:131], v[20:23]
	v_mfma_f32_16x16x32_f16 v[24:27], v[222:225], v[112:115], v[24:27]
	v_mfma_f32_16x16x32_f16 v[28:31], v[222:225], v[128:131], v[28:31]
	s_setprio 0
	s_barrier
	ds_read_b128 v[230:233], v81 offset:49152
	ds_read_b128 v[234:237], v81 offset:50176
	ds_read_b128 v[250:253], v81 offset:51200
	ds_read_b128 v[176:179], v81 offset:52224
	s_waitcnt vmcnt(0)
	s_barrier
	s_waitcnt lgkmcnt(0)
	s_setprio 1
	s_waitcnt lgkmcnt(0)
	v_mfma_f32_16x16x32_f16 v[32:35], v[36:39], v[250:253], v[32:35]
	v_mfma_f32_16x16x32_f16 v[64:67], v[36:39], v[230:233], v[238:241]
	v_mfma_f32_16x16x32_f16 v[36:39], v[44:47], v[176:179], v[32:35]
	v_mfma_f32_16x16x32_f16 v[32:35], v[52:55], v[230:233], v[158:161]
	v_mfma_f32_16x16x32_f16 v[68:71], v[60:63], v[234:237], v[32:35]
	v_mfma_f32_16x16x32_f16 v[32:35], v[52:55], v[250:253], v[40:43]
	v_mfma_f32_16x16x32_f16 v[64:67], v[44:47], v[234:237], v[64:67]
	v_mfma_f32_16x16x32_f16 v[44:47], v[60:63], v[176:179], v[32:35]
	v_mfma_f32_16x16x32_f16 v[32:35], v[104:107], v[230:233], v[162:165]
	v_mfma_f32_16x16x32_f16 v[96:99], v[132:135], v[234:237], v[32:35]
	v_mfma_f32_16x16x32_f16 v[32:35], v[104:107], v[250:253], v[48:51]
	v_mfma_f32_16x16x32_f16 v[52:55], v[132:135], v[176:179], v[32:35]
	v_mfma_f32_16x16x32_f16 v[32:35], v[218:221], v[230:233], v[170:173]
	v_mfma_f32_16x16x32_f16 v[100:103], v[222:225], v[234:237], v[32:35]
	v_mfma_f32_16x16x32_f16 v[32:35], v[218:221], v[250:253], v[56:59]
	v_mfma_f32_16x16x32_f16 v[60:63], v[222:225], v[176:179], v[32:35]
	s_setprio 0
	s_barrier
	ds_read_b128 v[132:135], v123 offset:49152
	ds_read_b128 v[158:161], v123 offset:50176
	ds_read_b128 v[162:165], v123 offset:51200
	ds_read_b128 v[170:173], v123 offset:52224
	ds_read_b128 v[218:221], v123 offset:53248
	ds_read_b128 v[222:225], v123 offset:54272
	ds_read_b128 v[238:241], v123 offset:55296
	ds_read_b128 v[166:169], v123 offset:56320
	s_barrier
	s_waitcnt lgkmcnt(0)
	s_setprio 1
	s_waitcnt lgkmcnt(0)
	v_mfma_f32_16x16x32_f16 v[32:35], v[132:135], v[108:111], v[186:189]
	v_mfma_f32_16x16x32_f16 v[40:43], v[162:165], v[108:111], v[194:197]
	v_mfma_f32_16x16x32_f16 v[76:79], v[218:221], v[108:111], v[202:205]
	v_mfma_f32_16x16x32_f16 v[84:87], v[238:241], v[108:111], v[124:127]
	v_mfma_f32_16x16x32_f16 v[48:51], v[158:161], v[112:115], v[32:35]
	v_mfma_f32_16x16x32_f16 v[32:35], v[132:135], v[116:119], v[190:193]
	v_mfma_f32_16x16x32_f16 v[56:59], v[170:173], v[112:115], v[40:43]
	v_mfma_f32_16x16x32_f16 v[40:43], v[162:165], v[116:119], v[198:201]
	v_mfma_f32_16x16x32_f16 v[104:107], v[222:225], v[112:115], v[76:79]
	v_mfma_f32_16x16x32_f16 v[76:79], v[218:221], v[116:119], v[206:209]
	v_mfma_f32_16x16x32_f16 v[112:115], v[166:169], v[112:115], v[84:87]
	v_mfma_f32_16x16x32_f16 v[84:87], v[238:241], v[116:119], v[140:143]
	v_mfma_f32_16x16x32_f16 v[32:35], v[158:161], v[128:131], v[32:35]
	v_mfma_f32_16x16x32_f16 v[40:43], v[170:173], v[128:131], v[40:43]
	v_mfma_f32_16x16x32_f16 v[76:79], v[222:225], v[128:131], v[76:79]
	v_mfma_f32_16x16x32_f16 v[84:87], v[166:169], v[128:131], v[84:87]
	s_setprio 0
	s_setprio 1
	v_mfma_f32_16x16x32_f16 v[124:127], v[162:165], v[250:253], v[242:245]
	v_mfma_f32_16x16x32_f16 v[108:111], v[132:135], v[230:233], v[144:147]
	v_mfma_f32_16x16x32_f16 v[116:119], v[132:135], v[250:253], v[148:151]
	v_mfma_f32_16x16x32_f16 v[132:135], v[170:173], v[176:179], v[124:127]
	v_mfma_f32_16x16x32_f16 v[124:127], v[218:221], v[230:233], v[246:249]
	v_mfma_f32_16x16x32_f16 v[144:147], v[222:225], v[234:237], v[124:127]
	v_mfma_f32_16x16x32_f16 v[124:127], v[218:221], v[250:253], v[136:139]
	v_mfma_f32_16x16x32_f16 v[136:139], v[222:225], v[176:179], v[124:127]
	v_mfma_f32_16x16x32_f16 v[124:127], v[238:241], v[230:233], v[210:213]
	v_mfma_f32_16x16x32_f16 v[128:131], v[158:161], v[176:179], v[116:119]
	v_mfma_f32_16x16x32_f16 v[116:119], v[162:165], v[230:233], v[226:229]
	v_mfma_f32_16x16x32_f16 v[148:151], v[166:169], v[234:237], v[124:127]
	v_mfma_f32_16x16x32_f16 v[124:127], v[238:241], v[250:253], v[214:217]
	v_mfma_f32_16x16x32_f16 v[108:111], v[158:161], v[234:237], v[108:111]
	v_mfma_f32_16x16x32_f16 v[116:119], v[170:173], v[234:237], v[116:119]
	v_mfma_f32_16x16x32_f16 v[140:143], v[166:169], v[176:179], v[124:127]
	s_setprio 0
	s_movk_i32 s12, 0x100
	v_cmp_gt_u32_e32 vcc, s12, v122
	s_barrier
	s_and_saveexec_b64 s[12:13], vcc
	s_cbranch_execz .LBB0_481
	s_barrier

;   #define STAGE(P,BASE,LD,br,kt) do{ const HALF* _u=(BASE)+(long)(br)*(((&(LD))==&lda)?lda_u:(LD))+(long)(kt)*G_BK; \
;     for(int _i=0;_i<2;++_i){ \
;       __builtin_amdgcn_global_load_lds((const unsigned*)(_u+(long)_i*(((&(LD))==&lda)?stepa:stepb)+((&(LD))==&lda?oa0:ob0)), \
;         (unsigned*)((char*)(P)+t5*16+_i*8192),16,0,0);}}while(0)
;   #define WAIT_V(n) asm volatile("s_waitcnt vmcnt(" #n ")":::"memory")
;   #define BAR __builtin_amdgcn_s_barrier()
; #define FOR_AI _Pragma("unroll") for (int ai = 0; ai < 2; ++ai)
; #define FOR_BJ _Pragma("unroll") for (int bj = 0; bj < 2; ++bj)
; #define FOR_M4 _Pragma("unroll") for (int m = 0; m < 4; ++m)
; #define FOR_NN _Pragma("unroll") for (int n = 0; n < 2; ++n)
;     ...
;   {int _b=t5*16;int _r,_c;g_stage_rc(_b,_r,_c);
;     oa0=n2 ? (unsigned)((n2*(_r&63)+(_r>>6))*1024+_c) : (unsigned)(_r*lda+_c); ob0=(unsigned)(_r*ldb+_c);}
;   STAGE(SB(0,0),Bt,ldb,0,0); STAGE(SA(0,0),A,lda,0,0);
;   STAGE(SB(0,1),Bt,ldb,G_HALF,0); STAGE(SA(0,1),A,lda,G_HALF,0);
;   if(wr==1)BAR;
;   WAIT_V(4); BAR;
;   STAGE(SB(1,0),Bt,ldb,0,1); STAGE(SA(1,0),A,lda,0,1); STAGE(SB(1,1),Bt,ldb,G_HALF,1);
;   WAIT_V(6); BAR;
; __device__ void job_retout_g(const P& p, int l, int job, HALF* sm) {
;     ...
;     FOR_BJ FOR_NN {
;       const int i = bj * 128 + wc * 32 + n * 16 + fr;
;       const float sc = expf(lgf * (float)(i + 1) - lgb * (float)(256 - i));
;       FOR_AI FOR_M4 { acc[ai][bj][m][n] *= sc; }
;     }
.LBB0_483:
	s_or_b64 exec, exec, s[10:11]
	v_pk_mul_f32 v[74:75], v[26:27], v[120:121] op_sel_hi:[1,0]
	v_pk_mul_f32 v[26:27], v[50:51], v[120:121] op_sel_hi:[1,0]
	v_pk_mul_f32 v[50:51], v[42:43], v[170:171] op_sel_hi:[1,0]
	v_pk_mul_f32 v[42:43], v[78:79], v[170:171] op_sel_hi:[1,0]
	v_pk_mul_f32 v[78:79], v[70:71], v[172:173] op_sel_hi:[1,0]
	v_pk_mul_f32 v[70:71], v[98:99], v[172:173] op_sel_hi:[1,0]
	v_pk_mul_f32 v[98:99], v[62:63], v[168:169] op_sel_hi:[1,0]
	v_pk_mul_f32 v[62:63], v[130:131], v[168:169] op_sel_hi:[1,0]
	v_lshlrev_b32_e32 v130, 6, v157
	v_lshlrev_b32_e32 v131, 2, v157
	v_pk_mul_f32 v[72:73], v[24:25], v[120:121] op_sel_hi:[1,0]
	v_pk_mul_f32 v[24:25], v[48:49], v[120:121] op_sel_hi:[1,0]
	v_pk_mul_f32 v[48:49], v[40:41], v[170:171] op_sel_hi:[1,0]
	v_pk_mul_f32 v[40:41], v[76:77], v[170:171] op_sel_hi:[1,0]
	v_pk_mul_f32 v[76:77], v[68:69], v[172:173] op_sel_hi:[1,0]
	v_pk_mul_f32 v[68:69], v[96:97], v[172:173] op_sel_hi:[1,0]
	v_pk_mul_f32 v[96:97], v[60:61], v[168:169] op_sel_hi:[1,0]
	v_pk_mul_f32 v[60:61], v[128:129], v[168:169] op_sel_hi:[1,0]
	v_and_b32_e32 v128, 48, v157
	v_and_b32_e32 v129, 0x3c0, v130
	v_and_b32_e32 v131, 32, v131
	v_bitop3_b32 v128, v129, v131, v128 bitop3:0x36
	v_add_u32_e32 v131, s29, v194
	v_pk_mul_f32 v[80:81], v[16:17], v[120:121] op_sel_hi:[1,0]
	v_readfirstlane_b32 s13, v131
	v_add_u32_e32 v131, 0x2000, v131
	v_pk_mul_f32 v[16:17], v[56:57], v[120:121] op_sel_hi:[1,0]
	v_pk_mul_f32 v[56:57], v[32:33], v[170:171] op_sel_hi:[1,0]
	v_pk_mul_f32 v[32:33], v[84:85], v[170:171] op_sel_hi:[1,0]
	v_pk_mul_f32 v[84:85], v[64:65], v[172:173] op_sel_hi:[1,0]
	v_pk_mul_f32 v[64:65], v[100:101], v[172:173] op_sel_hi:[1,0]
	v_pk_mul_f32 v[100:101], v[52:53], v[168:169] op_sel_hi:[1,0]
	v_pk_mul_f32 v[52:53], v[132:133], v[168:169] op_sel_hi:[1,0]
	v_lshl_add_u64 v[132:133], v[164:165], 0, s[84:85]
	s_mov_b32 m0, s13
	s_mov_b64 s[10:11], 0x20080
	v_readfirstlane_b32 s12, v131
	v_add_u32_e32 v131, 0x8000, v190
	global_load_lds_dwordx4 v[132:133], off
	v_lshl_add_u64 v[132:133], v[164:165], 0, s[10:11]
	s_mov_b32 m0, s12
	v_readfirstlane_b32 s11, v131
	v_add_u32_e32 v131, 0xa000, v190
	global_load_lds_dwordx4 v[132:133], off
	v_lshl_add_u64 v[132:133], v[160:161], 0, s[84:85]
	s_mov_b32 m0, s11
	s_mov_b64 s[20:21], 0x8080
	v_readfirstlane_b32 s10, v131
	global_load_lds_dwordx4 v[132:133], off
	v_lshl_add_u64 v[132:133], v[160:161], 0, s[20:21]
	s_mov_b32 m0, s10
	v_add_u32_e32 v131, s62, v194
	global_load_lds_dwordx4 v[132:133], off
	v_lshl_add_u64 v[132:133], v[152:153], 1, s[6:7]
	v_readfirstlane_b32 s7, v131
	v_add_u32_e32 v131, 0x2000, v131
	s_mov_b32 m0, s7
	v_readfirstlane_b32 s6, v131
	global_load_lds_dwordx4 v[132:133], off
	v_lshl_add_u64 v[132:133], v[132:133], 0, s[18:19]
	s_mov_b32 m0, s6
	v_and_b32_e32 v130, 0x3000, v130
	global_load_lds_dwordx4 v[132:133], off
	v_lshlrev_b32_e32 v129, 13, v159
	v_add3_u32 v152, s95, v130, v128
	v_pk_mul_f32 v[94:95], v[2:3], v[120:121] op_sel_hi:[1,0]
	v_pk_mul_f32 v[92:93], v[0:1], v[120:121] op_sel_hi:[1,0]
	v_pk_mul_f32 v[90:91], v[10:11], v[120:121] op_sel_hi:[1,0]
	v_pk_mul_f32 v[88:89], v[8:9], v[120:121] op_sel_hi:[1,0]
	v_pk_mul_f32 v[82:83], v[18:19], v[120:121] op_sel_hi:[1,0]
	v_pk_mul_f32 v[18:19], v[58:59], v[120:121] op_sel_hi:[1,0]
	v_pk_mul_f32 v[10:11], v[106:107], v[120:121] op_sel_hi:[1,0]
	v_pk_mul_f32 v[8:9], v[104:105], v[120:121] op_sel_hi:[1,0]
	v_pk_mul_f32 v[2:3], v[114:115], v[120:121] op_sel_hi:[1,0]
	v_pk_mul_f32 v[0:1], v[112:113], v[120:121] op_sel_hi:[1,0]
	v_pk_mul_f32 v[114:115], v[22:23], v[170:171] op_sel_hi:[1,0]
	v_pk_mul_f32 v[112:113], v[20:21], v[170:171] op_sel_hi:[1,0]
	v_pk_mul_f32 v[106:107], v[30:31], v[170:171] op_sel_hi:[1,0]
	v_pk_mul_f32 v[104:105], v[28:29], v[170:171] op_sel_hi:[1,0]
	v_pk_mul_f32 v[58:59], v[34:35], v[170:171] op_sel_hi:[1,0]
	v_pk_mul_f32 v[34:35], v[86:87], v[170:171] op_sel_hi:[1,0]
	v_pk_mul_f32 v[86:87], v[66:67], v[172:173] op_sel_hi:[1,0]
	v_pk_mul_f32 v[66:67], v[102:103], v[172:173] op_sel_hi:[1,0]
	v_pk_mul_f32 v[30:31], v[110:111], v[172:173] op_sel_hi:[1,0]
	v_pk_mul_f32 v[28:29], v[108:109], v[172:173] op_sel_hi:[1,0]
	v_pk_mul_f32 v[22:23], v[118:119], v[172:173] op_sel_hi:[1,0]
	v_pk_mul_f32 v[20:21], v[116:117], v[172:173] op_sel_hi:[1,0]
	v_pk_mul_f32 v[118:119], v[38:39], v[168:169] op_sel_hi:[1,0]
	v_pk_mul_f32 v[116:117], v[36:37], v[168:169] op_sel_hi:[1,0]
	v_pk_mul_f32 v[110:111], v[46:47], v[168:169] op_sel_hi:[1,0]
	v_pk_mul_f32 v[108:109], v[44:45], v[168:169] op_sel_hi:[1,0]
	v_pk_mul_f32 v[102:103], v[54:55], v[168:169] op_sel_hi:[1,0]
	v_pk_mul_f32 v[54:55], v[134:135], v[168:169] op_sel_hi:[1,0]
	v_pk_mul_f32 v[46:47], v[138:139], v[168:169] op_sel_hi:[1,0]
	v_pk_mul_f32 v[44:45], v[136:137], v[168:169] op_sel_hi:[1,0]
	v_pk_mul_f32 v[38:39], v[142:143], v[168:169] op_sel_hi:[1,0]
	v_pk_mul_f32 v[36:37], v[140:141], v[168:169] op_sel_hi:[1,0]
	s_waitcnt vmcnt(10)
	s_barrier
	s_waitcnt vmcnt(6)
	s_barrier
;   #define STAGE(P,BASE,LD,br,kt) do{ const HALF* _u=(BASE)+(long)(br)*(((&(LD))==&lda)?lda_u:(LD))+(long)(kt)*G_BK; \
;     for(int _i=0;_i<2;++_i){ \
;       __builtin_amdgcn_global_load_lds((const unsigned*)(_u+(long)_i*(((&(LD))==&lda)?stepa:stepb)+((&(LD))==&lda?oa0:ob0)), \
;         (unsigned*)((char*)(P)+t5*16+_i*8192),16,0,0);}}while(0)
;   #define LDA(dst,b,h) for(int m=0;m<4;++m)for(int k=0;k<2;++k) \
;     dst[m][k]=*reinterpret_cast<const h8*>(la+(((b)*2+(h))*16384+m*2048+k*1024))
;   #define LDB(dst,b,h) for(int n=0;n<2;++n)for(int k=0;k<2;++k) \
;     dst[n][k]=*reinterpret_cast<const h8*>(lb+(((b)*2+(h))*16384+n*2048+k*1024))
;   #define MMA(ai,bj,At,Bt_) do{__builtin_amdgcn_s_setprio(1); \
;     for(int m=0;m<4;++m)for(int n=0;n<2;++n)for(int k=0;k<2;++k) \
;       acc[ai][bj][m][n]=__builtin_amdgcn_mfma_f32_16x16x32_f16(At[m][k],Bt_[n][k],acc[ai][bj][m][n],0,0,0); \
;     __builtin_amdgcn_s_setprio(0);}while(0)
;   #define WAIT_V(n) asm volatile("s_waitcnt vmcnt(" #n ")":::"memory")
;   #define WAIT_L(n) asm volatile("s_waitcnt lgkmcnt(" #n ")":::"memory")
;   #define BAR __builtin_amdgcn_s_barrier()
;   #define SCHED __builtin_amdgcn_sched_barrier(0)
;     ...
;   for(int t=0;t<nt-2;t+=2){
;     LDB(B0,0,0); SCHED; LDA(At,0,0); STAGE(SA(1,1),A,lda,G_HALF,t+1);
;     WAIT_L(8); BAR; WAIT_L(0); MMA(0,0,At,B0); BAR; SCHED;
;     LDB(B1,0,1); STAGE(SB(0,0),Bt,ldb,0,t+2);
;     BAR; WAIT_L(0); MMA(0,1,At,B1); BAR;
;     LDA(At,0,1); STAGE(SA(0,0),A,lda,0,t+2);
;     BAR; WAIT_L(0); MMA(1,0,At,B0); BAR; SCHED;
;     STAGE(SB(0,1),Bt,ldb,G_HALF,t+2);
;     WAIT_V(6); BAR; MMA(1,1,At,B1); BAR;
	v_add3_u32 v159, 0, v129, v128
	ds_read_b128 v[128:131], v152
	ds_read_b128 v[132:135], v152 offset:1024
	ds_read_b128 v[136:139], v152 offset:2048
	ds_read_b128 v[140:143], v152 offset:3072
	v_pk_mul_f32 v[126:127], v[6:7], v[170:171] op_sel_hi:[1,0]
	v_pk_mul_f32 v[124:125], v[4:5], v[170:171] op_sel_hi:[1,0]
	v_pk_mul_f32 v[122:123], v[14:15], v[170:171] op_sel_hi:[1,0]
	v_pk_mul_f32 v[120:121], v[12:13], v[170:171] op_sel_hi:[1,0]
	v_pk_mul_f32 v[14:15], v[146:147], v[172:173] op_sel_hi:[1,0]
	v_pk_mul_f32 v[12:13], v[144:145], v[172:173] op_sel_hi:[1,0]
	v_pk_mul_f32 v[6:7], v[150:151], v[172:173] op_sel_hi:[1,0]
	v_pk_mul_f32 v[4:5], v[148:149], v[172:173] op_sel_hi:[1,0]
	v_add_u32_e32 v210, 0xc000, v190
	v_lshl_add_u64 v[172:173], v[166:167], 0, s[84:85]
	v_readfirstlane_b32 s18, v210
	v_add_u32_e32 v210, 0xe000, v190
	s_mov_b32 m0, s18
	v_readfirstlane_b32 s17, v210
	ds_read_b128 v[144:147], v159
	ds_read_b128 v[148:151], v159 offset:1024
	ds_read_b128 v[168:171], v159 offset:2048
	ds_read_b128 v[176:179], v159 offset:3072
	ds_read_b128 v[194:197], v159 offset:4096
	ds_read_b128 v[198:201], v159 offset:5120
	ds_read_b128 v[202:205], v159 offset:6144
	ds_read_b128 v[206:209], v159 offset:7168
	global_load_lds_dwordx4 v[172:173], off
	v_lshl_add_u64 v[172:173], v[166:167], 0, s[20:21]
	s_mov_b32 m0, s17
	s_nop 0
	global_load_lds_dwordx4 v[172:173], off
	s_waitcnt lgkmcnt(8)
	s_barrier
	s_waitcnt lgkmcnt(0)
	s_setprio 1
	s_waitcnt lgkmcnt(0)
	v_mfma_f32_16x16x32_f16 v[112:115], v[194:197], v[136:139], v[112:115]
	v_mfma_f32_16x16x32_f16 v[104:107], v[202:205], v[136:139], v[104:107]
	v_mfma_f32_16x16x32_f16 v[92:95], v[144:147], v[128:131], v[92:95]
	v_mfma_f32_16x16x32_f16 v[124:127], v[144:147], v[136:139], v[124:127]
	v_mfma_f32_16x16x32_f16 v[88:91], v[168:171], v[128:131], v[88:91]
	v_mfma_f32_16x16x32_f16 v[120:123], v[168:171], v[136:139], v[120:123]
	v_mfma_f32_16x16x32_f16 v[80:83], v[194:197], v[128:131], v[80:83]
	v_mfma_f32_16x16x32_f16 v[112:115], v[198:201], v[140:143], v[112:115]
	v_mfma_f32_16x16x32_f16 v[72:75], v[202:205], v[128:131], v[72:75]
	v_mfma_f32_16x16x32_f16 v[104:107], v[206:209], v[140:143], v[104:107]
	v_mfma_f32_16x16x32_f16 v[92:95], v[148:151], v[132:135], v[92:95]
	v_mfma_f32_16x16x32_f16 v[124:127], v[148:151], v[140:143], v[124:127]
	v_mfma_f32_16x16x32_f16 v[88:91], v[176:179], v[132:135], v[88:91]
	v_mfma_f32_16x16x32_f16 v[120:123], v[176:179], v[140:143], v[120:123]
	v_mfma_f32_16x16x32_f16 v[80:83], v[198:201], v[132:135], v[80:83]
	v_mfma_f32_16x16x32_f16 v[72:75], v[206:209], v[132:135], v[72:75]
	s_setprio 0
	s_barrier
	v_readfirstlane_b32 s19, v192
	v_lshl_add_u64 v[172:173], v[164:165], 0, s[92:93]
	s_mov_b32 m0, s19
	v_readfirstlane_b32 s19, v193
	ds_read_b128 v[210:213], v152 offset:16384
	ds_read_b128 v[214:217], v152 offset:17408
	ds_read_b128 v[218:221], v152 offset:18432
	ds_read_b128 v[222:225], v152 offset:19456
	global_load_lds_dwordx4 v[172:173], off
	v_lshl_add_u64 v[172:173], v[164:165], 0, s[66:67]
	s_mov_b32 m0, s19
	s_nop 0
	global_load_lds_dwordx4 v[172:173], off
	s_barrier
	s_waitcnt lgkmcnt(0)
	s_setprio 1
	s_waitcnt lgkmcnt(0)
	v_mfma_f32_16x16x32_f16 v[84:87], v[144:147], v[210:213], v[84:87]
	v_mfma_f32_16x16x32_f16 v[116:119], v[144:147], v[218:221], v[116:119]
	v_mfma_f32_16x16x32_f16 v[76:79], v[168:171], v[210:213], v[76:79]
	v_mfma_f32_16x16x32_f16 v[108:111], v[168:171], v[218:221], v[108:111]
	v_mfma_f32_16x16x32_f16 v[68:71], v[194:197], v[210:213], v[68:71]
	v_mfma_f32_16x16x32_f16 v[100:103], v[194:197], v[218:221], v[100:103]
	v_mfma_f32_16x16x32_f16 v[64:67], v[202:205], v[210:213], v[64:67]
	v_mfma_f32_16x16x32_f16 v[96:99], v[202:205], v[218:221], v[96:99]
	v_mfma_f32_16x16x32_f16 v[84:87], v[148:151], v[214:217], v[84:87]
	v_mfma_f32_16x16x32_f16 v[116:119], v[148:151], v[222:225], v[116:119]
	v_mfma_f32_16x16x32_f16 v[76:79], v[176:179], v[214:217], v[76:79]
	v_mfma_f32_16x16x32_f16 v[108:111], v[176:179], v[222:225], v[108:111]
	v_mfma_f32_16x16x32_f16 v[68:71], v[198:201], v[214:217], v[68:71]
	v_mfma_f32_16x16x32_f16 v[100:103], v[198:201], v[222:225], v[100:103]
	v_mfma_f32_16x16x32_f16 v[64:67], v[206:209], v[214:217], v[64:67]
	v_mfma_f32_16x16x32_f16 v[96:99], v[206:209], v[222:225], v[96:99]
	s_setprio 0
	v_readfirstlane_b32 s19, v190
	v_lshl_add_u64 v[172:173], v[160:161], 0, s[92:93]
	s_mov_b32 m0, s19
	s_mov_b64 s[20:21], 0x8100
	v_readfirstlane_b32 s19, v191
	s_barrier
	ds_read_b128 v[144:147], v159 offset:16384
	ds_read_b128 v[148:151], v159 offset:17408
	ds_read_b128 v[168:171], v159 offset:18432
	ds_read_b128 v[176:179], v159 offset:19456
	ds_read_b128 v[192:195], v159 offset:20480
	ds_read_b128 v[196:199], v159 offset:21504
	ds_read_b128 v[200:203], v159 offset:22528
	ds_read_b128 v[204:207], v159 offset:23552
	global_load_lds_dwordx4 v[172:173], off
	v_lshl_add_u64 v[172:173], v[160:161], 0, s[20:21]
	s_mov_b32 m0, s19
	s_nop 0
	global_load_lds_dwordx4 v[172:173], off
	s_barrier
	s_waitcnt lgkmcnt(0)
	s_setprio 1
	s_waitcnt lgkmcnt(0)
	v_mfma_f32_16x16x32_f16 v[24:27], v[144:147], v[128:131], v[24:27]
	v_mfma_f32_16x16x32_f16 v[56:59], v[144:147], v[136:139], v[56:59]
	v_mfma_f32_16x16x32_f16 v[16:19], v[168:171], v[128:131], v[16:19]
	v_mfma_f32_16x16x32_f16 v[48:51], v[168:171], v[136:139], v[48:51]
	v_mfma_f32_16x16x32_f16 v[8:11], v[192:195], v[128:131], v[8:11]
	v_mfma_f32_16x16x32_f16 v[40:43], v[192:195], v[136:139], v[40:43]
	v_mfma_f32_16x16x32_f16 v[0:3], v[200:203], v[128:131], v[0:3]
	v_mfma_f32_16x16x32_f16 v[32:35], v[200:203], v[136:139], v[32:35]
	v_mfma_f32_16x16x32_f16 v[24:27], v[148:151], v[132:135], v[24:27]
	v_mfma_f32_16x16x32_f16 v[56:59], v[148:151], v[140:143], v[56:59]
	v_mfma_f32_16x16x32_f16 v[16:19], v[176:179], v[132:135], v[16:19]
	v_mfma_f32_16x16x32_f16 v[48:51], v[176:179], v[140:143], v[48:51]
	v_mfma_f32_16x16x32_f16 v[8:11], v[196:199], v[132:135], v[8:11]
	v_mfma_f32_16x16x32_f16 v[40:43], v[196:199], v[140:143], v[40:43]
	v_mfma_f32_16x16x32_f16 v[0:3], v[204:207], v[132:135], v[0:3]
	v_mfma_f32_16x16x32_f16 v[32:35], v[204:207], v[140:143], v[32:35]
	s_setprio 0
	s_barrier
;   #define STAGE(P,BASE,LD,br,kt) do{ const HALF* _u=(BASE)+(long)(br)*(((&(LD))==&lda)?lda_u:(LD))+(long)(kt)*G_BK; \
;     for(int _i=0;_i<2;++_i){ \
;       __builtin_amdgcn_global_load_lds((const unsigned*)(_u+(long)_i*(((&(LD))==&lda)?stepa:stepb)+((&(LD))==&lda?oa0:ob0)), \
;         (unsigned*)((char*)(P)+t5*16+_i*8192),16,0,0);}}while(0)
;   #define LDA(dst,b,h) for(int m=0;m<4;++m)for(int k=0;k<2;++k) \
;     dst[m][k]=*reinterpret_cast<const h8*>(la+(((b)*2+(h))*16384+m*2048+k*1024))
;   #define LDB(dst,b,h) for(int n=0;n<2;++n)for(int k=0;k<2;++k) \
;     dst[n][k]=*reinterpret_cast<const h8*>(lb+(((b)*2+(h))*16384+n*2048+k*1024))
;   #define MMA(ai,bj,At,Bt_) do{__builtin_amdgcn_s_setprio(1); \
;     for(int m=0;m<4;++m)for(int n=0;n<2;++n)for(int k=0;k<2;++k) \
;       acc[ai][bj][m][n]=__builtin_amdgcn_mfma_f32_16x16x32_f16(At[m][k],Bt_[n][k],acc[ai][bj][m][n],0,0,0); \
;     __builtin_amdgcn_s_setprio(0);}while(0)
;   #define WAIT_V(n) asm volatile("s_waitcnt vmcnt(" #n ")":::"memory")
;   #define WAIT_L(n) asm volatile("s_waitcnt lgkmcnt(" #n ")":::"memory")
;   #define BAR __builtin_amdgcn_s_barrier()
;   #define SCHED __builtin_amdgcn_sched_barrier(0)
;     ...
;     WAIT_V(6); BAR; MMA(1,1,At,B1); BAR;
;     LDB(B0,1,0); SCHED; LDA(At,1,0); STAGE(SA(0,1),A,lda,G_HALF,t+2);
;     WAIT_L(8); BAR; WAIT_L(0); MMA(0,0,At,B0); BAR; SCHED;
;     LDB(B1,1,1); STAGE(SB(1,0),Bt,ldb,0,t+3);
;     BAR; WAIT_L(0); MMA(0,1,At,B1); BAR;
;     LDA(At,1,1); STAGE(SA(1,0),A,lda,0,t+3);
	v_readfirstlane_b32 s19, v188
	v_lshl_add_u64 v[128:129], v[162:163], 0, s[92:93]
	s_mov_b32 m0, s19
	v_readfirstlane_b32 s19, v189
	global_load_lds_dwordx4 v[128:129], off
	v_lshl_add_u64 v[128:129], v[162:163], 0, s[66:67]
	s_mov_b32 m0, s19
	s_nop 0
	global_load_lds_dwordx4 v[128:129], off
	s_waitcnt vmcnt(6)
	s_barrier
	s_setprio 1
	v_mfma_f32_16x16x32_f16 v[28:31], v[144:147], v[210:213], v[28:31]
	v_mfma_f32_16x16x32_f16 v[60:63], v[144:147], v[218:221], v[60:63]
	v_mfma_f32_16x16x32_f16 v[20:23], v[168:171], v[210:213], v[20:23]
	v_mfma_f32_16x16x32_f16 v[52:55], v[168:171], v[218:221], v[52:55]
	v_mfma_f32_16x16x32_f16 v[12:15], v[192:195], v[210:213], v[12:15]
	v_mfma_f32_16x16x32_f16 v[44:47], v[192:195], v[218:221], v[44:47]
	v_mfma_f32_16x16x32_f16 v[4:7], v[200:203], v[210:213], v[4:7]
	v_mfma_f32_16x16x32_f16 v[36:39], v[200:203], v[218:221], v[36:39]
	v_mfma_f32_16x16x32_f16 v[28:31], v[148:151], v[214:217], v[28:31]
	v_mfma_f32_16x16x32_f16 v[60:63], v[148:151], v[222:225], v[60:63]
	v_mfma_f32_16x16x32_f16 v[20:23], v[176:179], v[214:217], v[20:23]
	v_mfma_f32_16x16x32_f16 v[52:55], v[176:179], v[222:225], v[52:55]
	v_mfma_f32_16x16x32_f16 v[12:15], v[196:199], v[214:217], v[12:15]
	v_mfma_f32_16x16x32_f16 v[44:47], v[196:199], v[222:225], v[44:47]
	v_mfma_f32_16x16x32_f16 v[4:7], v[204:207], v[214:217], v[4:7]
	v_mfma_f32_16x16x32_f16 v[36:39], v[204:207], v[222:225], v[36:39]
	s_setprio 0
	s_barrier
	ds_read_b128 v[128:131], v152 offset:32768
	ds_read_b128 v[132:135], v152 offset:33792
	ds_read_b128 v[136:139], v152 offset:34816
	ds_read_b128 v[140:143], v152 offset:35840
	v_readfirstlane_b32 s19, v186
	v_lshl_add_u64 v[172:173], v[166:167], 0, s[92:93]
	s_mov_b32 m0, s19
	v_readfirstlane_b32 s19, v187
	ds_read_b128 v[144:147], v159 offset:32768
	ds_read_b128 v[148:151], v159 offset:33792
	ds_read_b128 v[168:171], v159 offset:34816
	ds_read_b128 v[176:179], v159 offset:35840
	ds_read_b128 v[188:191], v159 offset:36864
	ds_read_b128 v[192:195], v159 offset:37888
	ds_read_b128 v[196:199], v159 offset:38912
	ds_read_b128 v[200:203], v159 offset:39936
	global_load_lds_dwordx4 v[172:173], off
	v_lshl_add_u64 v[166:167], v[166:167], 0, s[20:21]
	s_mov_b32 m0, s19
	s_nop 0
	global_load_lds_dwordx4 v[166:167], off
	s_waitcnt lgkmcnt(8)
	s_barrier
	s_waitcnt lgkmcnt(0)
	s_setprio 1
	s_waitcnt lgkmcnt(0)
	v_mfma_f32_16x16x32_f16 v[112:115], v[188:191], v[136:139], v[112:115]
	v_mfma_f32_16x16x32_f16 v[104:107], v[196:199], v[136:139], v[104:107]
	v_mfma_f32_16x16x32_f16 v[92:95], v[144:147], v[128:131], v[92:95]
	v_mfma_f32_16x16x32_f16 v[124:127], v[144:147], v[136:139], v[124:127]
	v_mfma_f32_16x16x32_f16 v[88:91], v[168:171], v[128:131], v[88:91]
	v_mfma_f32_16x16x32_f16 v[120:123], v[168:171], v[136:139], v[120:123]
	v_mfma_f32_16x16x32_f16 v[80:83], v[188:191], v[128:131], v[80:83]
	v_mfma_f32_16x16x32_f16 v[112:115], v[192:195], v[140:143], v[112:115]
	v_mfma_f32_16x16x32_f16 v[72:75], v[196:199], v[128:131], v[72:75]
	v_mfma_f32_16x16x32_f16 v[104:107], v[200:203], v[140:143], v[104:107]
	v_mfma_f32_16x16x32_f16 v[92:95], v[148:151], v[132:135], v[92:95]
	v_mfma_f32_16x16x32_f16 v[124:127], v[148:151], v[140:143], v[124:127]
	v_mfma_f32_16x16x32_f16 v[88:91], v[176:179], v[132:135], v[88:91]
	v_mfma_f32_16x16x32_f16 v[120:123], v[176:179], v[140:143], v[120:123]
	v_mfma_f32_16x16x32_f16 v[80:83], v[192:195], v[132:135], v[80:83]
	v_mfma_f32_16x16x32_f16 v[72:75], v[200:203], v[132:135], v[72:75]
	s_setprio 0
	s_barrier
	s_mov_b32 m0, s13
	v_lshl_add_u64 v[166:167], v[164:165], 0, s[42:43]
	ds_read_b128 v[204:207], v152 offset:49152
	ds_read_b128 v[208:211], v152 offset:50176
	ds_read_b128 v[212:215], v152 offset:51200
	ds_read_b128 v[216:219], v152 offset:52224
	global_load_lds_dwordx4 v[166:167], off
	v_lshl_add_u64 v[164:165], v[164:165], 0, s[96:97]
	s_mov_b32 m0, s12
	s_nop 0
	global_load_lds_dwordx4 v[164:165], off
	s_barrier
	s_waitcnt lgkmcnt(0)
	s_setprio 1
	s_waitcnt lgkmcnt(0)
	v_mfma_f32_16x16x32_f16 v[84:87], v[144:147], v[204:207], v[84:87]
	v_mfma_f32_16x16x32_f16 v[116:119], v[144:147], v[212:215], v[116:119]
	v_mfma_f32_16x16x32_f16 v[76:79], v[168:171], v[204:207], v[76:79]
	v_mfma_f32_16x16x32_f16 v[108:111], v[168:171], v[212:215], v[108:111]
	v_mfma_f32_16x16x32_f16 v[68:71], v[188:191], v[204:207], v[68:71]
	v_mfma_f32_16x16x32_f16 v[100:103], v[188:191], v[212:215], v[100:103]
	v_mfma_f32_16x16x32_f16 v[64:67], v[196:199], v[204:207], v[64:67]
	v_mfma_f32_16x16x32_f16 v[96:99], v[196:199], v[212:215], v[96:99]
	v_mfma_f32_16x16x32_f16 v[84:87], v[148:151], v[208:211], v[84:87]
	v_mfma_f32_16x16x32_f16 v[116:119], v[148:151], v[216:219], v[116:119]
	v_mfma_f32_16x16x32_f16 v[76:79], v[176:179], v[208:211], v[76:79]
	v_mfma_f32_16x16x32_f16 v[108:111], v[176:179], v[216:219], v[108:111]
	v_mfma_f32_16x16x32_f16 v[68:71], v[192:195], v[208:211], v[68:71]
	v_mfma_f32_16x16x32_f16 v[100:103], v[192:195], v[216:219], v[100:103]
	v_mfma_f32_16x16x32_f16 v[64:67], v[200:203], v[208:211], v[64:67]
	v_mfma_f32_16x16x32_f16 v[96:99], v[200:203], v[216:219], v[96:99]
	s_setprio 0
	s_mov_b32 m0, s11
	v_lshl_add_u64 v[172:173], v[160:161], 0, s[42:43]
	s_mov_b64 s[12:13], 0x8180
	s_barrier
	ds_read_b128 v[144:147], v159 offset:49152
	ds_read_b128 v[148:151], v159 offset:50176
	ds_read_b128 v[164:167], v159 offset:51200
	ds_read_b128 v[168:171], v159 offset:52224
	ds_read_b128 v[176:179], v159 offset:53248
	ds_read_b128 v[186:189], v159 offset:54272
	ds_read_b128 v[190:193], v159 offset:55296
	ds_read_b128 v[194:197], v159 offset:56320
	global_load_lds_dwordx4 v[172:173], off
	v_lshl_add_u64 v[172:173], v[160:161], 0, s[12:13]
	s_mov_b32 m0, s10
	s_nop 0
	global_load_lds_dwordx4 v[172:173], off
	s_barrier
;   #define STAGE(P,BASE,LD,br,kt) do{ const HALF* _u=(BASE)+(long)(br)*(((&(LD))==&lda)?lda_u:(LD))+(long)(kt)*G_BK; \
;     for(int _i=0;_i<2;++_i){ \
;       __builtin_amdgcn_global_load_lds((const unsigned*)(_u+(long)_i*(((&(LD))==&lda)?stepa:stepb)+((&(LD))==&lda?oa0:ob0)), \
;         (unsigned*)((char*)(P)+t5*16+_i*8192),16,0,0);}}while(0)
;   #define LDA(dst,b,h) for(int m=0;m<4;++m)for(int k=0;k<2;++k) \
;     dst[m][k]=*reinterpret_cast<const h8*>(la+(((b)*2+(h))*16384+m*2048+k*1024))
;   #define LDB(dst,b,h) for(int n=0;n<2;++n)for(int k=0;k<2;++k) \
;     dst[n][k]=*reinterpret_cast<const h8*>(lb+(((b)*2+(h))*16384+n*2048+k*1024))
;   #define MMA(ai,bj,At,Bt_) do{__builtin_amdgcn_s_setprio(1); \
;     for(int m=0;m<4;++m)for(int n=0;n<2;++n)for(int k=0;k<2;++k) \
;       acc[ai][bj][m][n]=__builtin_amdgcn_mfma_f32_16x16x32_f16(At[m][k],Bt_[n][k],acc[ai][bj][m][n],0,0,0); \
;     __builtin_amdgcn_s_setprio(0);}while(0)
;   #define WAIT_V(n) asm volatile("s_waitcnt vmcnt(" #n ")":::"memory")
;   #define WAIT_L(n) asm volatile("s_waitcnt lgkmcnt(" #n ")":::"memory")
;   #define BAR __builtin_amdgcn_s_barrier()
;   #define SCHED __builtin_amdgcn_sched_barrier(0)
;     ...
;     LDA(At,1,1); STAGE(SA(1,0),A,lda,0,t+3);
;     BAR; WAIT_L(0); MMA(1,0,At,B0); BAR; SCHED;
;     STAGE(SB(1,1),Bt,ldb,G_HALF,t+3);
;     WAIT_V(6); BAR; MMA(1,1,At,B1); BAR;
;   }
;   { LDB(B0,0,0); LDA(At,0,0); STAGE(SA(1,1),A,lda,G_HALF,nt-1);
;     BAR; WAIT_L(0); MMA(0,0,At,B0); BAR;
;     LDB(B1,0,1); BAR; WAIT_L(0); MMA(0,1,At,B1); BAR;
	s_waitcnt lgkmcnt(0)
	s_setprio 1
	s_waitcnt lgkmcnt(0)
	v_mfma_f32_16x16x32_f16 v[24:27], v[144:147], v[128:131], v[24:27]
	v_mfma_f32_16x16x32_f16 v[56:59], v[144:147], v[136:139], v[56:59]
	v_mfma_f32_16x16x32_f16 v[16:19], v[164:167], v[128:131], v[16:19]
	v_mfma_f32_16x16x32_f16 v[48:51], v[164:167], v[136:139], v[48:51]
	v_mfma_f32_16x16x32_f16 v[8:11], v[176:179], v[128:131], v[8:11]
	v_mfma_f32_16x16x32_f16 v[40:43], v[176:179], v[136:139], v[40:43]
	v_mfma_f32_16x16x32_f16 v[0:3], v[190:193], v[128:131], v[0:3]
	v_mfma_f32_16x16x32_f16 v[32:35], v[190:193], v[136:139], v[32:35]
	v_mfma_f32_16x16x32_f16 v[24:27], v[148:151], v[132:135], v[24:27]
	v_mfma_f32_16x16x32_f16 v[56:59], v[148:151], v[140:143], v[56:59]
	v_mfma_f32_16x16x32_f16 v[16:19], v[168:171], v[132:135], v[16:19]
	v_mfma_f32_16x16x32_f16 v[48:51], v[168:171], v[140:143], v[48:51]
	v_mfma_f32_16x16x32_f16 v[8:11], v[186:189], v[132:135], v[8:11]
	v_mfma_f32_16x16x32_f16 v[40:43], v[186:189], v[140:143], v[40:43]
	v_mfma_f32_16x16x32_f16 v[0:3], v[194:197], v[132:135], v[0:3]
	v_mfma_f32_16x16x32_f16 v[32:35], v[194:197], v[140:143], v[32:35]
	s_setprio 0
	s_barrier
	s_mov_b32 m0, s7
	v_lshl_add_u64 v[128:129], v[162:163], 0, s[42:43]
	global_load_lds_dwordx4 v[128:129], off
	v_lshl_add_u64 v[128:129], v[162:163], 0, s[96:97]
	s_mov_b32 m0, s6
	s_nop 0
	global_load_lds_dwordx4 v[128:129], off
	s_waitcnt vmcnt(6)
	s_barrier
	s_setprio 1
	v_mfma_f32_16x16x32_f16 v[28:31], v[144:147], v[204:207], v[28:31]
	v_mfma_f32_16x16x32_f16 v[60:63], v[144:147], v[212:215], v[60:63]
	v_mfma_f32_16x16x32_f16 v[20:23], v[164:167], v[204:207], v[20:23]
	v_mfma_f32_16x16x32_f16 v[52:55], v[164:167], v[212:215], v[52:55]
	v_mfma_f32_16x16x32_f16 v[12:15], v[176:179], v[204:207], v[12:15]
	v_mfma_f32_16x16x32_f16 v[44:47], v[176:179], v[212:215], v[44:47]
	v_mfma_f32_16x16x32_f16 v[4:7], v[190:193], v[204:207], v[4:7]
	v_mfma_f32_16x16x32_f16 v[36:39], v[190:193], v[212:215], v[36:39]
	v_mfma_f32_16x16x32_f16 v[28:31], v[148:151], v[208:211], v[28:31]
	v_mfma_f32_16x16x32_f16 v[60:63], v[148:151], v[216:219], v[60:63]
	v_mfma_f32_16x16x32_f16 v[20:23], v[168:171], v[208:211], v[20:23]
	v_mfma_f32_16x16x32_f16 v[52:55], v[168:171], v[216:219], v[52:55]
	v_mfma_f32_16x16x32_f16 v[12:15], v[186:189], v[208:211], v[12:15]
	v_mfma_f32_16x16x32_f16 v[44:47], v[186:189], v[216:219], v[44:47]
	v_mfma_f32_16x16x32_f16 v[4:7], v[194:197], v[208:211], v[4:7]
	v_mfma_f32_16x16x32_f16 v[36:39], v[194:197], v[216:219], v[36:39]
	s_setprio 0
	s_mov_b64 s[6:7], 0x10180
	s_mov_b32 m0, s18
	v_lshl_add_u64 v[194:195], v[160:161], 0, s[6:7]
	s_mov_b64 s[6:7], 0x18180
	s_barrier
	ds_read_b128 v[128:131], v152
	ds_read_b128 v[132:135], v152 offset:1024
	ds_read_b128 v[136:139], v152 offset:2048
	ds_read_b128 v[140:143], v152 offset:3072
	ds_read_b128 v[144:147], v159
	ds_read_b128 v[148:151], v159 offset:1024
	ds_read_b128 v[162:165], v159 offset:2048
	ds_read_b128 v[166:169], v159 offset:3072
	ds_read_b128 v[170:173], v159 offset:4096
	ds_read_b128 v[176:179], v159 offset:5120
	ds_read_b128 v[186:189], v159 offset:6144
	ds_read_b128 v[190:193], v159 offset:7168
	global_load_lds_dwordx4 v[194:195], off
	v_lshl_add_u64 v[160:161], v[160:161], 0, s[6:7]
	s_mov_b32 m0, s17
	s_nop 0
	global_load_lds_dwordx4 v[160:161], off
	s_barrier
	s_waitcnt lgkmcnt(0)
	s_setprio 1
	s_waitcnt lgkmcnt(0)
	v_mfma_f32_16x16x32_f16 v[112:115], v[170:173], v[136:139], v[112:115]
	v_mfma_f32_16x16x32_f16 v[104:107], v[186:189], v[136:139], v[104:107]
	v_mfma_f32_16x16x32_f16 v[92:95], v[144:147], v[128:131], v[92:95]
	v_mfma_f32_16x16x32_f16 v[124:127], v[144:147], v[136:139], v[124:127]
	v_mfma_f32_16x16x32_f16 v[88:91], v[162:165], v[128:131], v[88:91]
	v_mfma_f32_16x16x32_f16 v[120:123], v[162:165], v[136:139], v[120:123]
	v_mfma_f32_16x16x32_f16 v[80:83], v[170:173], v[128:131], v[80:83]
	v_mfma_f32_16x16x32_f16 v[112:115], v[176:179], v[140:143], v[112:115]
	v_mfma_f32_16x16x32_f16 v[72:75], v[186:189], v[128:131], v[72:75]
	v_mfma_f32_16x16x32_f16 v[104:107], v[190:193], v[140:143], v[104:107]
	v_mfma_f32_16x16x32_f16 v[92:95], v[148:151], v[132:135], v[92:95]
	v_mfma_f32_16x16x32_f16 v[124:127], v[148:151], v[140:143], v[124:127]
	v_mfma_f32_16x16x32_f16 v[88:91], v[166:169], v[132:135], v[88:91]
	v_mfma_f32_16x16x32_f16 v[120:123], v[166:169], v[140:143], v[120:123]
	v_mfma_f32_16x16x32_f16 v[80:83], v[176:179], v[132:135], v[80:83]
	v_mfma_f32_16x16x32_f16 v[72:75], v[190:193], v[132:135], v[72:75]
	s_setprio 0
	s_barrier
	ds_read_b128 v[194:197], v152 offset:16384
	ds_read_b128 v[198:201], v152 offset:17408
	ds_read_b128 v[202:205], v152 offset:18432
	ds_read_b128 v[206:209], v152 offset:19456
	s_barrier
	s_waitcnt lgkmcnt(0)
	s_setprio 1
	s_waitcnt lgkmcnt(0)
	v_mfma_f32_16x16x32_f16 v[68:71], v[170:173], v[194:197], v[68:71]
	v_mfma_f32_16x16x32_f16 v[84:87], v[144:147], v[194:197], v[84:87]
	v_mfma_f32_16x16x32_f16 v[116:119], v[144:147], v[202:205], v[116:119]
	v_mfma_f32_16x16x32_f16 v[76:79], v[162:165], v[194:197], v[76:79]
	v_mfma_f32_16x16x32_f16 v[108:111], v[162:165], v[202:205], v[108:111]
	v_mfma_f32_16x16x32_f16 v[144:147], v[176:179], v[198:201], v[68:71]
	v_mfma_f32_16x16x32_f16 v[68:71], v[170:173], v[202:205], v[100:103]
	v_mfma_f32_16x16x32_f16 v[64:67], v[186:189], v[194:197], v[64:67]
	v_mfma_f32_16x16x32_f16 v[84:87], v[148:151], v[198:201], v[84:87]
	v_mfma_f32_16x16x32_f16 v[116:119], v[148:151], v[206:209], v[116:119]
	v_mfma_f32_16x16x32_f16 v[76:79], v[166:169], v[198:201], v[76:79]
	v_mfma_f32_16x16x32_f16 v[108:111], v[166:169], v[206:209], v[108:111]
	v_mfma_f32_16x16x32_f16 v[100:103], v[176:179], v[206:209], v[68:71]
	v_mfma_f32_16x16x32_f16 v[148:151], v[190:193], v[198:201], v[64:67]
	v_mfma_f32_16x16x32_f16 v[64:67], v[186:189], v[202:205], v[96:99]
	v_mfma_f32_16x16x32_f16 v[160:163], v[190:193], v[206:209], v[64:67]
	s_setprio 0
	s_barrier
;   #define LDA(dst,b,h) for(int m=0;m<4;++m)for(int k=0;k<2;++k) \
;     dst[m][k]=*reinterpret_cast<const h8*>(la+(((b)*2+(h))*16384+m*2048+k*1024))
;   #define LDB(dst,b,h) for(int n=0;n<2;++n)for(int k=0;k<2;++k) \
;     dst[n][k]=*reinterpret_cast<const h8*>(lb+(((b)*2+(h))*16384+n*2048+k*1024))
;   #define MMA(ai,bj,At,Bt_) do{__builtin_amdgcn_s_setprio(1); \
;     for(int m=0;m<4;++m)for(int n=0;n<2;++n)for(int k=0;k<2;++k) \
;       acc[ai][bj][m][n]=__builtin_amdgcn_mfma_f32_16x16x32_f16(At[m][k],Bt_[n][k],acc[ai][bj][m][n],0,0,0); \
;     __builtin_amdgcn_s_setprio(0);}while(0)
;   #define WAIT_V(n) asm volatile("s_waitcnt vmcnt(" #n ")":::"memory")
;   #define WAIT_L(n) asm volatile("s_waitcnt lgkmcnt(" #n ")":::"memory")
;   #define BAR __builtin_amdgcn_s_barrier()
;     ...
;     LDA(At,0,1); WAIT_V(4); BAR; WAIT_L(0); MMA(1,0,At,B0); MMA(1,1,At,B1); BAR; }
;   { LDB(B0,1,0); LDA(At,1,0); WAIT_V(2); BAR; WAIT_L(0); MMA(0,0,At,B0); BAR;
	s_nop 4
	ds_read_b128 v[64:67], v159 offset:16384
	ds_read_b128 v[68:71], v159 offset:17408
	ds_read_b128 v[96:99], v159 offset:18432
	ds_read_b128 v[164:167], v159 offset:19456
	ds_read_b128 v[168:171], v159 offset:20480
	ds_read_b128 v[176:179], v159 offset:21504
	ds_read_b128 v[186:189], v159 offset:22528
	ds_read_b128 v[190:193], v159 offset:23552
	s_waitcnt vmcnt(4)
	s_barrier
	s_waitcnt lgkmcnt(0)
	s_setprio 1
	s_waitcnt lgkmcnt(0)
	v_mfma_f32_16x16x32_f16 v[24:27], v[64:67], v[128:131], v[24:27]
	v_mfma_f32_16x16x32_f16 v[0:3], v[186:189], v[128:131], v[0:3]
	v_mfma_f32_16x16x32_f16 v[210:213], v[68:71], v[132:135], v[24:27]
	v_mfma_f32_16x16x32_f16 v[24:27], v[64:67], v[136:139], v[56:59]
	v_mfma_f32_16x16x32_f16 v[16:19], v[96:99], v[128:131], v[16:19]
	v_mfma_f32_16x16x32_f16 v[8:11], v[168:171], v[128:131], v[8:11]
	v_mfma_f32_16x16x32_f16 v[128:131], v[190:193], v[132:135], v[0:3]
	v_mfma_f32_16x16x32_f16 v[0:3], v[186:189], v[136:139], v[32:35]
	v_mfma_f32_16x16x32_f16 v[56:59], v[68:71], v[140:143], v[24:27]
	v_mfma_f32_16x16x32_f16 v[214:217], v[164:167], v[132:135], v[16:19]
	v_mfma_f32_16x16x32_f16 v[16:19], v[96:99], v[136:139], v[48:51]
	v_mfma_f32_16x16x32_f16 v[222:225], v[176:179], v[132:135], v[8:11]
	v_mfma_f32_16x16x32_f16 v[8:11], v[168:171], v[136:139], v[40:43]
	v_mfma_f32_16x16x32_f16 v[132:135], v[190:193], v[140:143], v[0:3]
	v_mfma_f32_16x16x32_f16 v[218:221], v[164:167], v[140:143], v[16:19]
	v_mfma_f32_16x16x32_f16 v[226:229], v[176:179], v[140:143], v[8:11]
	s_setprio 0
	s_setprio 1
	v_mfma_f32_16x16x32_f16 v[0:3], v[64:67], v[194:197], v[28:31]
	v_mfma_f32_16x16x32_f16 v[136:139], v[68:71], v[198:201], v[0:3]
	v_mfma_f32_16x16x32_f16 v[0:3], v[64:67], v[202:205], v[60:63]
	v_mfma_f32_16x16x32_f16 v[140:143], v[68:71], v[206:209], v[0:3]
	v_mfma_f32_16x16x32_f16 v[0:3], v[96:99], v[194:197], v[20:23]
	v_mfma_f32_16x16x32_f16 v[230:233], v[164:167], v[198:201], v[0:3]
	v_mfma_f32_16x16x32_f16 v[0:3], v[96:99], v[202:205], v[52:55]
	v_mfma_f32_16x16x32_f16 v[164:167], v[164:167], v[206:209], v[0:3]
	v_mfma_f32_16x16x32_f16 v[0:3], v[168:171], v[194:197], v[12:15]
	v_mfma_f32_16x16x32_f16 v[234:237], v[176:179], v[198:201], v[0:3]
	v_mfma_f32_16x16x32_f16 v[0:3], v[168:171], v[202:205], v[44:47]
	v_mfma_f32_16x16x32_f16 v[168:171], v[176:179], v[206:209], v[0:3]
	v_mfma_f32_16x16x32_f16 v[0:3], v[186:189], v[194:197], v[4:7]
	v_mfma_f32_16x16x32_f16 v[176:179], v[190:193], v[198:201], v[0:3]
	v_mfma_f32_16x16x32_f16 v[0:3], v[186:189], v[202:205], v[36:39]
	v_mfma_f32_16x16x32_f16 v[186:189], v[190:193], v[206:209], v[0:3]
	s_setprio 0
	s_barrier
	ds_read_b128 v[190:193], v152 offset:32768
	ds_read_b128 v[194:197], v152 offset:33792
	ds_read_b128 v[198:201], v152 offset:34816
	ds_read_b128 v[202:205], v152 offset:35840
	ds_read_b128 v[32:35], v159 offset:32768
	ds_read_b128 v[36:39], v159 offset:33792
	ds_read_b128 v[40:43], v159 offset:34816
	ds_read_b128 v[44:47], v159 offset:35840
	ds_read_b128 v[48:51], v159 offset:36864
	ds_read_b128 v[52:55], v159 offset:37888
	ds_read_b128 v[60:63], v159 offset:38912
	ds_read_b128 v[206:209], v159 offset:39936
	s_waitcnt vmcnt(2)
	s_barrier
	s_waitcnt lgkmcnt(0)
	s_setprio 1
	s_waitcnt lgkmcnt(0)
	v_mfma_f32_16x16x32_f16 v[0:3], v[32:35], v[190:193], v[92:95]
	v_mfma_f32_16x16x32_f16 v[4:7], v[32:35], v[198:201], v[124:127]
	v_mfma_f32_16x16x32_f16 v[8:11], v[40:43], v[190:193], v[88:91]
	v_mfma_f32_16x16x32_f16 v[12:15], v[40:43], v[198:201], v[120:123]
	v_mfma_f32_16x16x32_f16 v[16:19], v[48:51], v[190:193], v[80:83]
	v_mfma_f32_16x16x32_f16 v[20:23], v[48:51], v[198:201], v[112:115]
	v_mfma_f32_16x16x32_f16 v[24:27], v[60:63], v[190:193], v[72:75]
	v_mfma_f32_16x16x32_f16 v[28:31], v[60:63], v[198:201], v[104:107]
	v_mfma_f32_16x16x32_f16 v[0:3], v[36:39], v[194:197], v[0:3]
	v_mfma_f32_16x16x32_f16 v[4:7], v[36:39], v[202:205], v[4:7]
	v_mfma_f32_16x16x32_f16 v[8:11], v[44:47], v[194:197], v[8:11]
	v_mfma_f32_16x16x32_f16 v[12:15], v[44:47], v[202:205], v[12:15]
	v_mfma_f32_16x16x32_f16 v[16:19], v[52:55], v[194:197], v[16:19]
	v_mfma_f32_16x16x32_f16 v[20:23], v[52:55], v[202:205], v[20:23]
	v_mfma_f32_16x16x32_f16 v[24:27], v[206:209], v[194:197], v[24:27]
	v_mfma_f32_16x16x32_f16 v[28:31], v[206:209], v[202:205], v[28:31]
	s_setprio 0
	s_barrier
;   #define LDA(dst,b,h) for(int m=0;m<4;++m)for(int k=0;k<2;++k) \
;     dst[m][k]=*reinterpret_cast<const h8*>(la+(((b)*2+(h))*16384+m*2048+k*1024))
;   #define LDB(dst,b,h) for(int n=0;n<2;++n)for(int k=0;k<2;++k) \
;     dst[n][k]=*reinterpret_cast<const h8*>(lb+(((b)*2+(h))*16384+n*2048+k*1024))
;   #define MMA(ai,bj,At,Bt_) do{__builtin_amdgcn_s_setprio(1); \
;     for(int m=0;m<4;++m)for(int n=0;n<2;++n)for(int k=0;k<2;++k) \
;       acc[ai][bj][m][n]=__builtin_amdgcn_mfma_f32_16x16x32_f16(At[m][k],Bt_[n][k],acc[ai][bj][m][n],0,0,0); \
;     __builtin_amdgcn_s_setprio(0);}while(0)
;   #define WAIT_V(n) asm volatile("s_waitcnt vmcnt(" #n ")":::"memory")
;   #define WAIT_L(n) asm volatile("s_waitcnt lgkmcnt(" #n ")":::"memory")
;   #define BAR __builtin_amdgcn_s_barrier()
;     ...
;     LDB(B1,1,1); WAIT_V(0); BAR; WAIT_L(0); MMA(0,1,At,B1); BAR;
;     LDA(At,1,1); BAR; WAIT_L(0); MMA(1,0,At,B0); MMA(1,1,At,B1); BAR; }
;   if(wr==0)BAR;
	ds_read_b128 v[72:75], v152 offset:49152
	ds_read_b128 v[80:83], v152 offset:50176
	ds_read_b128 v[88:91], v152 offset:51200
	ds_read_b128 v[92:95], v152 offset:52224
	s_waitcnt vmcnt(0)
	s_barrier
	s_waitcnt lgkmcnt(0)
	s_setprio 1
	s_waitcnt lgkmcnt(0)
	v_mfma_f32_16x16x32_f16 v[64:67], v[32:35], v[72:75], v[84:87]
	v_mfma_f32_16x16x32_f16 v[32:35], v[32:35], v[88:91], v[116:119]
	v_mfma_f32_16x16x32_f16 v[64:67], v[36:39], v[80:83], v[64:67]
	v_mfma_f32_16x16x32_f16 v[36:39], v[36:39], v[92:95], v[32:35]
	v_mfma_f32_16x16x32_f16 v[32:35], v[40:43], v[72:75], v[76:79]
	v_mfma_f32_16x16x32_f16 v[68:71], v[44:47], v[80:83], v[32:35]
	v_mfma_f32_16x16x32_f16 v[32:35], v[40:43], v[88:91], v[108:111]
	v_mfma_f32_16x16x32_f16 v[44:47], v[44:47], v[92:95], v[32:35]
	v_mfma_f32_16x16x32_f16 v[32:35], v[48:51], v[72:75], v[144:147]
	v_mfma_f32_16x16x32_f16 v[96:99], v[52:55], v[80:83], v[32:35]
	v_mfma_f32_16x16x32_f16 v[32:35], v[48:51], v[88:91], v[100:103]
	v_mfma_f32_16x16x32_f16 v[52:55], v[52:55], v[92:95], v[32:35]
	v_mfma_f32_16x16x32_f16 v[32:35], v[60:63], v[72:75], v[148:151]
	v_mfma_f32_16x16x32_f16 v[100:103], v[206:209], v[80:83], v[32:35]
	v_mfma_f32_16x16x32_f16 v[32:35], v[60:63], v[88:91], v[160:163]
	v_mfma_f32_16x16x32_f16 v[60:63], v[206:209], v[92:95], v[32:35]
	s_setprio 0
	s_barrier
	ds_read_b128 v[116:119], v159 offset:49152
	ds_read_b128 v[120:123], v159 offset:50176
	ds_read_b128 v[124:127], v159 offset:51200
	ds_read_b128 v[144:147], v159 offset:52224
	ds_read_b128 v[148:151], v159 offset:53248
	ds_read_b128 v[160:163], v159 offset:54272
	ds_read_b128 v[206:209], v159 offset:55296
	ds_read_b128 v[238:241], v159 offset:56320
	s_barrier
	s_waitcnt lgkmcnt(0)
	s_setprio 1
	s_waitcnt lgkmcnt(0)
	v_mfma_f32_16x16x32_f16 v[32:35], v[116:119], v[190:193], v[210:213]
	v_mfma_f32_16x16x32_f16 v[40:43], v[124:127], v[190:193], v[214:217]
	v_mfma_f32_16x16x32_f16 v[76:79], v[148:151], v[190:193], v[222:225]
	v_mfma_f32_16x16x32_f16 v[84:87], v[206:209], v[190:193], v[128:131]
	v_mfma_f32_16x16x32_f16 v[48:51], v[120:123], v[194:197], v[32:35]
	v_mfma_f32_16x16x32_f16 v[32:35], v[116:119], v[198:201], v[56:59]
	v_mfma_f32_16x16x32_f16 v[56:59], v[144:147], v[194:197], v[40:43]
	v_mfma_f32_16x16x32_f16 v[40:43], v[124:127], v[198:201], v[218:221]
	v_mfma_f32_16x16x32_f16 v[104:107], v[160:163], v[194:197], v[76:79]
	v_mfma_f32_16x16x32_f16 v[76:79], v[148:151], v[198:201], v[226:229]
	v_mfma_f32_16x16x32_f16 v[112:115], v[238:241], v[194:197], v[84:87]
	v_mfma_f32_16x16x32_f16 v[84:87], v[206:209], v[198:201], v[132:135]
	v_mfma_f32_16x16x32_f16 v[32:35], v[120:123], v[202:205], v[32:35]
	v_mfma_f32_16x16x32_f16 v[40:43], v[144:147], v[202:205], v[40:43]
	v_mfma_f32_16x16x32_f16 v[76:79], v[160:163], v[202:205], v[76:79]
	v_mfma_f32_16x16x32_f16 v[84:87], v[238:241], v[202:205], v[84:87]
	s_setprio 0
	s_setprio 1
	v_mfma_f32_16x16x32_f16 v[108:111], v[116:119], v[72:75], v[136:139]
	v_mfma_f32_16x16x32_f16 v[116:119], v[116:119], v[88:91], v[140:143]
	v_mfma_f32_16x16x32_f16 v[108:111], v[120:123], v[80:83], v[108:111]
	v_mfma_f32_16x16x32_f16 v[128:131], v[120:123], v[92:95], v[116:119]
	v_mfma_f32_16x16x32_f16 v[120:123], v[124:127], v[88:91], v[164:167]
	v_mfma_f32_16x16x32_f16 v[116:119], v[124:127], v[72:75], v[230:233]
	v_mfma_f32_16x16x32_f16 v[132:135], v[144:147], v[92:95], v[120:123]
	v_mfma_f32_16x16x32_f16 v[120:123], v[148:151], v[72:75], v[234:237]
	v_mfma_f32_16x16x32_f16 v[72:75], v[206:209], v[72:75], v[176:179]
	v_mfma_f32_16x16x32_f16 v[116:119], v[144:147], v[80:83], v[116:119]
	v_mfma_f32_16x16x32_f16 v[144:147], v[160:163], v[80:83], v[120:123]
	v_mfma_f32_16x16x32_f16 v[120:123], v[148:151], v[88:91], v[168:171]
	v_mfma_f32_16x16x32_f16 v[148:151], v[238:241], v[80:83], v[72:75]
	v_mfma_f32_16x16x32_f16 v[72:75], v[206:209], v[88:91], v[186:189]
	v_mfma_f32_16x16x32_f16 v[136:139], v[160:163], v[92:95], v[120:123]
	v_mfma_f32_16x16x32_f16 v[140:143], v[238:241], v[92:95], v[72:75]
	s_setprio 0
	s_movk_i32 s6, 0x100
	v_cmp_gt_u32_e32 vcc, s6, v157
	s_barrier
	s_and_saveexec_b64 s[6:7], vcc
	s_cbranch_execz .LBB0_485
	s_barrier

;   #define STAGE(P,BASE,LD,br,kt) do{ const HALF* _u=(BASE)+(long)(br)*(((&(LD))==&lda)?lda_u:(LD))+(long)(kt)*G_BK; \
;     for(int _i=0;_i<2;++_i){ \
;       __builtin_amdgcn_global_load_lds((const unsigned*)(_u+(long)_i*(((&(LD))==&lda)?stepa:stepb)+((&(LD))==&lda?oa0:ob0)), \
;         (unsigned*)((char*)(P)+t5*16+_i*8192),16,0,0);}}while(0)
;   #define WAIT_V(n) asm volatile("s_waitcnt vmcnt(" #n ")":::"memory")
;   #define BAR __builtin_amdgcn_s_barrier()
; #define FOR_AI _Pragma("unroll") for (int ai = 0; ai < 2; ++ai)
; #define FOR_BJ _Pragma("unroll") for (int bj = 0; bj < 2; ++bj)
; #define FOR_M4 _Pragma("unroll") for (int m = 0; m < 4; ++m)
; #define FOR_NN _Pragma("unroll") for (int n = 0; n < 2; ++n)
;     ...
;   const int stepa = n2 ? 1024 : 64 * lda, stepb = 64 * ldb;
;   const int lda_u = n2 ? 16 : lda;
;   {int _b=t5*16;int _r,_c;g_stage_rc(_b,_r,_c);
;     oa0=n2 ? (unsigned)((n2*(_r&63)+(_r>>6))*1024+_c) : (unsigned)(_r*lda+_c); ob0=(unsigned)(_r*ldb+_c);}
;   STAGE(SB(0,0),Bt,ldb,0,0); STAGE(SA(0,0),A,lda,0,0);
;   STAGE(SB(0,1),Bt,ldb,G_HALF,0); STAGE(SA(0,1),A,lda,G_HALF,0);
;   if(wr==1)BAR;
;   WAIT_V(4); BAR;
;   STAGE(SB(1,0),Bt,ldb,0,1); STAGE(SA(1,0),A,lda,0,1); STAGE(SB(1,1),Bt,ldb,G_HALF,1);
;   WAIT_V(6); BAR;
; __device__ void job_retout_g(const P& p, int l, int job, HALF* sm) {
;     ...
;     FOR_BJ FOR_NN {
;       const int i = bj * 128 + wc * 32 + n * 16 + fr;
;       const float sc = expf(lgb * (float)(256 - i));
;       FOR_AI FOR_M4 { acc[ai][bj][m][n] *= sc; }
;     }
.LBB0_487:
	s_or_b64 exec, exec, s[6:7]
	v_pk_mul_f32 v[74:75], v[26:27], v[120:121] op_sel_hi:[1,0]
	v_pk_mul_f32 v[26:27], v[50:51], v[120:121] op_sel_hi:[1,0]
	v_pk_mul_f32 v[50:51], v[42:43], v[168:169] op_sel_hi:[1,0]
	v_pk_mul_f32 v[42:43], v[78:79], v[168:169] op_sel_hi:[1,0]
	v_pk_mul_f32 v[78:79], v[70:71], v[158:159] op_sel_hi:[1,0]
	v_pk_mul_f32 v[70:71], v[98:99], v[158:159] op_sel_hi:[1,0]
	v_pk_mul_f32 v[98:99], v[62:63], v[152:153] op_sel_hi:[1,0]
	v_pk_mul_f32 v[62:63], v[130:131], v[152:153] op_sel_hi:[1,0]
	v_lshlrev_b32_e32 v130, 6, v157
	v_lshlrev_b32_e32 v131, 2, v157
	v_pk_mul_f32 v[72:73], v[24:25], v[120:121] op_sel_hi:[1,0]
	v_pk_mul_f32 v[24:25], v[48:49], v[120:121] op_sel_hi:[1,0]
	v_pk_mul_f32 v[48:49], v[40:41], v[168:169] op_sel_hi:[1,0]
	v_pk_mul_f32 v[40:41], v[76:77], v[168:169] op_sel_hi:[1,0]
	v_pk_mul_f32 v[76:77], v[68:69], v[158:159] op_sel_hi:[1,0]
	v_pk_mul_f32 v[68:69], v[96:97], v[158:159] op_sel_hi:[1,0]
	v_pk_mul_f32 v[96:97], v[60:61], v[152:153] op_sel_hi:[1,0]
	v_pk_mul_f32 v[60:61], v[128:129], v[152:153] op_sel_hi:[1,0]
	v_and_b32_e32 v128, 48, v157
	v_and_b32_e32 v129, 0x3c0, v130
	v_and_b32_e32 v131, 32, v131
	v_bitop3_b32 v128, v129, v131, v128 bitop3:0x36
	v_add_u32_e32 v131, s29, v191
	v_pk_mul_f32 v[80:81], v[16:17], v[120:121] op_sel_hi:[1,0]
	v_readfirstlane_b32 s10, v131
	v_add_u32_e32 v131, 0x2000, v131
	v_pk_mul_f32 v[16:17], v[56:57], v[120:121] op_sel_hi:[1,0]
	v_pk_mul_f32 v[56:57], v[32:33], v[168:169] op_sel_hi:[1,0]
	v_pk_mul_f32 v[32:33], v[84:85], v[168:169] op_sel_hi:[1,0]
	v_pk_mul_f32 v[84:85], v[64:65], v[158:159] op_sel_hi:[1,0]
	v_pk_mul_f32 v[64:65], v[100:101], v[158:159] op_sel_hi:[1,0]
	v_pk_mul_f32 v[100:101], v[52:53], v[152:153] op_sel_hi:[1,0]
	v_pk_mul_f32 v[52:53], v[132:133], v[152:153] op_sel_hi:[1,0]
	v_lshl_add_u64 v[132:133], v[164:165], 0, s[84:85]
	s_mov_b32 m0, s10
	s_mov_b64 s[6:7], 0x20080
	v_readfirstlane_b32 s9, v131
	v_add_u32_e32 v131, 0x8000, v187
	global_load_lds_dwordx4 v[132:133], off
	v_lshl_add_u64 v[132:133], v[164:165], 0, s[6:7]
	s_mov_b32 m0, s9
	v_readfirstlane_b32 s8, v131
	v_add_u32_e32 v131, 0xa000, v187
	global_load_lds_dwordx4 v[132:133], off
	v_lshl_add_u64 v[132:133], v[160:161], 0, s[84:85]
	s_mov_b32 m0, s8
	s_mov_b64 s[18:19], 0x100080
	v_readfirstlane_b32 s7, v131
	v_add_u32_e32 v131, s62, v191
	global_load_lds_dwordx4 v[132:133], off
	v_lshl_add_u64 v[132:133], v[160:161], 0, s[18:19]
	s_mov_b32 m0, s7
	v_readfirstlane_b32 s6, v131
	v_add_u32_e32 v131, 0x2000, v131
	global_load_lds_dwordx4 v[132:133], off
	v_lshl_add_u64 v[132:133], v[164:165], 0, s[88:89]
	s_mov_b32 m0, s6
	v_readfirstlane_b32 s1, v131
	global_load_lds_dwordx4 v[132:133], off
	v_lshl_add_u64 v[132:133], v[164:165], 0, s[90:91]
	s_mov_b32 m0, s1
	v_and_b32_e32 v130, 0x3000, v130
	global_load_lds_dwordx4 v[132:133], off
	v_pk_mul_f32 v[94:95], v[2:3], v[120:121] op_sel_hi:[1,0]
	v_pk_mul_f32 v[92:93], v[0:1], v[120:121] op_sel_hi:[1,0]
	v_pk_mul_f32 v[90:91], v[10:11], v[120:121] op_sel_hi:[1,0]
	v_pk_mul_f32 v[88:89], v[8:9], v[120:121] op_sel_hi:[1,0]
	v_pk_mul_f32 v[82:83], v[18:19], v[120:121] op_sel_hi:[1,0]
	v_pk_mul_f32 v[18:19], v[58:59], v[120:121] op_sel_hi:[1,0]
	v_pk_mul_f32 v[10:11], v[106:107], v[120:121] op_sel_hi:[1,0]
	v_pk_mul_f32 v[8:9], v[104:105], v[120:121] op_sel_hi:[1,0]
	v_pk_mul_f32 v[2:3], v[114:115], v[120:121] op_sel_hi:[1,0]
	v_pk_mul_f32 v[0:1], v[112:113], v[120:121] op_sel_hi:[1,0]
	v_pk_mul_f32 v[114:115], v[22:23], v[168:169] op_sel_hi:[1,0]
	v_pk_mul_f32 v[112:113], v[20:21], v[168:169] op_sel_hi:[1,0]
	v_pk_mul_f32 v[106:107], v[30:31], v[168:169] op_sel_hi:[1,0]
	v_pk_mul_f32 v[104:105], v[28:29], v[168:169] op_sel_hi:[1,0]
	v_pk_mul_f32 v[58:59], v[34:35], v[168:169] op_sel_hi:[1,0]
	v_pk_mul_f32 v[34:35], v[86:87], v[168:169] op_sel_hi:[1,0]
	v_pk_mul_f32 v[86:87], v[66:67], v[158:159] op_sel_hi:[1,0]
	v_pk_mul_f32 v[66:67], v[102:103], v[158:159] op_sel_hi:[1,0]
	v_pk_mul_f32 v[30:31], v[110:111], v[158:159] op_sel_hi:[1,0]
	v_pk_mul_f32 v[28:29], v[108:109], v[158:159] op_sel_hi:[1,0]
	v_pk_mul_f32 v[22:23], v[118:119], v[158:159] op_sel_hi:[1,0]
	v_pk_mul_f32 v[20:21], v[116:117], v[158:159] op_sel_hi:[1,0]
	v_pk_mul_f32 v[118:119], v[38:39], v[152:153] op_sel_hi:[1,0]
	v_pk_mul_f32 v[116:117], v[36:37], v[152:153] op_sel_hi:[1,0]
	v_pk_mul_f32 v[110:111], v[46:47], v[152:153] op_sel_hi:[1,0]
	v_pk_mul_f32 v[108:109], v[44:45], v[152:153] op_sel_hi:[1,0]
	v_pk_mul_f32 v[102:103], v[54:55], v[152:153] op_sel_hi:[1,0]
	v_pk_mul_f32 v[54:55], v[134:135], v[152:153] op_sel_hi:[1,0]
	v_pk_mul_f32 v[46:47], v[138:139], v[152:153] op_sel_hi:[1,0]
	v_pk_mul_f32 v[44:45], v[136:137], v[152:153] op_sel_hi:[1,0]
	v_pk_mul_f32 v[38:39], v[142:143], v[152:153] op_sel_hi:[1,0]
	v_pk_mul_f32 v[36:37], v[140:141], v[152:153] op_sel_hi:[1,0]
	v_lshlrev_b32_e32 v129, 13, v192
	v_add3_u32 v152, s95, v130, v128
	s_waitcnt vmcnt(10)
	s_barrier
	s_waitcnt vmcnt(6)
	s_barrier
;   #define STAGE(P,BASE,LD,br,kt) do{ const HALF* _u=(BASE)+(long)(br)*(((&(LD))==&lda)?lda_u:(LD))+(long)(kt)*G_BK; \
;     for(int _i=0;_i<2;++_i){ \
;       __builtin_amdgcn_global_load_lds((const unsigned*)(_u+(long)_i*(((&(LD))==&lda)?stepa:stepb)+((&(LD))==&lda?oa0:ob0)), \
;         (unsigned*)((char*)(P)+t5*16+_i*8192),16,0,0);}}while(0)
;   #define LDA(dst,b,h) for(int m=0;m<4;++m)for(int k=0;k<2;++k) \
;     dst[m][k]=*reinterpret_cast<const h8*>(la+(((b)*2+(h))*16384+m*2048+k*1024))
;   #define LDB(dst,b,h) for(int n=0;n<2;++n)for(int k=0;k<2;++k) \
;     dst[n][k]=*reinterpret_cast<const h8*>(lb+(((b)*2+(h))*16384+n*2048+k*1024))
;   #define MMA(ai,bj,At,Bt_) do{__builtin_amdgcn_s_setprio(1); \
;     for(int m=0;m<4;++m)for(int n=0;n<2;++n)for(int k=0;k<2;++k) \
;       acc[ai][bj][m][n]=__builtin_amdgcn_mfma_f32_16x16x32_f16(At[m][k],Bt_[n][k],acc[ai][bj][m][n],0,0,0); \
;     __builtin_amdgcn_s_setprio(0);}while(0)
;   #define WAIT_L(n) asm volatile("s_waitcnt lgkmcnt(" #n ")":::"memory")
;   #define BAR __builtin_amdgcn_s_barrier()
;   #define SCHED __builtin_amdgcn_sched_barrier(0)
;     ...
;     LDB(B0,0,0); SCHED; LDA(At,0,0); STAGE(SA(1,1),A,lda,G_HALF,t+1);
;     WAIT_L(8); BAR; WAIT_L(0); MMA(0,0,At,B0); BAR; SCHED;
;     LDB(B1,0,1); STAGE(SB(0,0),Bt,ldb,0,t+2);
;     BAR; WAIT_L(0); MMA(0,1,At,B1); BAR;
;     LDA(At,0,1); STAGE(SA(0,0),A,lda,0,t+2);
;     BAR; WAIT_L(0); MMA(1,0,At,B0); BAR; SCHED;
	v_add3_u32 v228, 0, v129, v128
	ds_read_b128 v[128:131], v152
	ds_read_b128 v[132:135], v152 offset:1024
	ds_read_b128 v[136:139], v152 offset:2048
	ds_read_b128 v[140:143], v152 offset:3072
	v_pk_mul_f32 v[126:127], v[6:7], v[168:169] op_sel_hi:[1,0]
	v_pk_mul_f32 v[124:125], v[4:5], v[168:169] op_sel_hi:[1,0]
	v_pk_mul_f32 v[122:123], v[14:15], v[168:169] op_sel_hi:[1,0]
	v_pk_mul_f32 v[120:121], v[12:13], v[168:169] op_sel_hi:[1,0]
	v_pk_mul_f32 v[14:15], v[146:147], v[158:159] op_sel_hi:[1,0]
	v_pk_mul_f32 v[12:13], v[144:145], v[158:159] op_sel_hi:[1,0]
	v_pk_mul_f32 v[6:7], v[150:151], v[158:159] op_sel_hi:[1,0]
	v_pk_mul_f32 v[4:5], v[148:149], v[158:159] op_sel_hi:[1,0]
	v_add_u32_e32 v158, 0xc000, v187
	v_lshl_add_u64 v[168:169], v[166:167], 0, s[84:85]
	v_readfirstlane_b32 s12, v158
	v_add_u32_e32 v158, 0xe000, v187
	s_mov_b32 m0, s12
	v_readfirstlane_b32 s11, v158
	ds_read_b128 v[144:147], v228
	ds_read_b128 v[148:151], v228 offset:1024
	ds_read_b128 v[176:179], v228 offset:2048
	ds_read_b128 v[192:195], v228 offset:3072
	ds_read_b128 v[196:199], v228 offset:4096
	ds_read_b128 v[200:203], v228 offset:5120
	ds_read_b128 v[204:207], v228 offset:6144
	ds_read_b128 v[208:211], v228 offset:7168
	global_load_lds_dwordx4 v[168:169], off
	v_lshl_add_u64 v[168:169], v[166:167], 0, s[18:19]
	s_mov_b32 m0, s11
	s_nop 0
	global_load_lds_dwordx4 v[168:169], off
	s_waitcnt lgkmcnt(8)
	s_barrier
	s_waitcnt lgkmcnt(0)
	s_setprio 1
	s_waitcnt lgkmcnt(0)
	v_mfma_f32_16x16x32_f16 v[92:95], v[144:147], v[128:131], v[92:95]
	v_mfma_f32_16x16x32_f16 v[124:127], v[144:147], v[136:139], v[124:127]
	v_mfma_f32_16x16x32_f16 v[88:91], v[176:179], v[128:131], v[88:91]
	v_mfma_f32_16x16x32_f16 v[120:123], v[176:179], v[136:139], v[120:123]
	v_mfma_f32_16x16x32_f16 v[80:83], v[196:199], v[128:131], v[80:83]
	v_mfma_f32_16x16x32_f16 v[112:115], v[196:199], v[136:139], v[112:115]
	v_mfma_f32_16x16x32_f16 v[72:75], v[204:207], v[128:131], v[72:75]
	v_mfma_f32_16x16x32_f16 v[104:107], v[204:207], v[136:139], v[104:107]
	v_mfma_f32_16x16x32_f16 v[92:95], v[148:151], v[132:135], v[92:95]
	v_mfma_f32_16x16x32_f16 v[124:127], v[148:151], v[140:143], v[124:127]
	v_mfma_f32_16x16x32_f16 v[88:91], v[192:195], v[132:135], v[88:91]
	v_mfma_f32_16x16x32_f16 v[120:123], v[192:195], v[140:143], v[120:123]
	v_mfma_f32_16x16x32_f16 v[80:83], v[200:203], v[132:135], v[80:83]
	v_mfma_f32_16x16x32_f16 v[112:115], v[200:203], v[140:143], v[112:115]
	v_mfma_f32_16x16x32_f16 v[72:75], v[208:211], v[132:135], v[72:75]
	v_mfma_f32_16x16x32_f16 v[104:107], v[208:211], v[140:143], v[104:107]
	s_setprio 0
	s_barrier
	v_readfirstlane_b32 s13, v189
	v_lshl_add_u64 v[168:169], v[164:165], 0, s[92:93]
	s_mov_b32 m0, s13
	v_readfirstlane_b32 s13, v190
	ds_read_b128 v[212:215], v152 offset:16384
	ds_read_b128 v[216:219], v152 offset:17408
	ds_read_b128 v[220:223], v152 offset:18432
	ds_read_b128 v[224:227], v152 offset:19456
	global_load_lds_dwordx4 v[168:169], off
	v_lshl_add_u64 v[168:169], v[164:165], 0, s[66:67]
	s_mov_b32 m0, s13
	s_nop 0
	global_load_lds_dwordx4 v[168:169], off
	s_barrier
	s_waitcnt lgkmcnt(0)
	s_setprio 1
	s_waitcnt lgkmcnt(0)
	v_mfma_f32_16x16x32_f16 v[84:87], v[144:147], v[212:215], v[84:87]
	v_mfma_f32_16x16x32_f16 v[116:119], v[144:147], v[220:223], v[116:119]
	v_mfma_f32_16x16x32_f16 v[76:79], v[176:179], v[212:215], v[76:79]
	v_mfma_f32_16x16x32_f16 v[108:111], v[176:179], v[220:223], v[108:111]
	v_mfma_f32_16x16x32_f16 v[68:71], v[196:199], v[212:215], v[68:71]
	v_mfma_f32_16x16x32_f16 v[100:103], v[196:199], v[220:223], v[100:103]
	v_mfma_f32_16x16x32_f16 v[64:67], v[204:207], v[212:215], v[64:67]
	v_mfma_f32_16x16x32_f16 v[96:99], v[204:207], v[220:223], v[96:99]
	v_mfma_f32_16x16x32_f16 v[84:87], v[148:151], v[216:219], v[84:87]
	v_mfma_f32_16x16x32_f16 v[116:119], v[148:151], v[224:227], v[116:119]
	v_mfma_f32_16x16x32_f16 v[76:79], v[192:195], v[216:219], v[76:79]
	v_mfma_f32_16x16x32_f16 v[108:111], v[192:195], v[224:227], v[108:111]
	v_mfma_f32_16x16x32_f16 v[68:71], v[200:203], v[216:219], v[68:71]
	v_mfma_f32_16x16x32_f16 v[100:103], v[200:203], v[224:227], v[100:103]
	v_mfma_f32_16x16x32_f16 v[64:67], v[208:211], v[216:219], v[64:67]
	v_mfma_f32_16x16x32_f16 v[96:99], v[208:211], v[224:227], v[96:99]
	s_setprio 0
	v_readfirstlane_b32 s13, v187
	v_lshl_add_u64 v[168:169], v[160:161], 0, s[92:93]
	s_mov_b32 m0, s13
	s_mov_b64 s[18:19], 0x100100
	v_readfirstlane_b32 s13, v188
	s_barrier
	ds_read_b128 v[144:147], v228 offset:16384
	ds_read_b128 v[148:151], v228 offset:17408
	ds_read_b128 v[176:179], v228 offset:18432
	ds_read_b128 v[190:193], v228 offset:19456
	ds_read_b128 v[194:197], v228 offset:20480
	ds_read_b128 v[198:201], v228 offset:21504
	ds_read_b128 v[202:205], v228 offset:22528
	ds_read_b128 v[206:209], v228 offset:23552
	global_load_lds_dwordx4 v[168:169], off
	v_lshl_add_u64 v[168:169], v[160:161], 0, s[18:19]
	s_mov_b32 m0, s13
	s_nop 0
	global_load_lds_dwordx4 v[168:169], off
	s_barrier
	s_waitcnt lgkmcnt(0)
	s_setprio 1
	s_waitcnt lgkmcnt(0)
	v_mfma_f32_16x16x32_f16 v[24:27], v[144:147], v[128:131], v[24:27]
	v_mfma_f32_16x16x32_f16 v[56:59], v[144:147], v[136:139], v[56:59]
	v_mfma_f32_16x16x32_f16 v[16:19], v[176:179], v[128:131], v[16:19]
	v_mfma_f32_16x16x32_f16 v[48:51], v[176:179], v[136:139], v[48:51]
	v_mfma_f32_16x16x32_f16 v[8:11], v[194:197], v[128:131], v[8:11]
	v_mfma_f32_16x16x32_f16 v[40:43], v[194:197], v[136:139], v[40:43]
	v_mfma_f32_16x16x32_f16 v[0:3], v[202:205], v[128:131], v[0:3]
	v_mfma_f32_16x16x32_f16 v[32:35], v[202:205], v[136:139], v[32:35]
	v_mfma_f32_16x16x32_f16 v[24:27], v[148:151], v[132:135], v[24:27]
	v_mfma_f32_16x16x32_f16 v[56:59], v[148:151], v[140:143], v[56:59]
	v_mfma_f32_16x16x32_f16 v[16:19], v[190:193], v[132:135], v[16:19]
	v_mfma_f32_16x16x32_f16 v[48:51], v[190:193], v[140:143], v[48:51]
	v_mfma_f32_16x16x32_f16 v[8:11], v[198:201], v[132:135], v[8:11]
	v_mfma_f32_16x16x32_f16 v[40:43], v[198:201], v[140:143], v[40:43]
	v_mfma_f32_16x16x32_f16 v[0:3], v[206:209], v[132:135], v[0:3]
	v_mfma_f32_16x16x32_f16 v[32:35], v[206:209], v[140:143], v[32:35]
	s_setprio 0
	s_barrier
;   #define STAGE(P,BASE,LD,br,kt) do{ const HALF* _u=(BASE)+(long)(br)*(((&(LD))==&lda)?lda_u:(LD))+(long)(kt)*G_BK; \
;     for(int _i=0;_i<2;++_i){ \
;       __builtin_amdgcn_global_load_lds((const unsigned*)(_u+(long)_i*(((&(LD))==&lda)?stepa:stepb)+((&(LD))==&lda?oa0:ob0)), \
;         (unsigned*)((char*)(P)+t5*16+_i*8192),16,0,0);}}while(0)
;   #define LDA(dst,b,h) for(int m=0;m<4;++m)for(int k=0;k<2;++k) \
;     dst[m][k]=*reinterpret_cast<const h8*>(la+(((b)*2+(h))*16384+m*2048+k*1024))
;   #define LDB(dst,b,h) for(int n=0;n<2;++n)for(int k=0;k<2;++k) \
;     dst[n][k]=*reinterpret_cast<const h8*>(lb+(((b)*2+(h))*16384+n*2048+k*1024))
;   #define MMA(ai,bj,At,Bt_) do{__builtin_amdgcn_s_setprio(1); \
;     for(int m=0;m<4;++m)for(int n=0;n<2;++n)for(int k=0;k<2;++k) \
;       acc[ai][bj][m][n]=__builtin_amdgcn_mfma_f32_16x16x32_f16(At[m][k],Bt_[n][k],acc[ai][bj][m][n],0,0,0); \
;     __builtin_amdgcn_s_setprio(0);}while(0)
;   #define WAIT_V(n) asm volatile("s_waitcnt vmcnt(" #n ")":::"memory")
;   #define WAIT_L(n) asm volatile("s_waitcnt lgkmcnt(" #n ")":::"memory")
;   #define BAR __builtin_amdgcn_s_barrier()
;   #define SCHED __builtin_amdgcn_sched_barrier(0)
;     ...
;     STAGE(SB(0,1),Bt,ldb,G_HALF,t+2);
;     WAIT_V(6); BAR; MMA(1,1,At,B1); BAR;
;     LDB(B0,1,0); SCHED; LDA(At,1,0); STAGE(SA(0,1),A,lda,G_HALF,t+2);
;     WAIT_L(8); BAR; WAIT_L(0); MMA(0,0,At,B0); BAR; SCHED;
;     LDB(B1,1,1); STAGE(SB(1,0),Bt,ldb,0,t+3);
;     BAR; WAIT_L(0); MMA(0,1,At,B1); BAR;
;     LDA(At,1,1); STAGE(SA(1,0),A,lda,0,t+3);
	v_readfirstlane_b32 s13, v172
	v_lshl_add_u64 v[128:129], v[162:163], 0, s[92:93]
	s_mov_b32 m0, s13
	v_readfirstlane_b32 s13, v186
	global_load_lds_dwordx4 v[128:129], off
	v_lshl_add_u64 v[128:129], v[162:163], 0, s[66:67]
	s_mov_b32 m0, s13
	s_nop 0
	global_load_lds_dwordx4 v[128:129], off
	s_waitcnt vmcnt(6)
	s_barrier
	s_setprio 1
	v_mfma_f32_16x16x32_f16 v[28:31], v[144:147], v[212:215], v[28:31]
	v_mfma_f32_16x16x32_f16 v[60:63], v[144:147], v[220:223], v[60:63]
	v_mfma_f32_16x16x32_f16 v[20:23], v[176:179], v[212:215], v[20:23]
	v_mfma_f32_16x16x32_f16 v[52:55], v[176:179], v[220:223], v[52:55]
	v_mfma_f32_16x16x32_f16 v[12:15], v[194:197], v[212:215], v[12:15]
	v_mfma_f32_16x16x32_f16 v[44:47], v[194:197], v[220:223], v[44:47]
	v_mfma_f32_16x16x32_f16 v[4:7], v[202:205], v[212:215], v[4:7]
	v_mfma_f32_16x16x32_f16 v[36:39], v[202:205], v[220:223], v[36:39]
	v_mfma_f32_16x16x32_f16 v[28:31], v[148:151], v[216:219], v[28:31]
	v_mfma_f32_16x16x32_f16 v[60:63], v[148:151], v[224:227], v[60:63]
	v_mfma_f32_16x16x32_f16 v[20:23], v[190:193], v[216:219], v[20:23]
	v_mfma_f32_16x16x32_f16 v[52:55], v[190:193], v[224:227], v[52:55]
	v_mfma_f32_16x16x32_f16 v[12:15], v[198:201], v[216:219], v[12:15]
	v_mfma_f32_16x16x32_f16 v[44:47], v[198:201], v[224:227], v[44:47]
	v_mfma_f32_16x16x32_f16 v[4:7], v[206:209], v[216:219], v[4:7]
	v_mfma_f32_16x16x32_f16 v[36:39], v[206:209], v[224:227], v[36:39]
	s_setprio 0
	s_barrier
	ds_read_b128 v[128:131], v152 offset:32768
	ds_read_b128 v[132:135], v152 offset:33792
	ds_read_b128 v[136:139], v152 offset:34816
	ds_read_b128 v[140:143], v152 offset:35840
	v_readfirstlane_b32 s13, v159
	v_lshl_add_u64 v[168:169], v[166:167], 0, s[92:93]
	s_mov_b32 m0, s13
	v_readfirstlane_b32 s13, v170
	ds_read_b128 v[144:147], v228 offset:32768
	ds_read_b128 v[148:151], v228 offset:33792
	ds_read_b128 v[176:179], v228 offset:34816
	ds_read_b128 v[186:189], v228 offset:35840
	ds_read_b128 v[190:193], v228 offset:36864
	ds_read_b128 v[194:197], v228 offset:37888
	ds_read_b128 v[198:201], v228 offset:38912
	ds_read_b128 v[202:205], v228 offset:39936
	global_load_lds_dwordx4 v[168:169], off
	v_lshl_add_u64 v[158:159], v[166:167], 0, s[18:19]
	s_mov_b32 m0, s13
	s_nop 0
	global_load_lds_dwordx4 v[158:159], off
	s_waitcnt lgkmcnt(8)
	s_barrier
	s_waitcnt lgkmcnt(0)
	s_setprio 1
	s_waitcnt lgkmcnt(0)
	v_mfma_f32_16x16x32_f16 v[92:95], v[144:147], v[128:131], v[92:95]
	v_mfma_f32_16x16x32_f16 v[124:127], v[144:147], v[136:139], v[124:127]
	v_mfma_f32_16x16x32_f16 v[88:91], v[176:179], v[128:131], v[88:91]
	v_mfma_f32_16x16x32_f16 v[120:123], v[176:179], v[136:139], v[120:123]
	v_mfma_f32_16x16x32_f16 v[80:83], v[190:193], v[128:131], v[80:83]
	v_mfma_f32_16x16x32_f16 v[112:115], v[190:193], v[136:139], v[112:115]
	v_mfma_f32_16x16x32_f16 v[72:75], v[198:201], v[128:131], v[72:75]
	v_mfma_f32_16x16x32_f16 v[104:107], v[198:201], v[136:139], v[104:107]
	v_mfma_f32_16x16x32_f16 v[92:95], v[148:151], v[132:135], v[92:95]
	v_mfma_f32_16x16x32_f16 v[124:127], v[148:151], v[140:143], v[124:127]
	v_mfma_f32_16x16x32_f16 v[88:91], v[186:189], v[132:135], v[88:91]
	v_mfma_f32_16x16x32_f16 v[120:123], v[186:189], v[140:143], v[120:123]
	v_mfma_f32_16x16x32_f16 v[80:83], v[194:197], v[132:135], v[80:83]
	v_mfma_f32_16x16x32_f16 v[112:115], v[194:197], v[140:143], v[112:115]
	v_mfma_f32_16x16x32_f16 v[72:75], v[202:205], v[132:135], v[72:75]
	v_mfma_f32_16x16x32_f16 v[104:107], v[202:205], v[140:143], v[104:107]
	s_setprio 0
	s_barrier
	s_mov_b32 m0, s10
	v_lshl_add_u64 v[158:159], v[164:165], 0, s[42:43]
	ds_read_b128 v[166:169], v152 offset:49152
	ds_read_b128 v[170:173], v152 offset:50176
	ds_read_b128 v[206:209], v152 offset:51200
	ds_read_b128 v[210:213], v152 offset:52224
	global_load_lds_dwordx4 v[158:159], off
	v_lshl_add_u64 v[158:159], v[164:165], 0, s[96:97]
	s_mov_b32 m0, s9
	s_nop 0
	global_load_lds_dwordx4 v[158:159], off
	s_barrier
	s_waitcnt lgkmcnt(0)
	s_setprio 1
	s_waitcnt lgkmcnt(0)
	v_mfma_f32_16x16x32_f16 v[84:87], v[144:147], v[166:169], v[84:87]
	v_mfma_f32_16x16x32_f16 v[116:119], v[144:147], v[206:209], v[116:119]
	v_mfma_f32_16x16x32_f16 v[76:79], v[176:179], v[166:169], v[76:79]
	v_mfma_f32_16x16x32_f16 v[108:111], v[176:179], v[206:209], v[108:111]
	v_mfma_f32_16x16x32_f16 v[68:71], v[190:193], v[166:169], v[68:71]
	v_mfma_f32_16x16x32_f16 v[100:103], v[190:193], v[206:209], v[100:103]
	v_mfma_f32_16x16x32_f16 v[64:67], v[198:201], v[166:169], v[64:67]
	v_mfma_f32_16x16x32_f16 v[96:99], v[198:201], v[206:209], v[96:99]
	v_mfma_f32_16x16x32_f16 v[84:87], v[148:151], v[170:173], v[84:87]
	v_mfma_f32_16x16x32_f16 v[116:119], v[148:151], v[210:213], v[116:119]
	v_mfma_f32_16x16x32_f16 v[76:79], v[186:189], v[170:173], v[76:79]
	v_mfma_f32_16x16x32_f16 v[108:111], v[186:189], v[210:213], v[108:111]
	v_mfma_f32_16x16x32_f16 v[68:71], v[194:197], v[170:173], v[68:71]
	v_mfma_f32_16x16x32_f16 v[100:103], v[194:197], v[210:213], v[100:103]
	v_mfma_f32_16x16x32_f16 v[64:67], v[202:205], v[170:173], v[64:67]
	v_mfma_f32_16x16x32_f16 v[96:99], v[202:205], v[210:213], v[96:99]
	s_setprio 0
	s_mov_b32 m0, s8
	v_lshl_add_u64 v[158:159], v[160:161], 0, s[42:43]
	s_mov_b64 s[8:9], 0x100180
	s_barrier
	ds_read_b128 v[144:147], v228 offset:49152
	ds_read_b128 v[148:151], v228 offset:50176
	ds_read_b128 v[176:179], v228 offset:51200
	ds_read_b128 v[186:189], v228 offset:52224
	ds_read_b128 v[190:193], v228 offset:53248
	ds_read_b128 v[194:197], v228 offset:54272
	ds_read_b128 v[198:201], v228 offset:55296
	ds_read_b128 v[202:205], v228 offset:56320
	global_load_lds_dwordx4 v[158:159], off
	v_lshl_add_u64 v[158:159], v[160:161], 0, s[8:9]
	s_mov_b32 m0, s7
	s_nop 0
	global_load_lds_dwordx4 v[158:159], off
	s_barrier
;   #define STAGE(P,BASE,LD,br,kt) do{ const HALF* _u=(BASE)+(long)(br)*(((&(LD))==&lda)?lda_u:(LD))+(long)(kt)*G_BK; \
;     for(int _i=0;_i<2;++_i){ \
;       __builtin_amdgcn_global_load_lds((const unsigned*)(_u+(long)_i*(((&(LD))==&lda)?stepa:stepb)+((&(LD))==&lda?oa0:ob0)), \
;         (unsigned*)((char*)(P)+t5*16+_i*8192),16,0,0);}}while(0)
;   #define LDA(dst,b,h) for(int m=0;m<4;++m)for(int k=0;k<2;++k) \
;     dst[m][k]=*reinterpret_cast<const h8*>(la+(((b)*2+(h))*16384+m*2048+k*1024))
;   #define LDB(dst,b,h) for(int n=0;n<2;++n)for(int k=0;k<2;++k) \
;     dst[n][k]=*reinterpret_cast<const h8*>(lb+(((b)*2+(h))*16384+n*2048+k*1024))
;   #define MMA(ai,bj,At,Bt_) do{__builtin_amdgcn_s_setprio(1); \
;     for(int m=0;m<4;++m)for(int n=0;n<2;++n)for(int k=0;k<2;++k) \
;       acc[ai][bj][m][n]=__builtin_amdgcn_mfma_f32_16x16x32_f16(At[m][k],Bt_[n][k],acc[ai][bj][m][n],0,0,0); \
;     __builtin_amdgcn_s_setprio(0);}while(0)
;   #define WAIT_V(n) asm volatile("s_waitcnt vmcnt(" #n ")":::"memory")
;   #define WAIT_L(n) asm volatile("s_waitcnt lgkmcnt(" #n ")":::"memory")
;   #define BAR __builtin_amdgcn_s_barrier()
;   #define SCHED __builtin_amdgcn_sched_barrier(0)
;     ...
;     BAR; WAIT_L(0); MMA(1,0,At,B0); BAR; SCHED;
;     STAGE(SB(1,1),Bt,ldb,G_HALF,t+3);
;     WAIT_V(6); BAR; MMA(1,1,At,B1); BAR;
;   }
;   { LDB(B0,0,0); LDA(At,0,0); STAGE(SA(1,1),A,lda,G_HALF,nt-1);
;     BAR; WAIT_L(0); MMA(0,0,At,B0); BAR;
;     LDB(B1,0,1); BAR; WAIT_L(0); MMA(0,1,At,B1); BAR;
	s_waitcnt lgkmcnt(0)
	s_setprio 1
	s_waitcnt lgkmcnt(0)
	v_mfma_f32_16x16x32_f16 v[24:27], v[144:147], v[128:131], v[24:27]
	v_mfma_f32_16x16x32_f16 v[56:59], v[144:147], v[136:139], v[56:59]
	v_mfma_f32_16x16x32_f16 v[16:19], v[176:179], v[128:131], v[16:19]
	v_mfma_f32_16x16x32_f16 v[48:51], v[176:179], v[136:139], v[48:51]
	v_mfma_f32_16x16x32_f16 v[8:11], v[190:193], v[128:131], v[8:11]
	v_mfma_f32_16x16x32_f16 v[40:43], v[190:193], v[136:139], v[40:43]
	v_mfma_f32_16x16x32_f16 v[0:3], v[198:201], v[128:131], v[0:3]
	v_mfma_f32_16x16x32_f16 v[32:35], v[198:201], v[136:139], v[32:35]
	v_mfma_f32_16x16x32_f16 v[24:27], v[148:151], v[132:135], v[24:27]
	v_mfma_f32_16x16x32_f16 v[56:59], v[148:151], v[140:143], v[56:59]
	v_mfma_f32_16x16x32_f16 v[16:19], v[186:189], v[132:135], v[16:19]
	v_mfma_f32_16x16x32_f16 v[48:51], v[186:189], v[140:143], v[48:51]
	v_mfma_f32_16x16x32_f16 v[8:11], v[194:197], v[132:135], v[8:11]
	v_mfma_f32_16x16x32_f16 v[40:43], v[194:197], v[140:143], v[40:43]
	v_mfma_f32_16x16x32_f16 v[0:3], v[202:205], v[132:135], v[0:3]
	v_mfma_f32_16x16x32_f16 v[32:35], v[202:205], v[140:143], v[32:35]
	s_setprio 0
	s_barrier
	s_mov_b32 m0, s6
	v_lshl_add_u64 v[128:129], v[162:163], 0, s[42:43]
	global_load_lds_dwordx4 v[128:129], off
	v_lshl_add_u64 v[128:129], v[162:163], 0, s[96:97]
	s_mov_b32 m0, s1
	s_nop 0
	global_load_lds_dwordx4 v[128:129], off
	s_waitcnt vmcnt(6)
	s_barrier
	s_setprio 1
	v_mfma_f32_16x16x32_f16 v[28:31], v[144:147], v[166:169], v[28:31]
	v_mfma_f32_16x16x32_f16 v[60:63], v[144:147], v[206:209], v[60:63]
	v_mfma_f32_16x16x32_f16 v[20:23], v[176:179], v[166:169], v[20:23]
	v_mfma_f32_16x16x32_f16 v[52:55], v[176:179], v[206:209], v[52:55]
	v_mfma_f32_16x16x32_f16 v[12:15], v[190:193], v[166:169], v[12:15]
	v_mfma_f32_16x16x32_f16 v[44:47], v[190:193], v[206:209], v[44:47]
	v_mfma_f32_16x16x32_f16 v[4:7], v[198:201], v[166:169], v[4:7]
	v_mfma_f32_16x16x32_f16 v[36:39], v[198:201], v[206:209], v[36:39]
	v_mfma_f32_16x16x32_f16 v[28:31], v[148:151], v[170:173], v[28:31]
	v_mfma_f32_16x16x32_f16 v[60:63], v[148:151], v[210:213], v[60:63]
	v_mfma_f32_16x16x32_f16 v[20:23], v[186:189], v[170:173], v[20:23]
	v_mfma_f32_16x16x32_f16 v[52:55], v[186:189], v[210:213], v[52:55]
	v_mfma_f32_16x16x32_f16 v[12:15], v[194:197], v[170:173], v[12:15]
	v_mfma_f32_16x16x32_f16 v[44:47], v[194:197], v[210:213], v[44:47]
	v_mfma_f32_16x16x32_f16 v[4:7], v[202:205], v[170:173], v[4:7]
	v_mfma_f32_16x16x32_f16 v[36:39], v[202:205], v[210:213], v[36:39]
	s_setprio 0
	s_mov_b64 s[6:7], 0x200180
	s_mov_b32 m0, s12
	v_lshl_add_u64 v[158:159], v[160:161], 0, s[6:7]
	s_mov_b64 s[6:7], 0x300180
	s_barrier
	ds_read_b128 v[128:131], v152
	ds_read_b128 v[132:135], v152 offset:1024
	ds_read_b128 v[136:139], v152 offset:2048
	ds_read_b128 v[140:143], v152 offset:3072
	ds_read_b128 v[144:147], v228
	ds_read_b128 v[148:151], v228 offset:1024
	ds_read_b128 v[162:165], v228 offset:2048
	ds_read_b128 v[166:169], v228 offset:3072
	ds_read_b128 v[170:173], v228 offset:4096
	ds_read_b128 v[176:179], v228 offset:5120
	ds_read_b128 v[186:189], v228 offset:6144
	ds_read_b128 v[190:193], v228 offset:7168
	global_load_lds_dwordx4 v[158:159], off
	v_lshl_add_u64 v[158:159], v[160:161], 0, s[6:7]
	s_mov_b32 m0, s11
	s_nop 0
	global_load_lds_dwordx4 v[158:159], off
	s_barrier
	s_waitcnt lgkmcnt(0)
	s_setprio 1
	s_waitcnt lgkmcnt(0)
	v_mfma_f32_16x16x32_f16 v[92:95], v[144:147], v[128:131], v[92:95]
	v_mfma_f32_16x16x32_f16 v[88:91], v[162:165], v[128:131], v[88:91]
	v_mfma_f32_16x16x32_f16 v[80:83], v[170:173], v[128:131], v[80:83]
	v_mfma_f32_16x16x32_f16 v[72:75], v[186:189], v[128:131], v[72:75]
	v_mfma_f32_16x16x32_f16 v[104:107], v[186:189], v[136:139], v[104:107]
	v_mfma_f32_16x16x32_f16 v[92:95], v[148:151], v[132:135], v[92:95]
	v_mfma_f32_16x16x32_f16 v[124:127], v[144:147], v[136:139], v[124:127]
	v_mfma_f32_16x16x32_f16 v[88:91], v[166:169], v[132:135], v[88:91]
	v_mfma_f32_16x16x32_f16 v[120:123], v[162:165], v[136:139], v[120:123]
	v_mfma_f32_16x16x32_f16 v[80:83], v[176:179], v[132:135], v[80:83]
	v_mfma_f32_16x16x32_f16 v[112:115], v[170:173], v[136:139], v[112:115]
	v_mfma_f32_16x16x32_f16 v[72:75], v[190:193], v[132:135], v[72:75]
	v_mfma_f32_16x16x32_f16 v[104:107], v[190:193], v[140:143], v[104:107]
	v_mfma_f32_16x16x32_f16 v[158:161], v[148:151], v[140:143], v[124:127]
	v_mfma_f32_16x16x32_f16 v[194:197], v[166:169], v[140:143], v[120:123]
	v_mfma_f32_16x16x32_f16 v[198:201], v[176:179], v[140:143], v[112:115]
	s_setprio 0
	s_barrier
	s_nop 0
	ds_read_b128 v[112:115], v152 offset:16384
	ds_read_b128 v[120:123], v152 offset:17408
	ds_read_b128 v[124:127], v152 offset:18432
	ds_read_b128 v[202:205], v152 offset:19456
	s_barrier
	s_waitcnt lgkmcnt(0)
	s_setprio 1
	s_waitcnt lgkmcnt(0)
	v_mfma_f32_16x16x32_f16 v[84:87], v[144:147], v[112:115], v[84:87]
	v_mfma_f32_16x16x32_f16 v[76:79], v[162:165], v[112:115], v[76:79]
	v_mfma_f32_16x16x32_f16 v[68:71], v[170:173], v[112:115], v[68:71]
	v_mfma_f32_16x16x32_f16 v[64:67], v[186:189], v[112:115], v[64:67]
	v_mfma_f32_16x16x32_f16 v[84:87], v[148:151], v[120:123], v[84:87]
	v_mfma_f32_16x16x32_f16 v[116:119], v[144:147], v[124:127], v[116:119]
	v_mfma_f32_16x16x32_f16 v[76:79], v[166:169], v[120:123], v[76:79]
	v_mfma_f32_16x16x32_f16 v[108:111], v[162:165], v[124:127], v[108:111]
	v_mfma_f32_16x16x32_f16 v[68:71], v[176:179], v[120:123], v[68:71]
	v_mfma_f32_16x16x32_f16 v[100:103], v[170:173], v[124:127], v[100:103]
	v_mfma_f32_16x16x32_f16 v[64:67], v[190:193], v[120:123], v[64:67]
	v_mfma_f32_16x16x32_f16 v[96:99], v[186:189], v[124:127], v[96:99]
	v_mfma_f32_16x16x32_f16 v[144:147], v[148:151], v[202:205], v[116:119]
	v_mfma_f32_16x16x32_f16 v[148:151], v[166:169], v[202:205], v[108:111]
	v_mfma_f32_16x16x32_f16 v[162:165], v[176:179], v[202:205], v[100:103]
	v_mfma_f32_16x16x32_f16 v[166:169], v[190:193], v[202:205], v[96:99]
	s_setprio 0
	s_barrier
;   #define LDA(dst,b,h) for(int m=0;m<4;++m)for(int k=0;k<2;++k) \
;     dst[m][k]=*reinterpret_cast<const h8*>(la+(((b)*2+(h))*16384+m*2048+k*1024))
;   #define LDB(dst,b,h) for(int n=0;n<2;++n)for(int k=0;k<2;++k) \
;     dst[n][k]=*reinterpret_cast<const h8*>(lb+(((b)*2+(h))*16384+n*2048+k*1024))
;   #define MMA(ai,bj,At,Bt_) do{__builtin_amdgcn_s_setprio(1); \
;     for(int m=0;m<4;++m)for(int n=0;n<2;++n)for(int k=0;k<2;++k) \
;       acc[ai][bj][m][n]=__builtin_amdgcn_mfma_f32_16x16x32_f16(At[m][k],Bt_[n][k],acc[ai][bj][m][n],0,0,0); \
;     __builtin_amdgcn_s_setprio(0);}while(0)
;   #define WAIT_V(n) asm volatile("s_waitcnt vmcnt(" #n ")":::"memory")
;   #define WAIT_L(n) asm volatile("s_waitcnt lgkmcnt(" #n ")":::"memory")
;   #define BAR __builtin_amdgcn_s_barrier()
;     ...
;     LDA(At,0,1); WAIT_V(4); BAR; WAIT_L(0); MMA(1,0,At,B0); MMA(1,1,At,B1); BAR; }
;   { LDB(B0,1,0); LDA(At,1,0); WAIT_V(2); BAR; WAIT_L(0); MMA(0,0,At,B0); BAR;
	s_nop 1
	ds_read_b128 v[96:99], v228 offset:16384
	ds_read_b128 v[100:103], v228 offset:17408
	ds_read_b128 v[108:111], v228 offset:18432
	ds_read_b128 v[116:119], v228 offset:19456
	ds_read_b128 v[170:173], v228 offset:20480
	ds_read_b128 v[176:179], v228 offset:21504
	ds_read_b128 v[186:189], v228 offset:22528
	ds_read_b128 v[190:193], v228 offset:23552
	s_waitcnt vmcnt(4)
	s_barrier
	s_waitcnt lgkmcnt(0)
	s_setprio 1
	s_waitcnt lgkmcnt(0)
	v_mfma_f32_16x16x32_f16 v[24:27], v[96:99], v[128:131], v[24:27]
	v_mfma_f32_16x16x32_f16 v[56:59], v[96:99], v[136:139], v[56:59]
	v_mfma_f32_16x16x32_f16 v[16:19], v[108:111], v[128:131], v[16:19]
	v_mfma_f32_16x16x32_f16 v[8:11], v[170:173], v[128:131], v[8:11]
	v_mfma_f32_16x16x32_f16 v[40:43], v[170:173], v[136:139], v[40:43]
	v_mfma_f32_16x16x32_f16 v[0:3], v[186:189], v[128:131], v[0:3]
	v_mfma_f32_16x16x32_f16 v[32:35], v[186:189], v[136:139], v[32:35]
	v_mfma_f32_16x16x32_f16 v[24:27], v[100:103], v[132:135], v[24:27]
	v_mfma_f32_16x16x32_f16 v[56:59], v[100:103], v[140:143], v[56:59]
	v_mfma_f32_16x16x32_f16 v[16:19], v[116:119], v[132:135], v[16:19]
	v_mfma_f32_16x16x32_f16 v[48:51], v[108:111], v[136:139], v[48:51]
	v_mfma_f32_16x16x32_f16 v[8:11], v[176:179], v[132:135], v[8:11]
	v_mfma_f32_16x16x32_f16 v[40:43], v[176:179], v[140:143], v[40:43]
	v_mfma_f32_16x16x32_f16 v[0:3], v[190:193], v[132:135], v[0:3]
	v_mfma_f32_16x16x32_f16 v[32:35], v[190:193], v[140:143], v[32:35]
	v_mfma_f32_16x16x32_f16 v[206:209], v[116:119], v[140:143], v[48:51]
	s_setprio 0
	s_setprio 1
	v_mfma_f32_16x16x32_f16 v[28:31], v[96:99], v[112:115], v[28:31]
	v_mfma_f32_16x16x32_f16 v[48:51], v[96:99], v[124:127], v[60:63]
	v_mfma_f32_16x16x32_f16 v[20:23], v[108:111], v[112:115], v[20:23]
	v_mfma_f32_16x16x32_f16 v[12:15], v[170:173], v[112:115], v[12:15]
	v_mfma_f32_16x16x32_f16 v[4:7], v[186:189], v[112:115], v[4:7]
	v_mfma_f32_16x16x32_f16 v[28:31], v[100:103], v[120:123], v[28:31]
	v_mfma_f32_16x16x32_f16 v[128:131], v[100:103], v[202:205], v[48:51]
	v_mfma_f32_16x16x32_f16 v[20:23], v[116:119], v[120:123], v[20:23]
	v_mfma_f32_16x16x32_f16 v[48:51], v[108:111], v[124:127], v[52:55]
	v_mfma_f32_16x16x32_f16 v[12:15], v[176:179], v[120:123], v[12:15]
	v_mfma_f32_16x16x32_f16 v[44:47], v[170:173], v[124:127], v[44:47]
	v_mfma_f32_16x16x32_f16 v[4:7], v[190:193], v[120:123], v[4:7]
	v_mfma_f32_16x16x32_f16 v[36:39], v[186:189], v[124:127], v[36:39]
	v_mfma_f32_16x16x32_f16 v[132:135], v[116:119], v[202:205], v[48:51]
	v_mfma_f32_16x16x32_f16 v[136:139], v[176:179], v[202:205], v[44:47]
	v_mfma_f32_16x16x32_f16 v[140:143], v[190:193], v[202:205], v[36:39]
	s_setprio 0
	s_barrier
	s_nop 2
	ds_read_b128 v[36:39], v152 offset:32768
	ds_read_b128 v[170:173], v152 offset:33792
	ds_read_b128 v[176:179], v152 offset:34816
	ds_read_b128 v[186:189], v152 offset:35840
	ds_read_b128 v[44:47], v228 offset:32768
	ds_read_b128 v[48:51], v228 offset:33792
	ds_read_b128 v[52:55], v228 offset:34816
	ds_read_b128 v[60:63], v228 offset:35840
	ds_read_b128 v[190:193], v228 offset:36864
	ds_read_b128 v[202:205], v228 offset:37888
	ds_read_b128 v[210:213], v228 offset:38912
	ds_read_b128 v[214:217], v228 offset:39936
	s_waitcnt vmcnt(2)
	s_barrier
	s_waitcnt lgkmcnt(0)
	s_setprio 1
	s_waitcnt lgkmcnt(0)
	v_mfma_f32_16x16x32_f16 v[92:95], v[44:47], v[36:39], v[92:95]
	v_mfma_f32_16x16x32_f16 v[88:91], v[52:55], v[36:39], v[88:91]
	v_mfma_f32_16x16x32_f16 v[80:83], v[190:193], v[36:39], v[80:83]
	v_mfma_f32_16x16x32_f16 v[72:75], v[210:213], v[36:39], v[72:75]
	v_mfma_f32_16x16x32_f16 v[124:127], v[48:51], v[170:173], v[92:95]
	v_mfma_f32_16x16x32_f16 v[92:95], v[44:47], v[176:179], v[158:161]
	v_mfma_f32_16x16x32_f16 v[116:119], v[60:63], v[170:173], v[88:91]
	v_mfma_f32_16x16x32_f16 v[88:91], v[52:55], v[176:179], v[194:197]
	v_mfma_f32_16x16x32_f16 v[108:111], v[202:205], v[170:173], v[80:83]
	v_mfma_f32_16x16x32_f16 v[80:83], v[190:193], v[176:179], v[198:201]
	v_mfma_f32_16x16x32_f16 v[96:99], v[214:217], v[170:173], v[72:75]
	v_mfma_f32_16x16x32_f16 v[72:75], v[210:213], v[176:179], v[104:107]
	v_mfma_f32_16x16x32_f16 v[120:123], v[48:51], v[186:189], v[92:95]
	v_mfma_f32_16x16x32_f16 v[112:115], v[60:63], v[186:189], v[88:91]
	v_mfma_f32_16x16x32_f16 v[100:103], v[202:205], v[186:189], v[80:83]
	v_mfma_f32_16x16x32_f16 v[88:91], v[214:217], v[186:189], v[72:75]
	s_setprio 0
	s_barrier
;   #define LDA(dst,b,h) for(int m=0;m<4;++m)for(int k=0;k<2;++k) \
;     dst[m][k]=*reinterpret_cast<const h8*>(la+(((b)*2+(h))*16384+m*2048+k*1024))
;   #define LDB(dst,b,h) for(int n=0;n<2;++n)for(int k=0;k<2;++k) \
;     dst[n][k]=*reinterpret_cast<const h8*>(lb+(((b)*2+(h))*16384+n*2048+k*1024))
;   #define MMA(ai,bj,At,Bt_) do{__builtin_amdgcn_s_setprio(1); \
;     for(int m=0;m<4;++m)for(int n=0;n<2;++n)for(int k=0;k<2;++k) \
;       acc[ai][bj][m][n]=__builtin_amdgcn_mfma_f32_16x16x32_f16(At[m][k],Bt_[n][k],acc[ai][bj][m][n],0,0,0); \
;     __builtin_amdgcn_s_setprio(0);}while(0)
;   #define WAIT_V(n) asm volatile("s_waitcnt vmcnt(" #n ")":::"memory")
;   #define WAIT_L(n) asm volatile("s_waitcnt lgkmcnt(" #n ")":::"memory")
;   #define BAR __builtin_amdgcn_s_barrier()
;     ...
;     LDB(B1,1,1); WAIT_V(0); BAR; WAIT_L(0); MMA(0,1,At,B1); BAR;
;     LDA(At,1,1); BAR; WAIT_L(0); MMA(1,0,At,B0); MMA(1,1,At,B1); BAR; }
;   if(wr==0)BAR;
	ds_read_b128 v[158:161], v152 offset:49152
	ds_read_b128 v[194:197], v152 offset:50176
	ds_read_b128 v[198:201], v152 offset:51200
	ds_read_b128 v[218:221], v152 offset:52224
	s_waitcnt vmcnt(0)
	s_barrier
	s_waitcnt lgkmcnt(0)
	s_setprio 1
	s_waitcnt lgkmcnt(0)
	v_mfma_f32_16x16x32_f16 v[72:75], v[44:47], v[158:161], v[84:87]
	v_mfma_f32_16x16x32_f16 v[44:47], v[44:47], v[198:201], v[144:147]
	v_mfma_f32_16x16x32_f16 v[92:95], v[48:51], v[218:221], v[44:47]
	v_mfma_f32_16x16x32_f16 v[44:47], v[52:55], v[158:161], v[76:79]
	v_mfma_f32_16x16x32_f16 v[84:87], v[60:63], v[194:197], v[44:47]
	v_mfma_f32_16x16x32_f16 v[44:47], v[52:55], v[198:201], v[148:151]
	v_mfma_f32_16x16x32_f16 v[80:83], v[60:63], v[218:221], v[44:47]
	v_mfma_f32_16x16x32_f16 v[44:47], v[190:193], v[158:161], v[68:71]
	v_mfma_f32_16x16x32_f16 v[76:79], v[202:205], v[194:197], v[44:47]
	v_mfma_f32_16x16x32_f16 v[44:47], v[190:193], v[198:201], v[162:165]
	v_mfma_f32_16x16x32_f16 v[68:71], v[202:205], v[218:221], v[44:47]
	v_mfma_f32_16x16x32_f16 v[44:47], v[210:213], v[158:161], v[64:67]
	v_mfma_f32_16x16x32_f16 v[60:63], v[214:217], v[194:197], v[44:47]
	v_mfma_f32_16x16x32_f16 v[44:47], v[210:213], v[198:201], v[166:169]
	v_mfma_f32_16x16x32_f16 v[104:107], v[48:51], v[194:197], v[72:75]
	v_mfma_f32_16x16x32_f16 v[48:51], v[214:217], v[218:221], v[44:47]
	s_setprio 0
	s_barrier
	ds_read_b128 v[144:147], v228 offset:49152
	ds_read_b128 v[148:151], v228 offset:50176
	ds_read_b128 v[162:165], v228 offset:51200
	ds_read_b128 v[166:169], v228 offset:52224
	ds_read_b128 v[190:193], v228 offset:53248
	ds_read_b128 v[202:205], v228 offset:54272
	ds_read_b128 v[210:213], v228 offset:55296
	ds_read_b128 v[214:217], v228 offset:56320
	s_barrier
	s_waitcnt lgkmcnt(0)
	s_setprio 1
	s_waitcnt lgkmcnt(0)
	v_mfma_f32_16x16x32_f16 v[24:27], v[144:147], v[36:39], v[24:27]
	v_mfma_f32_16x16x32_f16 v[16:19], v[162:165], v[36:39], v[16:19]
	v_mfma_f32_16x16x32_f16 v[8:11], v[190:193], v[36:39], v[8:11]
	v_mfma_f32_16x16x32_f16 v[0:3], v[210:213], v[36:39], v[0:3]
	v_mfma_f32_16x16x32_f16 v[72:75], v[148:151], v[170:173], v[24:27]
	v_mfma_f32_16x16x32_f16 v[24:27], v[144:147], v[176:179], v[56:59]
	v_mfma_f32_16x16x32_f16 v[56:59], v[166:169], v[170:173], v[16:19]
	v_mfma_f32_16x16x32_f16 v[16:19], v[162:165], v[176:179], v[206:209]
	v_mfma_f32_16x16x32_f16 v[44:47], v[202:205], v[170:173], v[8:11]
	v_mfma_f32_16x16x32_f16 v[8:11], v[190:193], v[176:179], v[40:43]
	v_mfma_f32_16x16x32_f16 v[36:39], v[214:217], v[170:173], v[0:3]
	v_mfma_f32_16x16x32_f16 v[0:3], v[210:213], v[176:179], v[32:35]
	v_mfma_f32_16x16x32_f16 v[64:67], v[148:151], v[186:189], v[24:27]
	v_mfma_f32_16x16x32_f16 v[52:55], v[166:169], v[186:189], v[16:19]
	v_mfma_f32_16x16x32_f16 v[40:43], v[202:205], v[186:189], v[8:11]
	v_mfma_f32_16x16x32_f16 v[32:35], v[214:217], v[186:189], v[0:3]
	s_setprio 0
	s_setprio 1
	v_mfma_f32_16x16x32_f16 v[0:3], v[144:147], v[158:161], v[28:31]
	v_mfma_f32_16x16x32_f16 v[28:31], v[148:151], v[194:197], v[0:3]
	v_mfma_f32_16x16x32_f16 v[0:3], v[144:147], v[198:201], v[128:131]
	v_mfma_f32_16x16x32_f16 v[24:27], v[148:151], v[218:221], v[0:3]
	v_mfma_f32_16x16x32_f16 v[0:3], v[162:165], v[158:161], v[20:23]
	v_mfma_f32_16x16x32_f16 v[20:23], v[166:169], v[194:197], v[0:3]
	v_mfma_f32_16x16x32_f16 v[0:3], v[162:165], v[198:201], v[132:135]
	v_mfma_f32_16x16x32_f16 v[16:19], v[166:169], v[218:221], v[0:3]
	v_mfma_f32_16x16x32_f16 v[0:3], v[190:193], v[158:161], v[12:15]
	v_mfma_f32_16x16x32_f16 v[12:15], v[202:205], v[194:197], v[0:3]
	v_mfma_f32_16x16x32_f16 v[0:3], v[190:193], v[198:201], v[136:139]
	v_mfma_f32_16x16x32_f16 v[8:11], v[202:205], v[218:221], v[0:3]
	v_mfma_f32_16x16x32_f16 v[0:3], v[210:213], v[158:161], v[4:7]
	v_mfma_f32_16x16x32_f16 v[4:7], v[214:217], v[194:197], v[0:3]
	v_mfma_f32_16x16x32_f16 v[0:3], v[210:213], v[198:201], v[140:143]
	v_mfma_f32_16x16x32_f16 v[0:3], v[214:217], v[218:221], v[0:3]
	s_setprio 0
	s_movk_i32 s1, 0x100
	v_cmp_gt_u32_e32 vcc, s1, v157
	s_barrier
	s_and_saveexec_b64 s[6:7], vcc
	s_cbranch_execz .LBB0_489
	s_barrier

;   #define STAGE(P,BASE,LD,br,kt) do{ const HALF* _u=(BASE)+(long)(br)*(((&(LD))==&lda)?lda_u:(LD))+(long)(kt)*G_BK; \
;     for(int _i=0;_i<2;++_i){ \
;       __builtin_amdgcn_global_load_lds((const unsigned*)(_u+(long)_i*(((&(LD))==&lda)?stepa:stepb)+((&(LD))==&lda?oa0:ob0)), \
;         (unsigned*)((char*)(P)+t5*16+_i*8192),16,0,0);}}while(0)
;   #define WAIT_V(n) asm volatile("s_waitcnt vmcnt(" #n ")":::"memory")
;   #define BAR __builtin_amdgcn_s_barrier()
;     ...
;   const int stepa = n2 ? 1024 : 64 * lda, stepb = 64 * ldb;
;   const int lda_u = n2 ? 16 : lda;
;   {int _b=t5*16;int _r,_c;g_stage_rc(_b,_r,_c);
;     oa0=n2 ? (unsigned)((n2*(_r&63)+(_r>>6))*1024+_c) : (unsigned)(_r*lda+_c); ob0=(unsigned)(_r*ldb+_c);}
;   STAGE(SB(0,0),Bt,ldb,0,0); STAGE(SA(0,0),A,lda,0,0);
;   STAGE(SB(0,1),Bt,ldb,G_HALF,0); STAGE(SA(0,1),A,lda,G_HALF,0);
;   if(wr==1)BAR;
;   WAIT_V(4); BAR;
;   STAGE(SB(1,0),Bt,ldb,0,1); STAGE(SA(1,0),A,lda,0,1); STAGE(SB(1,1),Bt,ldb,G_HALF,1);
;   WAIT_V(6); BAR;
; __device__ void job_ffn_in_g(const P& p, int job, HALF* sm) {
;     ...
;   f4 acc[2][2][4][2];
;   zero_acc256(acc);
;   asm volatile("s_waitcnt vmcnt(0)" ::: "memory");
;   __syncthreads();
;   gemm256(acc, Bp, 1024, Ap, 1024, 1024, sm);
.LBB0_615:
	s_or_b64 exec, exec, s[14:15]
	v_lshlrev_b32_e32 v11, 6, v131
	v_lshlrev_b32_e32 v13, 2, v131
	v_and_b32_e32 v10, 48, v131
	v_and_b32_e32 v12, 0x3c0, v11
	v_and_b32_e32 v13, 32, v13
	v_add_u32_e32 v142, s29, v5
	v_bitop3_b32 v12, v12, v13, v10 bitop3:0x36
	v_and_b32_e32 v10, 0x3000, v11
	v_readfirstlane_b32 s1, v142
	v_add_u32_e32 v143, 0x2000, v142
	v_add_u32_e32 v13, s95, v10
	v_lshl_add_u64 v[10:11], v[0:1], 0, s[84:85]
	s_mov_b32 m0, s1
	s_mov_b64 s[14:15], 0x20080
	v_readfirstlane_b32 s1, v143
	v_add_u32_e32 v144, 0x8000, v136
	global_load_lds_dwordx4 v[10:11], off
	v_lshl_add_u64 v[0:1], v[0:1], 0, s[14:15]
	s_mov_b32 m0, s1
	v_readfirstlane_b32 s1, v144
	v_add_u32_e32 v145, 0xa000, v136
	global_load_lds_dwordx4 v[0:1], off
	v_lshl_add_u64 v[0:1], v[2:3], 0, s[84:85]
	s_mov_b32 m0, s1
	v_readfirstlane_b32 s1, v145
	global_load_lds_dwordx4 v[0:1], off
	v_lshl_add_u64 v[0:1], v[2:3], 0, s[14:15]
	s_mov_b32 m0, s1
	v_add_u32_e32 v146, s62, v5
	global_load_lds_dwordx4 v[0:1], off
	v_lshl_add_u64 v[0:1], v[152:153], 1, s[12:13]
	v_readfirstlane_b32 s1, v146
	v_add_u32_e32 v147, 0x2000, v146
	v_lshl_add_u64 v[2:3], v[0:1], 0, s[88:89]
	s_mov_b32 m0, s1
	v_readfirstlane_b32 s1, v147
	global_load_lds_dwordx4 v[2:3], off
	v_lshl_add_u64 v[0:1], v[0:1], 0, s[90:91]
	s_mov_b32 m0, s1
	s_add_u32 s8, s2, s8
	global_load_lds_dwordx4 v[0:1], off
	v_lshlrev_b32_e32 v0, 13, v4
	v_and_b32_e32 v0, 0xffffc000, v0
	v_lshl_add_u32 v0, v6, 10, v0
	v_or_b32_e32 v0, v0, v7
	s_waitcnt vmcnt(10)
	s_barrier
	s_waitcnt vmcnt(6)
	v_add_u32_sdwa v0, v0, sext(v8) dst_sel:DWORD dst_unused:UNUSED_PAD src0_sel:DWORD src1_sel:WORD_0
	v_mov_b32_e32 v1, v153
	s_addc_u32 s9, s3, s9
	v_lshl_add_u32 v9, v9, 13, 0
	v_lshlrev_b64 v[128:129], 1, v[0:1]
	s_add_u32 s10, s2, s10
	v_mov_b32_e32 v0, 0
	s_addc_u32 s11, s3, s11
	s_mov_b32 s1, -2
	v_add_u32_e32 v133, v13, v12
	v_add_u32_e32 v132, v9, v12
	v_mov_b32_e32 v1, v0
	v_mov_b32_e32 v2, v0
	v_mov_b32_e32 v3, v0
	v_mov_b32_e32 v4, v0
	v_mov_b32_e32 v5, v0
	v_mov_b32_e32 v6, v0
	v_mov_b32_e32 v7, v0
	v_mov_b32_e32 v8, v0
	v_mov_b32_e32 v9, v0
	v_mov_b32_e32 v10, v0
	v_mov_b32_e32 v11, v0
	v_mov_b32_e32 v12, v0
	v_mov_b32_e32 v13, v0
	v_mov_b32_e32 v14, v0
	v_mov_b32_e32 v15, v0
	v_mov_b32_e32 v16, v0
	v_mov_b32_e32 v17, v0
	v_mov_b32_e32 v18, v0
	v_mov_b32_e32 v19, v0
	v_mov_b32_e32 v20, v0
	v_mov_b32_e32 v21, v0
	v_mov_b32_e32 v22, v0
	v_mov_b32_e32 v23, v0
	v_mov_b32_e32 v24, v0
	v_mov_b32_e32 v25, v0
	v_mov_b32_e32 v26, v0
	v_mov_b32_e32 v27, v0
	v_mov_b32_e32 v28, v0
	v_mov_b32_e32 v29, v0
	v_mov_b32_e32 v30, v0
	v_mov_b32_e32 v31, v0
	v_mov_b32_e32 v32, v0
	v_mov_b32_e32 v33, v0
	v_mov_b32_e32 v34, v0
	v_mov_b32_e32 v35, v0
	v_mov_b32_e32 v36, v0
	v_mov_b32_e32 v37, v0
	v_mov_b32_e32 v38, v0
	v_mov_b32_e32 v39, v0
	v_mov_b32_e32 v40, v0
	v_mov_b32_e32 v41, v0
	v_mov_b32_e32 v42, v0
	v_mov_b32_e32 v43, v0
	v_mov_b32_e32 v44, v0
	v_mov_b32_e32 v45, v0
	v_mov_b32_e32 v46, v0
	v_mov_b32_e32 v47, v0
	v_mov_b32_e32 v48, v0
	v_mov_b32_e32 v49, v0
	v_mov_b32_e32 v50, v0
	v_mov_b32_e32 v51, v0
	v_mov_b32_e32 v52, v0
	v_mov_b32_e32 v53, v0
	v_mov_b32_e32 v54, v0
	v_mov_b32_e32 v55, v0
	v_mov_b32_e32 v56, v0
	v_mov_b32_e32 v57, v0
	v_mov_b32_e32 v58, v0
	v_mov_b32_e32 v59, v0
	v_mov_b32_e32 v60, v0
	v_mov_b32_e32 v61, v0
	v_mov_b32_e32 v62, v0
	v_mov_b32_e32 v63, v0
	v_mov_b32_e32 v64, v0
	v_mov_b32_e32 v65, v0
	v_mov_b32_e32 v66, v0
	v_mov_b32_e32 v67, v0
	v_mov_b32_e32 v68, v0
	v_mov_b32_e32 v69, v0
	v_mov_b32_e32 v70, v0
	v_mov_b32_e32 v71, v0
	v_mov_b32_e32 v72, v0
	v_mov_b32_e32 v73, v0
	v_mov_b32_e32 v74, v0
	v_mov_b32_e32 v75, v0
	v_mov_b32_e32 v76, v0
	v_mov_b32_e32 v77, v0
	v_mov_b32_e32 v78, v0
	v_mov_b32_e32 v79, v0
	v_mov_b32_e32 v80, v0
	v_mov_b32_e32 v81, v0
	v_mov_b32_e32 v82, v0
	v_mov_b32_e32 v83, v0
	v_mov_b32_e32 v84, v0
	v_mov_b32_e32 v85, v0
	v_mov_b32_e32 v86, v0
	v_mov_b32_e32 v87, v0
	v_mov_b32_e32 v88, v0
	v_mov_b32_e32 v89, v0
	v_mov_b32_e32 v90, v0
	v_mov_b32_e32 v91, v0
	v_mov_b32_e32 v92, v0
	v_mov_b32_e32 v93, v0
	v_mov_b32_e32 v94, v0
	v_mov_b32_e32 v95, v0
	v_mov_b32_e32 v96, v0
	v_mov_b32_e32 v97, v0
	v_mov_b32_e32 v98, v0
	v_mov_b32_e32 v99, v0
	v_mov_b32_e32 v100, v0
	v_mov_b32_e32 v101, v0
	v_mov_b32_e32 v102, v0
	v_mov_b32_e32 v103, v0
	v_mov_b32_e32 v104, v0
	v_mov_b32_e32 v105, v0
	v_mov_b32_e32 v106, v0
	v_mov_b32_e32 v107, v0
	v_mov_b32_e32 v108, v0
	v_mov_b32_e32 v109, v0
	v_mov_b32_e32 v110, v0
	v_mov_b32_e32 v111, v0
	v_mov_b32_e32 v112, v0
	v_mov_b32_e32 v113, v0
	v_mov_b32_e32 v114, v0
	v_mov_b32_e32 v115, v0
	v_mov_b32_e32 v116, v0
	v_mov_b32_e32 v117, v0
	v_mov_b32_e32 v118, v0
	v_mov_b32_e32 v119, v0
	v_mov_b32_e32 v120, v0
	v_mov_b32_e32 v121, v0
	v_mov_b32_e32 v122, v0
	v_mov_b32_e32 v123, v0
	v_mov_b32_e32 v124, v0
	v_mov_b32_e32 v125, v0
	v_mov_b32_e32 v126, v0
	v_mov_b32_e32 v127, v0
	s_barrier

;   #define STAGE(P,BASE,LD,br,kt) do{ const HALF* _u=(BASE)+(long)(br)*(((&(LD))==&lda)?lda_u:(LD))+(long)(kt)*G_BK; \
;     for(int _i=0;_i<2;++_i){ \
;       __builtin_amdgcn_global_load_lds((const unsigned*)(_u+(long)_i*(((&(LD))==&lda)?stepa:stepb)+((&(LD))==&lda?oa0:ob0)), \
;         (unsigned*)((char*)(P)+t5*16+_i*8192),16,0,0);}}while(0)
;   #define WAIT_V(n) asm volatile("s_waitcnt vmcnt(" #n ")":::"memory")
;   #define BAR __builtin_amdgcn_s_barrier()
;     ...
;   const int stepa = n2 ? 1024 : 64 * lda, stepb = 64 * ldb;
;   const int lda_u = n2 ? 16 : lda;
;   {int _b=t5*16;int _r,_c;g_stage_rc(_b,_r,_c);
;     oa0=n2 ? (unsigned)((n2*(_r&63)+(_r>>6))*1024+_c) : (unsigned)(_r*lda+_c); ob0=(unsigned)(_r*ldb+_c);}
;   STAGE(SB(0,0),Bt,ldb,0,0); STAGE(SA(0,0),A,lda,0,0);
;   STAGE(SB(0,1),Bt,ldb,G_HALF,0); STAGE(SA(0,1),A,lda,G_HALF,0);
;   if(wr==1)BAR;
;   WAIT_V(4); BAR;
;   STAGE(SB(1,0),Bt,ldb,0,1); STAGE(SA(1,0),A,lda,0,1); STAGE(SB(1,1),Bt,ldb,G_HALF,1);
;   WAIT_V(6); BAR;
; template <int K>
; __device__ void job_resid_g(const P& p, const HALF* A, const HALF* Bt, int job, HALF* sm) {
;     ...
;   const HALF* Ap = A + (size_t)(rt * 256) * K;
;   const HALF* Bp = Bt + (size_t)(ct2 * 256) * K;
;   f4 acc[2][2][4][2];
;   zero_acc256(acc);
;   asm volatile("s_waitcnt vmcnt(0)" ::: "memory");
;   __syncthreads();
;   gemm256(acc, Ap, K, Bp, K, K, sm);
.LBB0_665:
	s_or_b64 exec, exec, s[10:11]
	v_lshlrev_b32_e32 v11, 6, v131
	v_lshlrev_b32_e32 v13, 2, v131
	v_and_b32_e32 v10, 48, v131
	v_and_b32_e32 v12, 0x3c0, v11
	v_and_b32_e32 v13, 32, v13
	v_add_u32_e32 v142, s29, v5
	v_bitop3_b32 v12, v12, v13, v10 bitop3:0x36
	v_and_b32_e32 v10, 0x3000, v11
	v_readfirstlane_b32 s10, v142
	v_add_u32_e32 v143, 0x2000, v142
	v_add_u32_e32 v13, s95, v10
	v_lshl_add_u64 v[10:11], v[0:1], 0, s[84:85]
	s_mov_b32 m0, s10
	s_mov_b64 s[18:19], 0x58080
	v_readfirstlane_b32 s10, v143
	v_add_u32_e32 v144, 0x8000, v136
	global_load_lds_dwordx4 v[10:11], off
	v_lshl_add_u64 v[0:1], v[0:1], 0, s[18:19]
	s_mov_b32 m0, s10
	v_readfirstlane_b32 s10, v144
	v_add_u32_e32 v145, 0xa000, v136
	global_load_lds_dwordx4 v[0:1], off
	v_lshl_add_u64 v[0:1], v[2:3], 0, s[84:85]
	s_mov_b32 m0, s10
	v_readfirstlane_b32 s10, v145
	global_load_lds_dwordx4 v[0:1], off
	v_lshl_add_u64 v[0:1], v[2:3], 0, s[18:19]
	s_mov_b32 m0, s10
	v_add_u32_e32 v146, s62, v5
	global_load_lds_dwordx4 v[0:1], off
	v_lshl_add_u64 v[0:1], v[152:153], 1, s[8:9]
	s_mov_b64 s[8:9], 0xb0080
	v_lshl_add_u64 v[2:3], v[0:1], 0, s[8:9]
	v_readfirstlane_b32 s8, v146
	s_mov_b32 m0, s8
	s_mov_b64 s[8:9], 0x108080
	v_add_u32_e32 v147, 0x2000, v146
	v_lshl_add_u64 v[0:1], v[0:1], 0, s[8:9]
	v_readfirstlane_b32 s8, v147
	global_load_lds_dwordx4 v[2:3], off
	s_mov_b32 m0, s8
	s_movk_i32 s8, 0xb00
	global_load_lds_dwordx4 v[0:1], off
	v_lshrrev_b32_e32 v1, 1, v4
	v_mul_lo_u32 v0, v7, s8
	s_mov_b32 s8, 0xb000
	v_mad_u64_u32 v[0:1], s[8:9], v1, s8, v[0:1]
	v_readlane_b32 s10, v254, 8
	v_or_b32_e32 v0, v0, v6
	v_readlane_b32 s11, v254, 9
	s_add_u32 s8, s10, s17
	s_waitcnt vmcnt(10)
	s_barrier
	s_waitcnt vmcnt(6)
	v_add_u32_sdwa v0, v0, sext(v8) dst_sel:DWORD dst_unused:UNUSED_PAD src0_sel:DWORD src1_sel:WORD_0
	v_mov_b32_e32 v1, v153
	s_addc_u32 s9, s11, 0
	v_lshl_add_u32 v9, v9, 13, 0
	v_lshlrev_b64 v[128:129], 1, v[0:1]
	s_add_u32 s10, s10, s16
	v_mov_b32_e32 v0, 0
	s_addc_u32 s11, s11, s15
	s_mov_b32 s15, -2
	v_add_u32_e32 v133, v13, v12
	v_add_u32_e32 v132, v9, v12
	v_mov_b32_e32 v1, v0
	v_mov_b32_e32 v2, v0
	v_mov_b32_e32 v3, v0
	v_mov_b32_e32 v4, v0
	v_mov_b32_e32 v5, v0
	v_mov_b32_e32 v6, v0
	v_mov_b32_e32 v7, v0
	v_mov_b32_e32 v8, v0
	v_mov_b32_e32 v9, v0
	v_mov_b32_e32 v10, v0
	v_mov_b32_e32 v11, v0
	v_mov_b32_e32 v12, v0
	v_mov_b32_e32 v13, v0
	v_mov_b32_e32 v14, v0
	v_mov_b32_e32 v15, v0
	v_mov_b32_e32 v16, v0
	v_mov_b32_e32 v17, v0
	v_mov_b32_e32 v18, v0
	v_mov_b32_e32 v19, v0
	v_mov_b32_e32 v20, v0
	v_mov_b32_e32 v21, v0
	v_mov_b32_e32 v22, v0
	v_mov_b32_e32 v23, v0
	v_mov_b32_e32 v24, v0
	v_mov_b32_e32 v25, v0
	v_mov_b32_e32 v26, v0
	v_mov_b32_e32 v27, v0
	v_mov_b32_e32 v28, v0
	v_mov_b32_e32 v29, v0
	v_mov_b32_e32 v30, v0
	v_mov_b32_e32 v31, v0
	v_mov_b32_e32 v32, v0
	v_mov_b32_e32 v33, v0
	v_mov_b32_e32 v34, v0
	v_mov_b32_e32 v35, v0
	v_mov_b32_e32 v36, v0
	v_mov_b32_e32 v37, v0
	v_mov_b32_e32 v38, v0
	v_mov_b32_e32 v39, v0
	v_mov_b32_e32 v40, v0
	v_mov_b32_e32 v41, v0
	v_mov_b32_e32 v42, v0
	v_mov_b32_e32 v43, v0
	v_mov_b32_e32 v44, v0
	v_mov_b32_e32 v45, v0
	v_mov_b32_e32 v46, v0
	v_mov_b32_e32 v47, v0
	v_mov_b32_e32 v48, v0
	v_mov_b32_e32 v49, v0
	v_mov_b32_e32 v50, v0
	v_mov_b32_e32 v51, v0
	v_mov_b32_e32 v52, v0
	v_mov_b32_e32 v53, v0
	v_mov_b32_e32 v54, v0
	v_mov_b32_e32 v55, v0
	v_mov_b32_e32 v56, v0
	v_mov_b32_e32 v57, v0
	v_mov_b32_e32 v58, v0
	v_mov_b32_e32 v59, v0
	v_mov_b32_e32 v60, v0
	v_mov_b32_e32 v61, v0
	v_mov_b32_e32 v62, v0
	v_mov_b32_e32 v63, v0
	v_mov_b32_e32 v64, v0
	v_mov_b32_e32 v65, v0
	v_mov_b32_e32 v66, v0
	v_mov_b32_e32 v67, v0
	v_mov_b32_e32 v68, v0
	v_mov_b32_e32 v69, v0
	v_mov_b32_e32 v70, v0
	v_mov_b32_e32 v71, v0
	v_mov_b32_e32 v72, v0
	v_mov_b32_e32 v73, v0
	v_mov_b32_e32 v74, v0
	v_mov_b32_e32 v75, v0
	v_mov_b32_e32 v76, v0
	v_mov_b32_e32 v77, v0
	v_mov_b32_e32 v78, v0
	v_mov_b32_e32 v79, v0
	v_mov_b32_e32 v80, v0
	v_mov_b32_e32 v81, v0
	v_mov_b32_e32 v82, v0
	v_mov_b32_e32 v83, v0
	v_mov_b32_e32 v84, v0
	v_mov_b32_e32 v85, v0
	v_mov_b32_e32 v86, v0
	v_mov_b32_e32 v87, v0
	v_mov_b32_e32 v88, v0
	v_mov_b32_e32 v89, v0
	v_mov_b32_e32 v90, v0
	v_mov_b32_e32 v91, v0
	v_mov_b32_e32 v92, v0
	v_mov_b32_e32 v93, v0
	v_mov_b32_e32 v94, v0
	v_mov_b32_e32 v95, v0
	v_mov_b32_e32 v96, v0
	v_mov_b32_e32 v97, v0
	v_mov_b32_e32 v98, v0
	v_mov_b32_e32 v99, v0
	v_mov_b32_e32 v100, v0
	v_mov_b32_e32 v101, v0
	v_mov_b32_e32 v102, v0
	v_mov_b32_e32 v103, v0
	v_mov_b32_e32 v104, v0
	v_mov_b32_e32 v105, v0
	v_mov_b32_e32 v106, v0
	v_mov_b32_e32 v107, v0
	v_mov_b32_e32 v108, v0
	v_mov_b32_e32 v109, v0
	v_mov_b32_e32 v110, v0
	v_mov_b32_e32 v111, v0
	v_mov_b32_e32 v112, v0
	v_mov_b32_e32 v113, v0
	v_mov_b32_e32 v114, v0
	v_mov_b32_e32 v115, v0
	v_mov_b32_e32 v116, v0
	v_mov_b32_e32 v117, v0
	v_mov_b32_e32 v118, v0
	v_mov_b32_e32 v119, v0
	v_mov_b32_e32 v120, v0
	v_mov_b32_e32 v121, v0
	v_mov_b32_e32 v122, v0
	v_mov_b32_e32 v123, v0
	v_mov_b32_e32 v124, v0
	v_mov_b32_e32 v125, v0
	v_mov_b32_e32 v126, v0
	v_mov_b32_e32 v127, v0
	s_barrier
